# stack on v17: norm wave_sum via DPP/permlane, 64-bit acc zeroing, one static prio raise per GEMM K-loop, EpiQKV rope prefetch, branchless scan select
# speedup vs baseline: 1.0123x; 1.0049x over previous
; template <class Epi, class Sched, bool ALIGN_EPI = false, bool SP2 = false>
; __device__ __forceinline__ void gemm_phase(PG8_LAS unsigned char* lds, const Gemm g, const Sched& S, const Epi& E) {
;     ...
;         for (int a = 0; a < 2; ++a)
; #pragma unroll
;             for (int b = 0; b < 2; ++b)
; #pragma unroll
;                 for (int m = 0; m < 4; ++m)
; #pragma unroll
;                     for (int n = 0; n < 2; ++n) acc[a][b][m][n] = (f32x4){0.f, 0.f, 0.f, 0.f};
;         cur = nxt; cA = nA; cB = nB; ++ui;
.LBB0_170:
	s_ashr_i32 s37, s36, 31
	s_lshl_b64 s[46:47], s[36:37], 19
	s_add_u32 s46, s84, s46
	s_addc_u32 s47, s85, s47
	s_and_b64 s[48:49], s[6:7], exec
	s_cselect_b32 s11, s47, s9
	s_cselect_b32 s37, s46, s8
	s_ashr_i32 s35, s34, 31
	s_lshl_b64 s[48:49], s[34:35], 19
	s_add_u32 s48, s92, s48
	s_addc_u32 s49, s93, s49
	s_and_b64 s[52:53], s[6:7], exec
	s_cselect_b32 s35, s49, s51
	s_cselect_b32 s54, s48, s50
	s_add_u32 s8, s8, 0x40080
	s_addc_u32 s9, s9, 0
	s_add_u32 s55, s50, 0x100
	v_mov_b32_e32 v0, 0
	s_addc_u32 s58, s51, 0
	s_mov_b32 s59, -2
	v_mov_b32_e32 v1, v0
	v_mov_b64_e32 v[2:3], 0
	v_mov_b64_e32 v[4:5], 0
	v_mov_b64_e32 v[6:7], 0
	v_mov_b64_e32 v[8:9], 0
	v_mov_b64_e32 v[10:11], 0
	v_mov_b64_e32 v[12:13], 0
	v_mov_b64_e32 v[14:15], 0
	v_mov_b64_e32 v[16:17], 0
	v_mov_b64_e32 v[18:19], 0
	v_mov_b64_e32 v[20:21], 0
	v_mov_b64_e32 v[22:23], 0
	v_mov_b64_e32 v[24:25], 0
	v_mov_b64_e32 v[26:27], 0
	v_mov_b64_e32 v[28:29], 0
	v_mov_b64_e32 v[30:31], 0
	v_mov_b64_e32 v[32:33], 0
	v_mov_b64_e32 v[34:35], 0
	v_mov_b64_e32 v[36:37], 0
	v_mov_b64_e32 v[38:39], 0
	v_mov_b64_e32 v[40:41], 0
	v_mov_b64_e32 v[42:43], 0
	v_mov_b64_e32 v[44:45], 0
	v_mov_b64_e32 v[46:47], 0
	v_mov_b64_e32 v[48:49], 0
	v_mov_b64_e32 v[50:51], 0
	v_mov_b64_e32 v[52:53], 0
	v_mov_b64_e32 v[54:55], 0
	v_mov_b64_e32 v[56:57], 0
	v_mov_b64_e32 v[58:59], 0
	v_mov_b64_e32 v[60:61], 0
	v_mov_b64_e32 v[62:63], 0
	v_mov_b64_e32 v[80:81], 0
	v_mov_b64_e32 v[82:83], 0
	v_mov_b64_e32 v[84:85], 0
	v_mov_b64_e32 v[86:87], 0
	v_mov_b64_e32 v[88:89], 0
	v_mov_b64_e32 v[90:91], 0
	v_mov_b64_e32 v[92:93], 0
	v_mov_b64_e32 v[94:95], 0
	v_mov_b64_e32 v[96:97], 0
	v_mov_b64_e32 v[98:99], 0
	v_mov_b64_e32 v[100:101], 0
	v_mov_b64_e32 v[102:103], 0
	v_mov_b64_e32 v[104:105], 0
	v_mov_b64_e32 v[106:107], 0
	v_mov_b64_e32 v[108:109], 0
	v_mov_b64_e32 v[110:111], 0
	v_mov_b64_e32 v[112:113], 0
	v_mov_b64_e32 v[114:115], 0
	v_mov_b64_e32 v[116:117], 0
	v_mov_b64_e32 v[118:119], 0
	v_mov_b64_e32 v[120:121], 0
	v_mov_b64_e32 v[122:123], 0
	v_mov_b64_e32 v[124:125], 0
	v_mov_b64_e32 v[126:127], 0
	v_mov_b64_e32 v[128:129], 0
	v_mov_b64_e32 v[130:131], 0
	v_mov_b64_e32 v[132:133], 0
	v_mov_b64_e32 v[134:135], 0
	v_mov_b64_e32 v[136:137], 0
	v_mov_b64_e32 v[138:139], 0
	v_mov_b64_e32 v[140:141], 0
	v_mov_b64_e32 v[142:143], 0
	v_readfirstlane_b32 s100, v198
	s_nop 3
	s_bitcmp1_b32 s100, 8
	s_cbranch_scc0 .Lgprio_0_skip
	s_setprio 1

; template <class Epi, class Sched, bool ALIGN_EPI = false, bool SP2 = false>
; __device__ __forceinline__ void gemm_phase(PG8_LAS unsigned char* lds, const Gemm g, const Sched& S, const Epi& E) {
;     ...
;         for (int a = 0; a < 2; ++a)
; #pragma unroll
;             for (int b = 0; b < 2; ++b)
; #pragma unroll
;                 for (int m = 0; m < 4; ++m)
; #pragma unroll
;                     for (int n = 0; n < 2; ++n) acc[a][b][m][n] = (f32x4){0.f, 0.f, 0.f, 0.f};
;         cur = nxt; cA = nA; cB = nB; ++ui;
.LBB0_711:
	s_ashr_i32 s19, s18, 31
	s_lshl_b64 s[2:3], s[18:19], 19
	s_add_u32 s20, s35, s2
	s_addc_u32 s21, s36, s3
	s_and_b64 s[2:3], s[6:7], exec
	s_cselect_b32 s1, s21, s27
	s_cselect_b32 s2, s20, s26
	s_ashr_i32 s17, s16, 31
	s_lshl_b64 s[22:23], s[16:17], 19
	s_add_u32 s22, s37, s22
	s_addc_u32 s23, s38, s23
	s_and_b64 s[30:31], s[6:7], exec
	s_cselect_b32 s3, s23, s29
	s_cselect_b32 s4, s22, s28
	s_add_u32 s26, s26, 0x40080
	s_addc_u32 s27, s27, 0
	s_add_u32 s9, s28, 0x100
	v_mov_b32_e32 v0, 0
	s_addc_u32 s17, s29, 0
	s_mov_b32 s19, -2
	v_mov_b32_e32 v1, v0
	v_mov_b64_e32 v[2:3], 0
	v_mov_b64_e32 v[4:5], 0
	v_mov_b64_e32 v[6:7], 0
	v_mov_b64_e32 v[8:9], 0
	v_mov_b64_e32 v[10:11], 0
	v_mov_b64_e32 v[12:13], 0
	v_mov_b64_e32 v[14:15], 0
	v_mov_b64_e32 v[16:17], 0
	v_mov_b64_e32 v[18:19], 0
	v_mov_b64_e32 v[20:21], 0
	v_mov_b64_e32 v[22:23], 0
	v_mov_b64_e32 v[24:25], 0
	v_mov_b64_e32 v[26:27], 0
	v_mov_b64_e32 v[28:29], 0
	v_mov_b64_e32 v[30:31], 0
	v_mov_b64_e32 v[32:33], 0
	v_mov_b64_e32 v[34:35], 0
	v_mov_b64_e32 v[36:37], 0
	v_mov_b64_e32 v[38:39], 0
	v_mov_b64_e32 v[40:41], 0
	v_mov_b64_e32 v[42:43], 0
	v_mov_b64_e32 v[44:45], 0
	v_mov_b64_e32 v[46:47], 0
	v_mov_b64_e32 v[48:49], 0
	v_mov_b64_e32 v[50:51], 0
	v_mov_b64_e32 v[52:53], 0
	v_mov_b64_e32 v[54:55], 0
	v_mov_b64_e32 v[56:57], 0
	v_mov_b64_e32 v[58:59], 0
	v_mov_b64_e32 v[60:61], 0
	v_mov_b64_e32 v[62:63], 0
	v_mov_b64_e32 v[64:65], 0
	v_mov_b64_e32 v[66:67], 0
	v_mov_b64_e32 v[68:69], 0
	v_mov_b64_e32 v[70:71], 0
	v_mov_b64_e32 v[72:73], 0
	v_mov_b64_e32 v[74:75], 0
	v_mov_b64_e32 v[76:77], 0
	v_mov_b64_e32 v[78:79], 0
	v_mov_b64_e32 v[80:81], 0
	v_mov_b64_e32 v[82:83], 0
	v_mov_b64_e32 v[84:85], 0
	v_mov_b64_e32 v[86:87], 0
	v_mov_b64_e32 v[88:89], 0
	v_mov_b64_e32 v[90:91], 0
	v_mov_b64_e32 v[92:93], 0
	v_mov_b64_e32 v[94:95], 0
	v_mov_b64_e32 v[96:97], 0
	v_mov_b64_e32 v[98:99], 0
	v_mov_b64_e32 v[100:101], 0
	v_mov_b64_e32 v[102:103], 0
	v_mov_b64_e32 v[104:105], 0
	v_mov_b64_e32 v[106:107], 0
	v_mov_b64_e32 v[108:109], 0
	v_mov_b64_e32 v[110:111], 0
	v_mov_b64_e32 v[112:113], 0
	v_mov_b64_e32 v[114:115], 0
	v_mov_b64_e32 v[116:117], 0
	v_mov_b64_e32 v[118:119], 0
	v_mov_b64_e32 v[120:121], 0
	v_mov_b64_e32 v[122:123], 0
	v_mov_b64_e32 v[124:125], 0
	v_mov_b64_e32 v[126:127], 0
	v_readfirstlane_b32 s100, v198
	s_nop 3
	s_bitcmp1_b32 s100, 8
	s_cbranch_scc0 .Lgprio_1_skip
	s_setprio 1

; template <class Epi, class Sched, bool ALIGN_EPI = false, bool SP2 = false>
; __device__ __forceinline__ void gemm_phase(PG8_LAS unsigned char* lds, const Gemm g, const Sched& S, const Epi& E) {
;     ...
;         for (int a = 0; a < 2; ++a)
; #pragma unroll
;             for (int b = 0; b < 2; ++b)
; #pragma unroll
;                 for (int m = 0; m < 4; ++m)
; #pragma unroll
;                     for (int n = 0; n < 2; ++n) acc[a][b][m][n] = (f32x4){0.f, 0.f, 0.f, 0.f};
;         cur = nxt; cA = nA; cB = nB; ++ui;
.LBB0_900:
	s_ashr_i32 s25, s24, 31
	s_lshl_b64 s[28:29], s[24:25], 17
	s_add_u32 s28, s33, s28
	s_addc_u32 s29, s48, s29
	s_and_b64 s[8:9], s[8:9], exec
	v_mov_b32_e32 v0, 0
	s_cselect_b32 s25, s29, s31
	s_cselect_b32 s63, s28, s30
	s_mov_b64 s[38:39], 0
	s_mov_b64 s[8:9], -1
	s_mov_b64 s[36:37], 0
	v_mov_b32_e32 v1, v0
	v_mov_b64_e32 v[2:3], 0
	v_mov_b64_e32 v[4:5], 0
	v_mov_b64_e32 v[6:7], 0
	v_mov_b64_e32 v[8:9], 0
	v_mov_b64_e32 v[10:11], 0
	v_mov_b64_e32 v[12:13], 0
	v_mov_b64_e32 v[14:15], 0
	v_mov_b64_e32 v[16:17], 0
	v_mov_b64_e32 v[18:19], 0
	v_mov_b64_e32 v[20:21], 0
	v_mov_b64_e32 v[22:23], 0
	v_mov_b64_e32 v[24:25], 0
	v_mov_b64_e32 v[26:27], 0
	v_mov_b64_e32 v[28:29], 0
	v_mov_b64_e32 v[30:31], 0
	v_mov_b64_e32 v[32:33], 0
	v_mov_b64_e32 v[34:35], 0
	v_mov_b64_e32 v[36:37], 0
	v_mov_b64_e32 v[38:39], 0
	v_mov_b64_e32 v[40:41], 0
	v_mov_b64_e32 v[42:43], 0
	v_mov_b64_e32 v[44:45], 0
	v_mov_b64_e32 v[46:47], 0
	v_mov_b64_e32 v[48:49], 0
	v_mov_b64_e32 v[50:51], 0
	v_mov_b64_e32 v[52:53], 0
	v_mov_b64_e32 v[54:55], 0
	v_mov_b64_e32 v[56:57], 0
	v_mov_b64_e32 v[58:59], 0
	v_mov_b64_e32 v[60:61], 0
	v_mov_b64_e32 v[62:63], 0
	v_mov_b64_e32 v[64:65], 0
	v_mov_b64_e32 v[66:67], 0
	v_mov_b64_e32 v[68:69], 0
	v_mov_b64_e32 v[70:71], 0
	v_mov_b64_e32 v[72:73], 0
	v_mov_b64_e32 v[74:75], 0
	v_mov_b64_e32 v[76:77], 0
	v_mov_b64_e32 v[78:79], 0
	v_mov_b64_e32 v[80:81], 0
	v_mov_b64_e32 v[82:83], 0
	v_mov_b64_e32 v[84:85], 0
	v_mov_b64_e32 v[86:87], 0
	v_mov_b64_e32 v[88:89], 0
	v_mov_b64_e32 v[90:91], 0
	v_mov_b64_e32 v[92:93], 0
	v_mov_b64_e32 v[94:95], 0
	v_mov_b64_e32 v[96:97], 0
	v_mov_b64_e32 v[98:99], 0
	v_mov_b64_e32 v[100:101], 0
	v_mov_b64_e32 v[102:103], 0
	v_mov_b64_e32 v[104:105], 0
	v_mov_b64_e32 v[106:107], 0
	v_mov_b64_e32 v[108:109], 0
	v_mov_b64_e32 v[110:111], 0
	v_mov_b64_e32 v[112:113], 0
	v_mov_b64_e32 v[114:115], 0
	v_mov_b64_e32 v[116:117], 0
	v_mov_b64_e32 v[118:119], 0
	v_mov_b64_e32 v[120:121], 0
	v_mov_b64_e32 v[122:123], 0
	v_mov_b64_e32 v[124:125], 0
	v_mov_b64_e32 v[126:127], 0
	v_readfirstlane_b32 s100, v198
	s_nop 3
	s_bitcmp1_b32 s100, 8
	s_cbranch_scc0 .Lgprio_2_skip
	s_setprio 1

; __device__ __forceinline__ float sigmoidf_(float x) { return __builtin_amdgcn_rcpf(1.0f + __expf(-x)); }
; __device__ __forceinline__ void rg_unpack8(const u32x4 w, float* v) { v[0] = bflo(w.x); v[1] = bfhi(w.x); v[2] = bflo(w.y); v[3] = bfhi(w.y); v[4] = bflo(w.z); v[5] = bfhi(w.z); v[6] = bflo(w.w); v[7] = bfhi(w.w); }
; __device__ __forceinline__ void rg_ab(float ra, float ri, float x, float ba, float bx, float sp, float& a, float& b) {
;     const float r = sigmoidf_(ra + ba), ig = sigmoidf_(ri + bx); const float l2 = r * sp; a = exp2f(l2);
;     const float x2 = 1.3862943611198906f * l2;
;     const float om = x2 > -0.125f ? -x2 * (1.0f + x2 * (0.5f + x2 * (0.16666667f + x2 * (0.041666668f + x2 * 0.0083333338f)))) : 1.0f - __expf(x2);
;     b = __builtin_amdgcn_sqrtf(om) * (ig * x);
; }
; __device__ __forceinline__ void rg_scan1_phase(const bf16_t* RA0, const bf16_t* RI0, const bf16_t* RA1, const bf16_t* RI1, const bf16_t* XCV, const float* bap, const float* bxp, const float* lamp, float* CAR, int gtid, int ngt) {
;     ...
;         for (int i = 0; i < 32; ++i) { const size_t off = (size_t)(rbase + step * i) * DRNN + 8 * cg;
;             float ra[8], ri[8], xv[8]; rg_unpack8(*(const u32x4*)(RA + off), ra); rg_unpack8(*(const u32x4*)(RI + off), ri); rg_unpack8(*(const u32x4*)(XCV + off), xv);
; #pragma unroll
;             for (int e = 0; e < 8; ++e) { float a, bb; rg_ab(ra[e], ri[e], xv[e], ba[e], bx[e], sp[e], a, bb); p[e] *= a; sv[e] = a * sv[e] + bb; } }
.LBB0_1014:
	s_add_i32 s6, s4, 3
	v_mov_b32_e32 v32, s6
	v_mov_b32_e32 v33, s26
	v_cndmask_b32_e32 v32, v32, v33, vcc
	v_add_u32_e32 v32, v32, v80
	v_mad_i64_i32 v[32:33], s[6:7], v32, s34, v[70:71]
	v_lshlrev_b64 v[32:33], 1, v[32:33]
	v_lshl_add_u64 v[34:35], v[72:73], 0, v[32:33]
	global_load_dwordx4 v[40:43], v[34:35], off
	v_lshl_add_u64 v[34:35], v[74:75], 0, v[32:33]
	v_lshl_add_u64 v[32:33], s[20:21], 0, v[32:33]
	global_load_dwordx4 v[36:39], v[34:35], off
	s_waitcnt vmcnt(1)
	v_lshlrev_b32_e32 v44, 16, v40
	global_load_dwordx4 v[32:35], v[32:33], off
	v_add_f32_e32 v44, v0, v44
	v_mul_f32_e32 v44, 0xbfb8aa3b, v44
	v_exp_f32_e32 v44, v44
	s_nop 0
	v_add_f32_e32 v44, 1.0, v44
	v_rcp_f32_e32 v44, v44
	s_nop 0
	v_mul_f32_e32 v101, v88, v44
	v_mul_f32_e32 v44, 0x3fb17218, v101
	v_mul_f32_e32 v160, 0x3fb8aa3b, v44
	v_exp_f32_e32 v160, v160
	v_fmamk_f32 v161, v44, 0x3c088889, v202
	v_fmaak_f32 v161, v44, v161, 0x3e2aaaab
	v_fma_f32 v161, v44, v161, 0.5
	v_fma_f32 v161, v44, v161, 1.0
	v_mul_f32_e64 v161, v161, -v44
	v_sub_f32_e32 v160, 1.0, v160
	v_cmp_nlt_f32_e64 s[6:7], s5, v44
	s_nop 1
	v_cndmask_b32_e64 v77, v161, v160, s[6:7]
	v_and_b32_e32 v40, 0xffff0000, v40
	v_add_f32_e32 v40, v1, v40
	v_mul_f32_e32 v40, 0xbfb8aa3b, v40
	v_exp_f32_e32 v40, v40
	s_nop 0
	v_add_f32_e32 v40, 1.0, v40
	v_rcp_f32_e32 v40, v40
	s_nop 0
	v_mul_f32_e32 v102, v87, v40
	v_mul_f32_e32 v40, 0x3fb17218, v102
	v_mul_f32_e32 v160, 0x3fb8aa3b, v40
	v_exp_f32_e32 v160, v160
	v_fmamk_f32 v161, v40, 0x3c088889, v202
	v_fmaak_f32 v161, v40, v161, 0x3e2aaaab
	v_fma_f32 v161, v40, v161, 0.5
	v_fma_f32 v161, v40, v161, 1.0
	v_mul_f32_e64 v161, v161, -v40
	v_sub_f32_e32 v160, 1.0, v160
	v_cmp_nlt_f32_e64 s[6:7], s5, v40
	s_nop 1
	v_cndmask_b32_e64 v89, v161, v160, s[6:7]
	v_lshlrev_b32_e32 v40, 16, v41
	v_add_f32_e32 v40, v2, v40
	v_mul_f32_e32 v40, 0xbfb8aa3b, v40
	v_exp_f32_e32 v40, v40
	s_nop 0
	v_add_f32_e32 v40, 1.0, v40
	v_rcp_f32_e32 v40, v40
	s_nop 0
	v_mul_f32_e32 v103, v86, v40
	v_mul_f32_e32 v40, 0x3fb17218, v103
	v_mul_f32_e32 v160, 0x3fb8aa3b, v40
	v_exp_f32_e32 v160, v160
	v_fmamk_f32 v161, v40, 0x3c088889, v202
	v_fmaak_f32 v161, v40, v161, 0x3e2aaaab
	v_fma_f32 v161, v40, v161, 0.5
	v_fma_f32 v161, v40, v161, 1.0
	v_mul_f32_e64 v161, v161, -v40
	v_sub_f32_e32 v160, 1.0, v160
	v_cmp_nlt_f32_e64 s[6:7], s5, v40
	s_nop 1
	v_cndmask_b32_e64 v91, v161, v160, s[6:7]
	v_and_b32_e32 v40, 0xffff0000, v41
	v_add_f32_e32 v40, v3, v40
	v_mul_f32_e32 v40, 0xbfb8aa3b, v40
	v_exp_f32_e32 v40, v40
	s_nop 0
	v_add_f32_e32 v40, 1.0, v40
	v_rcp_f32_e32 v40, v40
	s_nop 0
	v_mul_f32_e32 v104, v85, v40
	v_mul_f32_e32 v40, 0x3fb17218, v104
	v_mul_f32_e32 v160, 0x3fb8aa3b, v40
	v_exp_f32_e32 v160, v160
	v_fmamk_f32 v161, v40, 0x3c088889, v202
	v_fmaak_f32 v161, v40, v161, 0x3e2aaaab
	v_fma_f32 v161, v40, v161, 0.5
	v_fma_f32 v161, v40, v161, 1.0
	v_mul_f32_e64 v161, v161, -v40
	v_sub_f32_e32 v160, 1.0, v160
	v_cmp_nlt_f32_e64 s[6:7], s5, v40
	s_nop 1
	v_cndmask_b32_e64 v93, v161, v160, s[6:7]
	v_lshlrev_b32_e32 v40, 16, v42
	v_add_f32_e32 v40, v8, v40
	v_mul_f32_e32 v40, 0xbfb8aa3b, v40
	v_exp_f32_e32 v40, v40
	s_nop 0
	v_add_f32_e32 v40, 1.0, v40
	v_rcp_f32_e32 v40, v40
	s_nop 0
	v_mul_f32_e32 v106, v84, v40
	v_mul_f32_e32 v40, 0x3fb17218, v106
	v_mul_f32_e32 v160, 0x3fb8aa3b, v40
	v_exp_f32_e32 v160, v160
	v_fmamk_f32 v161, v40, 0x3c088889, v202
	v_fmaak_f32 v161, v40, v161, 0x3e2aaaab
	v_fma_f32 v161, v40, v161, 0.5
	v_fma_f32 v161, v40, v161, 1.0
	v_mul_f32_e64 v161, v161, -v40
	v_sub_f32_e32 v160, 1.0, v160
	v_cmp_nlt_f32_e64 s[6:7], s5, v40
	s_nop 1
	v_cndmask_b32_e64 v95, v161, v160, s[6:7]
	v_and_b32_e32 v40, 0xffff0000, v42
	v_add_f32_e32 v40, v9, v40
	v_mul_f32_e32 v40, 0xbfb8aa3b, v40
	v_exp_f32_e32 v40, v40
	s_nop 0
	v_add_f32_e32 v40, 1.0, v40
	v_rcp_f32_e32 v40, v40
	s_nop 0
	v_mul_f32_e32 v108, v83, v40
	v_mul_f32_e32 v40, 0x3fb17218, v108
	v_mul_f32_e32 v160, 0x3fb8aa3b, v40
	v_exp_f32_e32 v160, v160
	v_fmamk_f32 v161, v40, 0x3c088889, v202
	v_fmaak_f32 v161, v40, v161, 0x3e2aaaab
	v_fma_f32 v161, v40, v161, 0.5
	v_fma_f32 v161, v40, v161, 1.0
	v_mul_f32_e64 v161, v161, -v40
	v_sub_f32_e32 v160, 1.0, v160
	v_cmp_nlt_f32_e64 s[6:7], s5, v40
	s_nop 1
	v_cndmask_b32_e64 v97, v161, v160, s[6:7]
	v_lshlrev_b32_e32 v40, 16, v43
	v_add_f32_e32 v40, v10, v40
	v_mul_f32_e32 v40, 0xbfb8aa3b, v40
	v_exp_f32_e32 v40, v40
	s_nop 0
	v_add_f32_e32 v40, 1.0, v40
	v_rcp_f32_e32 v40, v40
	s_nop 0
	v_mul_f32_e32 v105, v82, v40
	v_mul_f32_e32 v40, 0x3fb17218, v105
	v_mul_f32_e32 v160, 0x3fb8aa3b, v40
	v_exp_f32_e32 v160, v160
	v_fmamk_f32 v161, v40, 0x3c088889, v202
	v_fmaak_f32 v161, v40, v161, 0x3e2aaaab
	v_fma_f32 v161, v40, v161, 0.5
	v_fma_f32 v161, v40, v161, 1.0
	v_mul_f32_e64 v161, v161, -v40
	v_sub_f32_e32 v160, 1.0, v160
	v_cmp_nlt_f32_e64 s[6:7], s5, v40
	s_nop 1
	v_cndmask_b32_e64 v107, v161, v160, s[6:7]
	v_and_b32_e32 v40, 0xffff0000, v43
	v_add_f32_e32 v40, v11, v40
	v_mul_f32_e32 v40, 0xbfb8aa3b, v40
	v_exp_f32_e32 v40, v40
	s_nop 0
	v_add_f32_e32 v40, 1.0, v40
	v_rcp_f32_e32 v40, v40
	s_nop 0
	v_mul_f32_e32 v92, v81, v40
	v_mul_f32_e32 v40, 0x3fb17218, v92
	v_mul_f32_e32 v160, 0x3fb8aa3b, v40
	v_exp_f32_e32 v160, v160
	v_fmamk_f32 v161, v40, 0x3c088889, v202
	v_fmaak_f32 v161, v40, v161, 0x3e2aaaab
	v_fma_f32 v161, v40, v161, 0.5
	v_fma_f32 v161, v40, v161, 1.0
	v_mul_f32_e64 v161, v161, -v40
	v_sub_f32_e32 v160, 1.0, v160
	v_cmp_nlt_f32_e64 s[6:7], s5, v40
	s_nop 1
	v_cndmask_b32_e64 v90, v161, v160, s[6:7]
	s_add_i32 s6, s4, 2
	s_add_i32 s26, s26, 1
	v_mov_b32_e32 v40, s6
	v_mov_b32_e32 v41, s26
	v_cndmask_b32_e32 v40, v40, v41, vcc
	v_add_u32_e32 v40, v40, v80
	v_mad_i64_i32 v[40:41], s[6:7], v40, s34, v[70:71]
	v_lshlrev_b64 v[44:45], 1, v[40:41]
	v_lshl_add_u64 v[40:41], v[72:73], 0, v[44:45]
	global_load_dwordx4 v[48:51], v[40:41], off
	v_lshl_add_u64 v[40:41], v[74:75], 0, v[44:45]
	v_lshl_add_u64 v[44:45], s[20:21], 0, v[44:45]
	global_load_dwordx4 v[40:43], v[40:41], off
	s_waitcnt vmcnt(1)
; __device__ __forceinline__ float sigmoidf_(float x) { return __builtin_amdgcn_rcpf(1.0f + __expf(-x)); }
; __device__ __forceinline__ void rg_unpack8(const u32x4 w, float* v) { v[0] = bflo(w.x); v[1] = bfhi(w.x); v[2] = bflo(w.y); v[3] = bfhi(w.y); v[4] = bflo(w.z); v[5] = bfhi(w.z); v[6] = bflo(w.w); v[7] = bfhi(w.w); }
; __device__ __forceinline__ void rg_ab(float ra, float ri, float x, float ba, float bx, float sp, float& a, float& b) {
;     const float r = sigmoidf_(ra + ba), ig = sigmoidf_(ri + bx); const float l2 = r * sp; a = exp2f(l2);
;     const float x2 = 1.3862943611198906f * l2;
;     const float om = x2 > -0.125f ? -x2 * (1.0f + x2 * (0.5f + x2 * (0.16666667f + x2 * (0.041666668f + x2 * 0.0083333338f)))) : 1.0f - __expf(x2);
;     b = __builtin_amdgcn_sqrtf(om) * (ig * x);
; }
; __device__ __forceinline__ void rg_scan1_phase(const bf16_t* RA0, const bf16_t* RI0, const bf16_t* RA1, const bf16_t* RI1, const bf16_t* XCV, const float* bap, const float* bxp, const float* lamp, float* CAR, int gtid, int ngt) {
;     ...
;         for (int i = 0; i < 32; ++i) { const size_t off = (size_t)(rbase + step * i) * DRNN + 8 * cg;
;             float ra[8], ri[8], xv[8]; rg_unpack8(*(const u32x4*)(RA + off), ra); rg_unpack8(*(const u32x4*)(RI + off), ri); rg_unpack8(*(const u32x4*)(XCV + off), xv);
; #pragma unroll
;             for (int e = 0; e < 8; ++e) { float a, bb; rg_ab(ra[e], ri[e], xv[e], ba[e], bx[e], sp[e], a, bb); p[e] *= a; sv[e] = a * sv[e] + bb; } }
	v_lshlrev_b32_e32 v52, 16, v48
	global_load_dwordx4 v[44:47], v[44:45], off
	v_add_f32_e32 v52, v0, v52
	v_mul_f32_e32 v52, 0xbfb8aa3b, v52
	v_exp_f32_e32 v52, v52
	s_nop 0
	v_add_f32_e32 v52, 1.0, v52
	v_rcp_f32_e32 v52, v52
	s_nop 0
	v_mul_f32_e32 v117, v88, v52
	v_mul_f32_e32 v52, 0x3fb17218, v117
	v_mul_f32_e32 v160, 0x3fb8aa3b, v52
	v_exp_f32_e32 v160, v160
	v_fmamk_f32 v161, v52, 0x3c088889, v202
	v_fmaak_f32 v161, v52, v161, 0x3e2aaaab
	v_fma_f32 v161, v52, v161, 0.5
	v_fma_f32 v161, v52, v161, 1.0
	v_mul_f32_e64 v161, v161, -v52
	v_sub_f32_e32 v160, 1.0, v160
	v_cmp_nlt_f32_e64 s[6:7], s5, v52
	s_nop 1
	v_cndmask_b32_e64 v94, v161, v160, s[6:7]
	v_and_b32_e32 v48, 0xffff0000, v48
	v_add_f32_e32 v48, v1, v48
	v_mul_f32_e32 v48, 0xbfb8aa3b, v48
	v_exp_f32_e32 v48, v48
	s_nop 0
	v_add_f32_e32 v48, 1.0, v48
	v_rcp_f32_e32 v48, v48
	s_nop 0
	v_mul_f32_e32 v118, v87, v48
	v_mul_f32_e32 v48, 0x3fb17218, v118
	v_mul_f32_e32 v160, 0x3fb8aa3b, v48
	v_exp_f32_e32 v160, v160
	v_fmamk_f32 v161, v48, 0x3c088889, v202
	v_fmaak_f32 v161, v48, v161, 0x3e2aaaab
	v_fma_f32 v161, v48, v161, 0.5
	v_fma_f32 v161, v48, v161, 1.0
	v_mul_f32_e64 v161, v161, -v48
	v_sub_f32_e32 v160, 1.0, v160
	v_cmp_nlt_f32_e64 s[6:7], s5, v48
	s_nop 1
	v_cndmask_b32_e64 v96, v161, v160, s[6:7]
	v_lshlrev_b32_e32 v48, 16, v49
	v_add_f32_e32 v48, v2, v48
	v_mul_f32_e32 v48, 0xbfb8aa3b, v48
	v_exp_f32_e32 v48, v48
	s_nop 0
	v_add_f32_e32 v48, 1.0, v48
	v_rcp_f32_e32 v48, v48
	s_nop 0
	v_mul_f32_e32 v119, v86, v48
	v_mul_f32_e32 v48, 0x3fb17218, v119
	v_mul_f32_e32 v160, 0x3fb8aa3b, v48
	v_exp_f32_e32 v160, v160
	v_fmamk_f32 v161, v48, 0x3c088889, v202
	v_fmaak_f32 v161, v48, v161, 0x3e2aaaab
	v_fma_f32 v161, v48, v161, 0.5
	v_fma_f32 v161, v48, v161, 1.0
	v_mul_f32_e64 v161, v161, -v48
	v_sub_f32_e32 v160, 1.0, v160
	v_cmp_nlt_f32_e64 s[6:7], s5, v48
	s_nop 1
	v_cndmask_b32_e64 v99, v161, v160, s[6:7]
	v_and_b32_e32 v48, 0xffff0000, v49
	v_add_f32_e32 v48, v3, v48
	v_mul_f32_e32 v48, 0xbfb8aa3b, v48
	v_exp_f32_e32 v48, v48
	s_nop 0
	v_add_f32_e32 v48, 1.0, v48
	v_rcp_f32_e32 v48, v48
	s_nop 0
	v_mul_f32_e32 v122, v85, v48
	v_mul_f32_e32 v48, 0x3fb17218, v122
	v_mul_f32_e32 v160, 0x3fb8aa3b, v48
	v_exp_f32_e32 v160, v160
	v_fmamk_f32 v161, v48, 0x3c088889, v202
	v_fmaak_f32 v161, v48, v161, 0x3e2aaaab
	v_fma_f32 v161, v48, v161, 0.5
	v_fma_f32 v161, v48, v161, 1.0
	v_mul_f32_e64 v161, v161, -v48
	v_sub_f32_e32 v160, 1.0, v160
	v_cmp_nlt_f32_e64 s[6:7], s5, v48
	s_nop 1
	v_cndmask_b32_e64 v109, v161, v160, s[6:7]
	v_lshlrev_b32_e32 v48, 16, v50
	v_add_f32_e32 v48, v8, v48
	v_mul_f32_e32 v48, 0xbfb8aa3b, v48
	v_exp_f32_e32 v48, v48
	s_nop 0
	v_add_f32_e32 v48, 1.0, v48
	v_rcp_f32_e32 v48, v48
	s_nop 0
	v_mul_f32_e32 v123, v84, v48
	v_mul_f32_e32 v48, 0x3fb17218, v123
	v_mul_f32_e32 v160, 0x3fb8aa3b, v48
	v_exp_f32_e32 v160, v160
	v_fmamk_f32 v161, v48, 0x3c088889, v202
	v_fmaak_f32 v161, v48, v161, 0x3e2aaaab
	v_fma_f32 v161, v48, v161, 0.5
	v_fma_f32 v161, v48, v161, 1.0
	v_mul_f32_e64 v161, v161, -v48
	v_sub_f32_e32 v160, 1.0, v160
	v_cmp_nlt_f32_e64 s[6:7], s5, v48
	s_nop 1
	v_cndmask_b32_e64 v111, v161, v160, s[6:7]
	v_and_b32_e32 v48, 0xffff0000, v50
	v_add_f32_e32 v48, v9, v48
	v_mul_f32_e32 v48, 0xbfb8aa3b, v48
	v_exp_f32_e32 v48, v48
	s_nop 0
	v_add_f32_e32 v48, 1.0, v48
	v_rcp_f32_e32 v48, v48
	s_nop 0
	v_mul_f32_e32 v124, v83, v48
	v_mul_f32_e32 v48, 0x3fb17218, v124
	v_mul_f32_e32 v160, 0x3fb8aa3b, v48
	v_exp_f32_e32 v160, v160
	v_fmamk_f32 v161, v48, 0x3c088889, v202
	v_fmaak_f32 v161, v48, v161, 0x3e2aaaab
	v_fma_f32 v161, v48, v161, 0.5
	v_fma_f32 v161, v48, v161, 1.0
	v_mul_f32_e64 v161, v161, -v48
	v_sub_f32_e32 v160, 1.0, v160
	v_cmp_nlt_f32_e64 s[6:7], s5, v48
	s_nop 1
	v_cndmask_b32_e64 v113, v161, v160, s[6:7]
	v_lshlrev_b32_e32 v48, 16, v51
	v_add_f32_e32 v48, v10, v48
	v_mul_f32_e32 v48, 0xbfb8aa3b, v48
	v_exp_f32_e32 v48, v48
	s_nop 0
	v_add_f32_e32 v48, 1.0, v48
	v_rcp_f32_e32 v48, v48
	s_nop 0
	v_mul_f32_e32 v125, v82, v48
	v_mul_f32_e32 v48, 0x3fb17218, v125
	v_mul_f32_e32 v160, 0x3fb8aa3b, v48
	v_exp_f32_e32 v160, v160
	v_fmamk_f32 v161, v48, 0x3c088889, v202
	v_fmaak_f32 v161, v48, v161, 0x3e2aaaab
	v_fma_f32 v161, v48, v161, 0.5
	v_fma_f32 v161, v48, v161, 1.0
	v_mul_f32_e64 v161, v161, -v48
	v_sub_f32_e32 v160, 1.0, v160
	v_cmp_nlt_f32_e64 s[6:7], s5, v48
	s_nop 1
	v_cndmask_b32_e64 v120, v161, v160, s[6:7]
	v_and_b32_e32 v48, 0xffff0000, v51
	v_add_f32_e32 v48, v11, v48
	v_mul_f32_e32 v48, 0xbfb8aa3b, v48
	v_exp_f32_e32 v48, v48
	s_nop 0
	v_add_f32_e32 v48, 1.0, v48
	v_rcp_f32_e32 v48, v48
	s_nop 0
	v_mul_f32_e32 v100, v81, v48
	v_mul_f32_e32 v48, 0x3fb17218, v100
	v_mul_f32_e32 v160, 0x3fb8aa3b, v48
	v_exp_f32_e32 v160, v160
	v_fmamk_f32 v161, v48, 0x3c088889, v202
	v_fmaak_f32 v161, v48, v161, 0x3e2aaaab
	v_fma_f32 v161, v48, v161, 0.5
	v_fma_f32 v161, v48, v161, 1.0
	v_mul_f32_e64 v161, v161, -v48
	v_sub_f32_e32 v160, 1.0, v160
	v_cmp_nlt_f32_e64 s[6:7], s5, v48
	s_nop 1
	v_cndmask_b32_e64 v98, v161, v160, s[6:7]
	s_add_i32 s6, s4, 1
	s_add_i32 s26, s26, 1
	v_mov_b32_e32 v48, s6
	v_mov_b32_e32 v49, s26
	v_cndmask_b32_e32 v48, v48, v49, vcc
	v_add_u32_e32 v48, v48, v80
	v_mad_i64_i32 v[48:49], s[6:7], v48, s34, v[70:71]
	v_lshlrev_b64 v[52:53], 1, v[48:49]
	v_lshl_add_u64 v[48:49], v[72:73], 0, v[52:53]
	global_load_dwordx4 v[56:59], v[48:49], off
	v_lshl_add_u64 v[48:49], v[74:75], 0, v[52:53]
	v_lshl_add_u64 v[52:53], s[20:21], 0, v[52:53]
	global_load_dwordx4 v[48:51], v[48:49], off
	s_waitcnt vmcnt(1)
; __device__ __forceinline__ float sigmoidf_(float x) { return __builtin_amdgcn_rcpf(1.0f + __expf(-x)); }
; __device__ __forceinline__ void rg_unpack8(const u32x4 w, float* v) { v[0] = bflo(w.x); v[1] = bfhi(w.x); v[2] = bflo(w.y); v[3] = bfhi(w.y); v[4] = bflo(w.z); v[5] = bfhi(w.z); v[6] = bflo(w.w); v[7] = bfhi(w.w); }
; __device__ __forceinline__ void rg_ab(float ra, float ri, float x, float ba, float bx, float sp, float& a, float& b) {
;     const float r = sigmoidf_(ra + ba), ig = sigmoidf_(ri + bx); const float l2 = r * sp; a = exp2f(l2);
;     const float x2 = 1.3862943611198906f * l2;
;     const float om = x2 > -0.125f ? -x2 * (1.0f + x2 * (0.5f + x2 * (0.16666667f + x2 * (0.041666668f + x2 * 0.0083333338f)))) : 1.0f - __expf(x2);
;     b = __builtin_amdgcn_sqrtf(om) * (ig * x);
; }
; __device__ __forceinline__ void rg_scan1_phase(const bf16_t* RA0, const bf16_t* RI0, const bf16_t* RA1, const bf16_t* RI1, const bf16_t* XCV, const float* bap, const float* bxp, const float* lamp, float* CAR, int gtid, int ngt) {
;     ...
;         for (int i = 0; i < 32; ++i) { const size_t off = (size_t)(rbase + step * i) * DRNN + 8 * cg;
;             float ra[8], ri[8], xv[8]; rg_unpack8(*(const u32x4*)(RA + off), ra); rg_unpack8(*(const u32x4*)(RI + off), ri); rg_unpack8(*(const u32x4*)(XCV + off), xv);
; #pragma unroll
;             for (int e = 0; e < 8; ++e) { float a, bb; rg_ab(ra[e], ri[e], xv[e], ba[e], bx[e], sp[e], a, bb); p[e] *= a; sv[e] = a * sv[e] + bb; } }
	v_lshlrev_b32_e32 v60, 16, v56
	global_load_dwordx4 v[52:55], v[52:53], off
	v_add_f32_e32 v60, v0, v60
	v_mul_f32_e32 v60, 0xbfb8aa3b, v60
	v_exp_f32_e32 v60, v60
	s_nop 0
	v_add_f32_e32 v60, 1.0, v60
	v_rcp_f32_e32 v60, v60
	s_nop 0
	v_mul_f32_e32 v131, v88, v60
	v_mul_f32_e32 v60, 0x3fb17218, v131
	v_mul_f32_e32 v160, 0x3fb8aa3b, v60
	v_exp_f32_e32 v160, v160
	v_fmamk_f32 v161, v60, 0x3c088889, v202
	v_fmaak_f32 v161, v60, v161, 0x3e2aaaab
	v_fma_f32 v161, v60, v161, 0.5
	v_fma_f32 v161, v60, v161, 1.0
	v_mul_f32_e64 v161, v161, -v60
	v_sub_f32_e32 v160, 1.0, v160
	v_cmp_nlt_f32_e64 s[6:7], s5, v60
	s_nop 1
	v_cndmask_b32_e64 v110, v161, v160, s[6:7]
	v_and_b32_e32 v56, 0xffff0000, v56
	v_add_f32_e32 v56, v1, v56
	v_mul_f32_e32 v56, 0xbfb8aa3b, v56
	v_exp_f32_e32 v56, v56
	s_nop 0
	v_add_f32_e32 v56, 1.0, v56
	v_rcp_f32_e32 v56, v56
	s_nop 0
	v_mul_f32_e32 v133, v87, v56
	v_mul_f32_e32 v56, 0x3fb17218, v133
	v_mul_f32_e32 v160, 0x3fb8aa3b, v56
	v_exp_f32_e32 v160, v160
	v_fmamk_f32 v161, v56, 0x3c088889, v202
	v_fmaak_f32 v161, v56, v161, 0x3e2aaaab
	v_fma_f32 v161, v56, v161, 0.5
	v_fma_f32 v161, v56, v161, 1.0
	v_mul_f32_e64 v161, v161, -v56
	v_sub_f32_e32 v160, 1.0, v160
	v_cmp_nlt_f32_e64 s[6:7], s5, v56
	s_nop 1
	v_cndmask_b32_e64 v112, v161, v160, s[6:7]
	v_lshlrev_b32_e32 v56, 16, v57
	v_add_f32_e32 v56, v2, v56
	v_mul_f32_e32 v56, 0xbfb8aa3b, v56
	v_exp_f32_e32 v56, v56
	s_nop 0
	v_add_f32_e32 v56, 1.0, v56
	v_rcp_f32_e32 v56, v56
	s_nop 0
	v_mul_f32_e32 v135, v86, v56
	v_mul_f32_e32 v56, 0x3fb17218, v135
	v_mul_f32_e32 v160, 0x3fb8aa3b, v56
	v_exp_f32_e32 v160, v160
	v_fmamk_f32 v161, v56, 0x3c088889, v202
	v_fmaak_f32 v161, v56, v161, 0x3e2aaaab
	v_fma_f32 v161, v56, v161, 0.5
	v_fma_f32 v161, v56, v161, 1.0
	v_mul_f32_e64 v161, v161, -v56
	v_sub_f32_e32 v160, 1.0, v160
	v_cmp_nlt_f32_e64 s[6:7], s5, v56
	s_nop 1
	v_cndmask_b32_e64 v115, v161, v160, s[6:7]
	v_and_b32_e32 v56, 0xffff0000, v57
	v_add_f32_e32 v56, v3, v56
	v_mul_f32_e32 v56, 0xbfb8aa3b, v56
	v_exp_f32_e32 v56, v56
	s_nop 0
	v_add_f32_e32 v56, 1.0, v56
	v_rcp_f32_e32 v56, v56
	s_nop 0
	v_mul_f32_e32 v136, v85, v56
	v_mul_f32_e32 v56, 0x3fb17218, v136
	v_mul_f32_e32 v160, 0x3fb8aa3b, v56
	v_exp_f32_e32 v160, v160
	v_fmamk_f32 v161, v56, 0x3c088889, v202
	v_fmaak_f32 v161, v56, v161, 0x3e2aaaab
	v_fma_f32 v161, v56, v161, 0.5
	v_fma_f32 v161, v56, v161, 1.0
	v_mul_f32_e64 v161, v161, -v56
	v_sub_f32_e32 v160, 1.0, v160
	v_cmp_nlt_f32_e64 s[6:7], s5, v56
	s_nop 1
	v_cndmask_b32_e64 v121, v161, v160, s[6:7]
	v_lshlrev_b32_e32 v56, 16, v58
	v_add_f32_e32 v56, v8, v56
	v_mul_f32_e32 v56, 0xbfb8aa3b, v56
	v_exp_f32_e32 v56, v56
	s_nop 0
	v_add_f32_e32 v56, 1.0, v56
	v_rcp_f32_e32 v56, v56
	s_nop 0
	v_mul_f32_e32 v137, v84, v56
	v_mul_f32_e32 v56, 0x3fb17218, v137
	v_mul_f32_e32 v160, 0x3fb8aa3b, v56
	v_exp_f32_e32 v160, v160
	v_fmamk_f32 v161, v56, 0x3c088889, v202
	v_fmaak_f32 v161, v56, v161, 0x3e2aaaab
	v_fma_f32 v161, v56, v161, 0.5
	v_fma_f32 v161, v56, v161, 1.0
	v_mul_f32_e64 v161, v161, -v56
	v_sub_f32_e32 v160, 1.0, v160
	v_cmp_nlt_f32_e64 s[6:7], s5, v56
	s_nop 1
	v_cndmask_b32_e64 v127, v161, v160, s[6:7]
	v_and_b32_e32 v56, 0xffff0000, v58
	v_add_f32_e32 v56, v9, v56
	v_mul_f32_e32 v56, 0xbfb8aa3b, v56
	v_exp_f32_e32 v56, v56
	s_nop 0
	v_add_f32_e32 v56, 1.0, v56
	v_rcp_f32_e32 v56, v56
	s_nop 0
	v_mul_f32_e32 v138, v83, v56
	v_mul_f32_e32 v56, 0x3fb17218, v138
	v_mul_f32_e32 v160, 0x3fb8aa3b, v56
	v_exp_f32_e32 v160, v160
	v_fmamk_f32 v161, v56, 0x3c088889, v202
	v_fmaak_f32 v161, v56, v161, 0x3e2aaaab
	v_fma_f32 v161, v56, v161, 0.5
	v_fma_f32 v161, v56, v161, 1.0
	v_mul_f32_e64 v161, v161, -v56
	v_sub_f32_e32 v160, 1.0, v160
	v_cmp_nlt_f32_e64 s[6:7], s5, v56
	s_nop 1
	v_cndmask_b32_e64 v129, v161, v160, s[6:7]
	v_lshlrev_b32_e32 v56, 16, v59
	v_add_f32_e32 v56, v10, v56
	v_mul_f32_e32 v56, 0xbfb8aa3b, v56
	v_exp_f32_e32 v56, v56
	s_nop 0
	v_add_f32_e32 v56, 1.0, v56
	v_rcp_f32_e32 v56, v56
	s_nop 0
	v_mul_f32_e32 v139, v82, v56
	v_mul_f32_e32 v56, 0x3fb17218, v139
	v_mul_f32_e32 v160, 0x3fb8aa3b, v56
	v_exp_f32_e32 v160, v160
	v_fmamk_f32 v161, v56, 0x3c088889, v202
	v_fmaak_f32 v161, v56, v161, 0x3e2aaaab
	v_fma_f32 v161, v56, v161, 0.5
	v_fma_f32 v161, v56, v161, 1.0
	v_mul_f32_e64 v161, v161, -v56
	v_sub_f32_e32 v160, 1.0, v160
	v_cmp_nlt_f32_e64 s[6:7], s5, v56
	s_nop 1
	v_cndmask_b32_e64 v132, v161, v160, s[6:7]
	v_and_b32_e32 v56, 0xffff0000, v59
	v_add_f32_e32 v56, v11, v56
	v_mul_f32_e32 v56, 0xbfb8aa3b, v56
	v_exp_f32_e32 v56, v56
	s_nop 0
	v_add_f32_e32 v56, 1.0, v56
	v_rcp_f32_e32 v56, v56
	s_nop 0
	v_mul_f32_e32 v116, v81, v56
	v_mul_f32_e32 v56, 0x3fb17218, v116
	v_mul_f32_e32 v160, 0x3fb8aa3b, v56
	v_exp_f32_e32 v160, v160
	v_fmamk_f32 v161, v56, 0x3c088889, v202
	v_fmaak_f32 v161, v56, v161, 0x3e2aaaab
	v_fma_f32 v161, v56, v161, 0.5
	v_fma_f32 v161, v56, v161, 1.0
	v_mul_f32_e64 v161, v161, -v56
	v_sub_f32_e32 v160, 1.0, v160
	v_cmp_nlt_f32_e64 s[6:7], s5, v56
	s_nop 1
	v_cndmask_b32_e64 v114, v161, v160, s[6:7]
	s_add_i32 s26, s26, 1
	v_mov_b32_e32 v56, s4
	v_mov_b32_e32 v57, s26
	v_cndmask_b32_e32 v56, v56, v57, vcc
	v_add_u32_e32 v56, v56, v80
	v_mad_i64_i32 v[56:57], s[6:7], v56, s34, v[70:71]
	v_lshlrev_b64 v[60:61], 1, v[56:57]
	v_lshl_add_u64 v[56:57], v[72:73], 0, v[60:61]
	global_load_dwordx4 v[64:67], v[56:57], off
	v_lshl_add_u64 v[56:57], v[74:75], 0, v[60:61]
	v_lshl_add_u64 v[60:61], s[20:21], 0, v[60:61]
	global_load_dwordx4 v[56:59], v[56:57], off
	s_waitcnt vmcnt(1)
; __device__ __forceinline__ float sigmoidf_(float x) { return __builtin_amdgcn_rcpf(1.0f + __expf(-x)); }
; __device__ __forceinline__ void rg_unpack8(const u32x4 w, float* v) { v[0] = bflo(w.x); v[1] = bfhi(w.x); v[2] = bflo(w.y); v[3] = bfhi(w.y); v[4] = bflo(w.z); v[5] = bfhi(w.z); v[6] = bflo(w.w); v[7] = bfhi(w.w); }
; __device__ __forceinline__ void rg_ab(float ra, float ri, float x, float ba, float bx, float sp, float& a, float& b) {
;     const float r = sigmoidf_(ra + ba), ig = sigmoidf_(ri + bx); const float l2 = r * sp; a = exp2f(l2);
;     const float x2 = 1.3862943611198906f * l2;
;     const float om = x2 > -0.125f ? -x2 * (1.0f + x2 * (0.5f + x2 * (0.16666667f + x2 * (0.041666668f + x2 * 0.0083333338f)))) : 1.0f - __expf(x2);
;     b = __builtin_amdgcn_sqrtf(om) * (ig * x);
; }
; __device__ __forceinline__ void rg_scan1_phase(const bf16_t* RA0, const bf16_t* RI0, const bf16_t* RA1, const bf16_t* RI1, const bf16_t* XCV, const float* bap, const float* bxp, const float* lamp, float* CAR, int gtid, int ngt) {
;     ...
;         for (int i = 0; i < 32; ++i) { const size_t off = (size_t)(rbase + step * i) * DRNN + 8 * cg;
;             float ra[8], ri[8], xv[8]; rg_unpack8(*(const u32x4*)(RA + off), ra); rg_unpack8(*(const u32x4*)(RI + off), ri); rg_unpack8(*(const u32x4*)(XCV + off), xv);
; #pragma unroll
;             for (int e = 0; e < 8; ++e) { float a, bb; rg_ab(ra[e], ri[e], xv[e], ba[e], bx[e], sp[e], a, bb); p[e] *= a; sv[e] = a * sv[e] + bb; } }
	v_lshlrev_b32_e32 v126, 16, v64
	global_load_dwordx4 v[60:63], v[60:61], off
	v_add_f32_e32 v126, v0, v126
	v_mul_f32_e32 v126, 0xbfb8aa3b, v126
	v_exp_f32_e32 v126, v126
	s_nop 0
	v_add_f32_e32 v126, 1.0, v126
	v_rcp_f32_e32 v126, v126
	s_nop 0
	v_mul_f32_e32 v142, v88, v126
	v_mul_f32_e32 v128, 0x3fb17218, v142
	v_mul_f32_e32 v160, 0x3fb8aa3b, v128
	v_exp_f32_e32 v160, v160
	v_fmamk_f32 v161, v128, 0x3c088889, v202
	v_fmaak_f32 v161, v128, v161, 0x3e2aaaab
	v_fma_f32 v161, v128, v161, 0.5
	v_fma_f32 v161, v128, v161, 1.0
	v_mul_f32_e64 v161, v161, -v128
	v_sub_f32_e32 v160, 1.0, v160
	v_cmp_nlt_f32_e64 s[6:7], s5, v128
	s_nop 1
	v_cndmask_b32_e64 v126, v161, v160, s[6:7]
	v_and_b32_e32 v64, 0xffff0000, v64
	v_add_f32_e32 v64, v1, v64
	v_mul_f32_e32 v64, 0xbfb8aa3b, v64
	v_exp_f32_e32 v64, v64
	s_nop 0
	v_add_f32_e32 v64, 1.0, v64
	v_rcp_f32_e32 v64, v64
	s_nop 0
	v_mul_f32_e32 v144, v87, v64
	v_mul_f32_e32 v64, 0x3fb17218, v144
	v_mul_f32_e32 v160, 0x3fb8aa3b, v64
	v_exp_f32_e32 v160, v160
	v_fmamk_f32 v161, v64, 0x3c088889, v202
	v_fmaak_f32 v161, v64, v161, 0x3e2aaaab
	v_fma_f32 v161, v64, v161, 0.5
	v_fma_f32 v161, v64, v161, 1.0
	v_mul_f32_e64 v161, v161, -v64
	v_sub_f32_e32 v160, 1.0, v160
	v_cmp_nlt_f32_e64 s[6:7], s5, v64
	s_nop 1
	v_cndmask_b32_e64 v128, v161, v160, s[6:7]
	v_lshlrev_b32_e32 v64, 16, v65
	v_add_f32_e32 v64, v2, v64
	v_mul_f32_e32 v64, 0xbfb8aa3b, v64
	v_exp_f32_e32 v64, v64
	s_nop 0
	v_add_f32_e32 v64, 1.0, v64
	v_rcp_f32_e32 v64, v64
	s_nop 0
	v_mul_f32_e32 v145, v86, v64
	v_mul_f32_e32 v64, 0x3fb17218, v145
	v_mul_f32_e32 v160, 0x3fb8aa3b, v64
	v_exp_f32_e32 v160, v160
	v_fmamk_f32 v161, v64, 0x3c088889, v202
	v_fmaak_f32 v161, v64, v161, 0x3e2aaaab
	v_fma_f32 v161, v64, v161, 0.5
	v_fma_f32 v161, v64, v161, 1.0
	v_mul_f32_e64 v161, v161, -v64
	v_sub_f32_e32 v160, 1.0, v160
	v_cmp_nlt_f32_e64 s[6:7], s5, v64
	s_nop 1
	v_cndmask_b32_e64 v130, v161, v160, s[6:7]
	v_and_b32_e32 v64, 0xffff0000, v65
	v_add_f32_e32 v64, v3, v64
	v_mul_f32_e32 v64, 0xbfb8aa3b, v64
	v_exp_f32_e32 v64, v64
	s_nop 0
	v_add_f32_e32 v64, 1.0, v64
	v_rcp_f32_e32 v64, v64
	s_nop 0
	v_mul_f32_e32 v146, v85, v64
	v_mul_f32_e32 v64, 0x3fb17218, v146
	v_mul_f32_e32 v160, 0x3fb8aa3b, v64
	v_exp_f32_e32 v160, v160
	v_fmamk_f32 v161, v64, 0x3c088889, v202
	v_fmaak_f32 v161, v64, v161, 0x3e2aaaab
	v_fma_f32 v161, v64, v161, 0.5
	v_fma_f32 v161, v64, v161, 1.0
	v_mul_f32_e64 v161, v161, -v64
	v_sub_f32_e32 v160, 1.0, v160
	v_cmp_nlt_f32_e64 s[6:7], s5, v64
	s_nop 1
	v_cndmask_b32_e64 v134, v161, v160, s[6:7]
	v_lshlrev_b32_e32 v64, 16, v66
	v_add_f32_e32 v64, v8, v64
	v_mul_f32_e32 v64, 0xbfb8aa3b, v64
	v_exp_f32_e32 v64, v64
	s_nop 0
	v_add_f32_e32 v64, 1.0, v64
	v_rcp_f32_e32 v64, v64
	s_nop 0
	v_mul_f32_e32 v147, v84, v64
	v_mul_f32_e32 v64, 0x3fb17218, v147
	v_mul_f32_e32 v160, 0x3fb8aa3b, v64
	v_exp_f32_e32 v160, v160
	v_fmamk_f32 v161, v64, 0x3c088889, v202
	v_fmaak_f32 v161, v64, v161, 0x3e2aaaab
	v_fma_f32 v161, v64, v161, 0.5
	v_fma_f32 v161, v64, v161, 1.0
	v_mul_f32_e64 v161, v161, -v64
	v_sub_f32_e32 v160, 1.0, v160
	v_cmp_nlt_f32_e64 s[6:7], s5, v64
	s_nop 1
	v_cndmask_b32_e64 v140, v161, v160, s[6:7]
	v_and_b32_e32 v64, 0xffff0000, v66
	v_add_f32_e32 v64, v9, v64
	v_mul_f32_e32 v64, 0xbfb8aa3b, v64
	v_exp_f32_e32 v64, v64
	s_nop 0
	v_add_f32_e32 v64, 1.0, v64
	v_rcp_f32_e32 v64, v64
	s_nop 0
	v_mul_f32_e32 v148, v83, v64
	v_mul_f32_e32 v64, 0x3fb17218, v148
	v_mul_f32_e32 v160, 0x3fb8aa3b, v64
	v_exp_f32_e32 v160, v160
	v_fmamk_f32 v161, v64, 0x3c088889, v202
	v_fmaak_f32 v161, v64, v161, 0x3e2aaaab
	v_fma_f32 v161, v64, v161, 0.5
	v_fma_f32 v161, v64, v161, 1.0
	v_mul_f32_e64 v161, v161, -v64
	v_sub_f32_e32 v160, 1.0, v160
	v_cmp_nlt_f32_e64 s[6:7], s5, v64
	s_nop 1
	v_cndmask_b32_e64 v141, v161, v160, s[6:7]
	v_lshlrev_b32_e32 v64, 16, v67
	v_add_f32_e32 v64, v10, v64
	v_mul_f32_e32 v64, 0xbfb8aa3b, v64
	v_exp_f32_e32 v64, v64
	s_nop 0
	v_add_f32_e32 v64, 1.0, v64
	v_rcp_f32_e32 v64, v64
	s_nop 0
	v_mul_f32_e32 v149, v82, v64
	v_mul_f32_e32 v65, 0x3fb17218, v149
	v_mul_f32_e32 v160, 0x3fb8aa3b, v65
	v_exp_f32_e32 v160, v160
	v_fmamk_f32 v161, v65, 0x3c088889, v202
	v_fmaak_f32 v161, v65, v161, 0x3e2aaaab
	v_fma_f32 v161, v65, v161, 0.5
	v_fma_f32 v161, v65, v161, 1.0
	v_mul_f32_e64 v161, v161, -v65
	v_sub_f32_e32 v160, 1.0, v160
	v_cmp_nlt_f32_e64 s[6:7], s5, v65
	s_nop 1
	v_cndmask_b32_e64 v64, v161, v160, s[6:7]
	v_and_b32_e32 v65, 0xffff0000, v67
	v_add_f32_e32 v65, v11, v65
	v_mul_f32_e32 v65, 0xbfb8aa3b, v65
	v_exp_f32_e32 v65, v65
	s_nop 0
	v_add_f32_e32 v65, 1.0, v65
	v_rcp_f32_e32 v65, v65
	s_nop 0
	v_mul_f32_e32 v143, v81, v65
	v_mul_f32_e32 v66, 0x3fb17218, v143
	v_cmp_nlt_f32_e64 s[6:7], s5, v66
	s_and_saveexec_b64 s[28:29], s[6:7]
	s_xor_b64 s[6:7], exec, s[28:29]
	v_mul_f32_e32 v65, 0x3fb8aa3b, v66
	v_exp_f32_e32 v65, v65
	s_nop 0
	v_sub_f32_e32 v65, 1.0, v65
	s_andn2_saveexec_b64 s[6:7], s[6:7]
	s_cbranch_execz .LBB0_1013
	v_fmamk_f32 v65, v66, 0x3c088889, v202
	v_fmaak_f32 v65, v66, v65, 0x3e2aaaab
	v_fma_f32 v65, v66, v65, 0.5
	v_fma_f32 v65, v66, v65, 1.0
	v_mul_f32_e64 v65, v65, -v66
	s_branch .LBB0_1013

; __device__ __forceinline__ unsigned pk2(float lo, float hi) { f32x2_pk v = {lo, hi}; bf16x2_pk b = __builtin_convertvector(v, bf16x2_pk); return __builtin_bit_cast(unsigned, b); }
; __device__ __forceinline__ float sigmoidf_(float x) { return __builtin_amdgcn_rcpf(1.0f + __expf(-x)); }
; __device__ __forceinline__ void rg_unpack8(const u32x4 w, float* v) { v[0] = bflo(w.x); v[1] = bfhi(w.x); v[2] = bflo(w.y); v[3] = bfhi(w.y); v[4] = bflo(w.z); v[5] = bfhi(w.z); v[6] = bflo(w.w); v[7] = bfhi(w.w); }
; __device__ __forceinline__ void rg_ab(float ra, float ri, float x, float ba, float bx, float sp, float& a, float& b) {
;     const float r = sigmoidf_(ra + ba), ig = sigmoidf_(ri + bx); const float l2 = r * sp; a = exp2f(l2);
;     const float x2 = 1.3862943611198906f * l2;
;     const float om = x2 > -0.125f ? -x2 * (1.0f + x2 * (0.5f + x2 * (0.16666667f + x2 * (0.041666668f + x2 * 0.0083333338f)))) : 1.0f - __expf(x2);
;     b = __builtin_amdgcn_sqrtf(om) * (ig * x);
; }
; __device__ __forceinline__ void rg_scan2_phase(const bf16_t* RA0, bf16_t* RI0, const bf16_t* RA1, const bf16_t* RI1, const bf16_t* XCV, const float* bap, const float* bxp, const float* lamp, const float* CAR, bf16_t* Gb, int gtid, int ngt) {
;     ...
;         for (int i = 0; i < 64; ++i) { const size_t off = (size_t)(row0 + i) * DRNN + 8 * cg;
;             float ra[8], ri[8], xv[8]; rg_unpack8(*(const u32x4*)(RA0 + off), ra); rg_unpack8(*(const u32x4*)(RI0 + off), ri); rg_unpack8(*(const u32x4*)(XCV + off), xv);
; #pragma unroll
;             for (int e = 0; e < 8; ++e) { float a, bb; rg_ab(ra[e], ri[e], xv[e], ba[e], bx[e], sp[e], a, bb); h[e] = a * h[e] + bb; }
;             u32x4 o; o.x = pk2(h[0], h[1]); o.y = pk2(h[2], h[3]); o.z = pk2(h[4], h[5]); o.w = pk2(h[6], h[7]); *(u32x4*)(RI0 + off) = o; }
.LBB0_1251:
	v_lshl_add_u64 v[38:39], v[34:35], 0, s[6:7]
	v_add_co_u32_e32 v16, vcc, 0xe400000, v38
	s_nop 1
	v_addc_co_u32_e32 v17, vcc, 0, v39, vcc
	global_load_dwordx4 v[24:27], v[16:17], off
	v_add_co_u32_e32 v16, vcc, 0x13e00000, v38
	s_waitcnt vmcnt(0)
	v_lshlrev_b32_e32 v31, 16, v24
	v_addc_co_u32_e32 v17, vcc, 0, v39, vcc
	v_add_co_u32_e32 v20, vcc, 0x8a00000, v38
	global_load_dwordx4 v[16:19], v[16:17], off
	s_nop 0
	v_addc_co_u32_e32 v21, vcc, 0, v39, vcc
	global_load_dwordx4 v[20:23], v[20:21], off
	v_add_f32_e32 v31, v0, v31
	v_mul_f32_e32 v31, 0xbfb8aa3b, v31
	v_exp_f32_e32 v31, v31
	s_nop 0
	v_add_f32_e32 v31, 1.0, v31
	v_rcp_f32_e32 v31, v31
	s_nop 0
	v_mul_f32_e32 v31, v74, v31
	v_mul_f32_e32 v43, 0x3fb17218, v31
	v_mul_f32_e32 v92, 0x3fb8aa3b, v43
	v_exp_f32_e32 v92, v92
	v_fmamk_f32 v93, v43, 0x3c088889, v202
	v_fmaak_f32 v93, v43, v93, 0x3e2aaaab
	v_fma_f32 v93, v43, v93, 0.5
	v_fma_f32 v93, v43, v93, 1.0
	v_mul_f32_e64 v93, v93, -v43
	v_sub_f32_e32 v92, 1.0, v92
	v_cmp_nlt_f32_e32 vcc, s5, v43
	s_nop 1
	v_cndmask_b32_e32 v41, v93, v92, vcc
	v_and_b32_e32 v24, 0xffff0000, v24
	v_add_f32_e32 v24, v1, v24
	v_mul_f32_e32 v24, 0xbfb8aa3b, v24
	v_exp_f32_e32 v24, v24
	s_nop 0
	v_add_f32_e32 v24, 1.0, v24
	v_rcp_f32_e32 v24, v24
	s_nop 0
	v_mul_f32_e32 v43, v73, v24
	v_mul_f32_e32 v24, 0x3fb17218, v43
	v_mul_f32_e32 v92, 0x3fb8aa3b, v24
	v_exp_f32_e32 v92, v92
	v_fmamk_f32 v93, v24, 0x3c088889, v202
	v_fmaak_f32 v93, v24, v93, 0x3e2aaaab
	v_fma_f32 v93, v24, v93, 0.5
	v_fma_f32 v93, v24, v93, 1.0
	v_mul_f32_e64 v93, v93, -v24
	v_sub_f32_e32 v92, 1.0, v92
	v_cmp_nlt_f32_e32 vcc, s5, v24
	s_nop 1
	v_cndmask_b32_e32 v59, v93, v92, vcc
	v_lshlrev_b32_e32 v24, 16, v25
	v_add_f32_e32 v24, v2, v24
	v_mul_f32_e32 v24, 0xbfb8aa3b, v24
	v_exp_f32_e32 v24, v24
	s_nop 0
	v_add_f32_e32 v24, 1.0, v24
	v_rcp_f32_e32 v24, v24
	s_nop 0
	v_mul_f32_e32 v45, v71, v24
	v_mul_f32_e32 v24, 0x3fb17218, v45
	v_mul_f32_e32 v92, 0x3fb8aa3b, v24
	v_exp_f32_e32 v92, v92
	v_fmamk_f32 v93, v24, 0x3c088889, v202
	v_fmaak_f32 v93, v24, v93, 0x3e2aaaab
	v_fma_f32 v93, v24, v93, 0.5
	v_fma_f32 v93, v24, v93, 1.0
	v_mul_f32_e64 v93, v93, -v24
	v_sub_f32_e32 v92, 1.0, v92
	v_cmp_nlt_f32_e32 vcc, s5, v24
	s_nop 1
	v_cndmask_b32_e32 v60, v93, v92, vcc
	v_and_b32_e32 v24, 0xffff0000, v25
	v_add_f32_e32 v24, v3, v24
	v_mul_f32_e32 v24, 0xbfb8aa3b, v24
	v_exp_f32_e32 v24, v24
	s_nop 0
	v_add_f32_e32 v24, 1.0, v24
	v_rcp_f32_e32 v24, v24
	s_nop 0
	v_mul_f32_e32 v61, v70, v24
	v_mul_f32_e32 v24, 0x3fb17218, v61
	v_mul_f32_e32 v92, 0x3fb8aa3b, v24
	v_exp_f32_e32 v92, v92
	v_fmamk_f32 v93, v24, 0x3c088889, v202
	v_fmaak_f32 v93, v24, v93, 0x3e2aaaab
	v_fma_f32 v93, v24, v93, 0.5
	v_fma_f32 v93, v24, v93, 1.0
	v_mul_f32_e64 v93, v93, -v24
	v_sub_f32_e32 v92, 1.0, v92
	v_cmp_nlt_f32_e32 vcc, s5, v24
	s_nop 1
	v_cndmask_b32_e32 v51, v93, v92, vcc
	v_lshlrev_b32_e32 v24, 16, v26
	v_add_f32_e32 v24, v8, v24
	v_mul_f32_e32 v24, 0xbfb8aa3b, v24
	v_exp_f32_e32 v24, v24
	s_nop 0
	v_add_f32_e32 v24, 1.0, v24
	v_rcp_f32_e32 v24, v24
	s_nop 0
	v_mul_f32_e32 v56, v69, v24
	v_mul_f32_e32 v24, 0x3fb17218, v56
	v_mul_f32_e32 v92, 0x3fb8aa3b, v24
	v_exp_f32_e32 v92, v92
	v_fmamk_f32 v93, v24, 0x3c088889, v202
	v_fmaak_f32 v93, v24, v93, 0x3e2aaaab
	v_fma_f32 v93, v24, v93, 0.5
	v_fma_f32 v93, v24, v93, 1.0
	v_mul_f32_e64 v93, v93, -v24
	v_sub_f32_e32 v92, 1.0, v92
	v_cmp_nlt_f32_e32 vcc, s5, v24
	s_nop 1
	v_cndmask_b32_e32 v49, v93, v92, vcc
	v_and_b32_e32 v24, 0xffff0000, v26
	v_add_f32_e32 v24, v9, v24
	v_mul_f32_e32 v24, 0xbfb8aa3b, v24
	v_exp_f32_e32 v24, v24
	s_nop 0
	v_add_f32_e32 v24, 1.0, v24
	v_rcp_f32_e32 v24, v24
	s_nop 0
	v_mul_f32_e32 v57, v68, v24
	v_mul_f32_e32 v24, 0x3fb17218, v57
	v_mul_f32_e32 v92, 0x3fb8aa3b, v24
	v_exp_f32_e32 v92, v92
	v_fmamk_f32 v93, v24, 0x3c088889, v202
	v_fmaak_f32 v93, v24, v93, 0x3e2aaaab
	v_fma_f32 v93, v24, v93, 0.5
	v_fma_f32 v93, v24, v93, 1.0
	v_mul_f32_e64 v93, v93, -v24
	v_sub_f32_e32 v92, 1.0, v92
	v_cmp_nlt_f32_e32 vcc, s5, v24
	s_nop 1
	v_cndmask_b32_e32 v47, v93, v92, vcc
	v_lshlrev_b32_e32 v24, 16, v27
	v_add_f32_e32 v24, v10, v24
	v_mul_f32_e32 v24, 0xbfb8aa3b, v24
	v_exp_f32_e32 v24, v24
	s_nop 0
	v_add_f32_e32 v24, 1.0, v24
	v_rcp_f32_e32 v24, v24
	s_nop 0
	v_mul_f32_e32 v54, v67, v24
	v_mul_f32_e32 v24, 0x3fb17218, v54
	v_mul_f32_e32 v92, 0x3fb8aa3b, v24
	v_exp_f32_e32 v92, v92
	v_fmamk_f32 v93, v24, 0x3c088889, v202
	v_fmaak_f32 v93, v24, v93, 0x3e2aaaab
	v_fma_f32 v93, v24, v93, 0.5
	v_fma_f32 v93, v24, v93, 1.0
	v_mul_f32_e64 v93, v93, -v24
	v_sub_f32_e32 v92, 1.0, v92
	v_cmp_nlt_f32_e32 vcc, s5, v24
	s_nop 1
	v_cndmask_b32_e32 v53, v93, v92, vcc
	v_and_b32_e32 v24, 0xffff0000, v27
	v_add_f32_e32 v24, v11, v24
	v_mul_f32_e32 v24, 0xbfb8aa3b, v24
	v_exp_f32_e32 v24, v24
	s_nop 0
	v_add_f32_e32 v24, 1.0, v24
	v_rcp_f32_e32 v24, v24
	s_nop 0
	v_mul_f32_e32 v27, v75, v24
	v_mul_f32_e32 v24, 0x3fb17218, v27
	v_mul_f32_e32 v92, 0x3fb8aa3b, v24
	v_exp_f32_e32 v92, v92
	v_fmamk_f32 v93, v24, 0x3c088889, v202
	v_fmaak_f32 v93, v24, v93, 0x3e2aaaab
	v_fma_f32 v93, v24, v93, 0.5
	v_fma_f32 v93, v24, v93, 1.0
	v_mul_f32_e64 v93, v93, -v24
	v_sub_f32_e32 v92, 1.0, v92
	v_cmp_nlt_f32_e32 vcc, s5, v24
	s_nop 1
	v_cndmask_b32_e32 v26, v93, v92, vcc
	v_cmp_gt_f32_e32 vcc, s82, v54
	s_mov_b64 s[2:3], 0x13e00000
	v_lshl_add_u64 v[24:25], v[38:39], 0, s[2:3]
	v_cndmask_b32_e32 v62, 0, v221, vcc
	v_add_f32_e32 v54, v54, v62
	v_exp_f32_e32 v54, v54
	v_cndmask_b32_e32 v55, 0, v220, vcc
	s_waitcnt vmcnt(0)
; __device__ __forceinline__ unsigned pk2(float lo, float hi) { f32x2_pk v = {lo, hi}; bf16x2_pk b = __builtin_convertvector(v, bf16x2_pk); return __builtin_bit_cast(unsigned, b); }
; __device__ __forceinline__ float sigmoidf_(float x) { return __builtin_amdgcn_rcpf(1.0f + __expf(-x)); }
; __device__ __forceinline__ void rg_ab(float ra, float ri, float x, float ba, float bx, float sp, float& a, float& b) {
;     const float r = sigmoidf_(ra + ba), ig = sigmoidf_(ri + bx); const float l2 = r * sp; a = exp2f(l2);
;     const float x2 = 1.3862943611198906f * l2;
;     const float om = x2 > -0.125f ? -x2 * (1.0f + x2 * (0.5f + x2 * (0.16666667f + x2 * (0.041666668f + x2 * 0.0083333338f)))) : 1.0f - __expf(x2);
;     b = __builtin_amdgcn_sqrtf(om) * (ig * x);
; __device__ __forceinline__ void rg_scan2_phase(const bf16_t* RA0, bf16_t* RI0, const bf16_t* RA1, const bf16_t* RI1, const bf16_t* XCV, const float* bap, const float* bxp, const float* lamp, const float* CAR, bf16_t* Gb, int gtid, int ngt) {
;     ...
;             for (int e = 0; e < 8; ++e) { float a, bb; rg_ab(ra[e], ri[e], xv[e], ba[e], bx[e], sp[e], a, bb); h[e] = a * h[e] + bb; }
;             u32x4 o; o.x = pk2(h[0], h[1]); o.y = pk2(h[2], h[3]); o.z = pk2(h[4], h[5]); o.w = pk2(h[6], h[7]); *(u32x4*)(RI0 + off) = o; }
	v_lshlrev_b32_e32 v62, 16, v23
	v_cmp_gt_f32_e32 vcc, s82, v27
	v_ldexp_f32 v54, v54, v55
	v_lshlrev_b32_e32 v55, 16, v19
	v_add_f32_e32 v55, v14, v55
	v_mul_f32_e32 v55, 0xbfb8aa3b, v55
	v_exp_f32_e32 v55, v55
	s_mov_b32 s1, 0xe400000
	v_add_f32_e32 v55, 1.0, v55
	v_rcp_f32_e32 v63, v55
	v_sqrt_f32_e32 v55, v53
	v_mul_f32_e32 v53, v63, v62
	v_mul_f32_e32 v62, v53, v55
	v_pk_fma_f32 v[54:55], v[52:53], v[54:55], v[62:63] op_sel_hi:[1,1,0]
	v_cndmask_b32_e32 v53, 0, v221, vcc
	v_add_f32_e32 v27, v27, v53
	v_exp_f32_e32 v27, v27
	v_cndmask_b32_e32 v52, 0, v220, vcc
	v_cmp_gt_f32_e32 vcc, s82, v57
	v_sqrt_f32_e32 v53, v47
	v_ldexp_f32 v62, v27, v52
	v_cndmask_b32_e32 v52, 0, v221, vcc
	v_add_f32_e32 v52, v57, v52
	v_exp_f32_e32 v52, v52
	v_cndmask_b32_e32 v27, 0, v220, vcc
	v_and_b32_e32 v55, 0xffff0000, v22
	v_cmp_gt_f32_e32 vcc, s82, v56
	v_ldexp_f32 v52, v52, v27
	v_and_b32_e32 v27, 0xffff0000, v18
	v_add_f32_e32 v27, v13, v27
	v_mul_f32_e32 v27, 0xbfb8aa3b, v27
	v_exp_f32_e32 v27, v27
	v_lshlrev_b32_e32 v18, 16, v18
	v_add_f32_e32 v18, v12, v18
	v_mul_f32_e32 v18, 0xbfb8aa3b, v18
	v_add_f32_e32 v27, 1.0, v27
	v_exp_f32_e32 v18, v18
	v_rcp_f32_e32 v27, v27
	v_lshlrev_b32_e32 v22, 16, v22
	v_sqrt_f32_e32 v63, v26
	v_add_f32_e32 v18, 1.0, v18
	v_mul_f32_e32 v47, v27, v55
	v_rcp_f32_e32 v18, v18
	v_mul_f32_e32 v76, v47, v53
	v_pk_fma_f32 v[52:53], v[46:47], v[52:53], v[76:77] op_sel_hi:[1,1,0]
	v_cndmask_b32_e32 v46, 0, v221, vcc
	v_cndmask_b32_e32 v27, 0, v220, vcc
	v_add_f32_e32 v46, v56, v46
	v_cmp_gt_f32_e32 vcc, s82, v61
	v_exp_f32_e32 v46, v46
	v_sqrt_f32_e32 v47, v49
	v_mul_f32_e32 v49, v18, v22
	v_cndmask_b32_e32 v22, 0, v221, vcc
	v_add_f32_e32 v22, v61, v22
	v_exp_f32_e32 v22, v22
	v_ldexp_f32 v46, v46, v27
	v_mul_f32_e32 v18, v49, v47
	v_pk_fma_f32 v[56:57], v[48:49], v[46:47], v[18:19] op_sel_hi:[1,1,0]
	v_cndmask_b32_e32 v18, 0, v220, vcc
	v_ldexp_f32 v46, v22, v18
	v_and_b32_e32 v18, 0xffff0000, v17
	v_add_f32_e32 v18, v7, v18
	v_mul_f32_e32 v18, 0xbfb8aa3b, v18
	v_exp_f32_e32 v18, v18
	v_lshlrev_b32_e32 v17, 16, v17
	v_add_f32_e32 v17, v6, v17
	v_mul_f32_e32 v17, 0xbfb8aa3b, v17
	v_add_f32_e32 v18, 1.0, v18
	v_rcp_f32_e32 v18, v18
	v_exp_f32_e32 v17, v17
	v_and_b32_e32 v22, 0xffff0000, v21
	v_sqrt_f32_e32 v47, v51
	v_cmp_gt_f32_e32 vcc, s82, v45
	v_mul_f32_e32 v51, v18, v22
	v_add_f32_e32 v17, 1.0, v17
	v_cndmask_b32_e32 v22, 0, v221, vcc
	v_add_f32_e32 v22, v45, v22
	v_exp_f32_e32 v22, v22
	v_mul_f32_e32 v18, v51, v47
	v_rcp_f32_e32 v17, v17
	v_pk_fma_f32 v[50:51], v[50:51], v[46:47], v[18:19] op_sel_hi:[1,1,0]
	v_sqrt_f32_e32 v47, v60
	v_cndmask_b32_e32 v18, 0, v220, vcc
	v_ldexp_f32 v46, v22, v18
	v_lshlrev_b32_e32 v18, 16, v21
	v_mul_f32_e32 v45, v17, v18
	v_mul_f32_e32 v18, v45, v47
	v_cmp_gt_f32_e32 vcc, s82, v43
	v_pk_fma_f32 v[48:49], v[44:45], v[46:47], v[18:19] op_sel_hi:[1,1,0]
	v_sqrt_f32_e32 v45, v59
	v_cndmask_b32_e32 v18, 0, v221, vcc
	v_add_f32_e32 v18, v43, v18
	v_exp_f32_e32 v18, v18
	v_cndmask_b32_e32 v17, 0, v220, vcc
	v_cmp_gt_f32_e32 vcc, s82, v31
	v_ldexp_f32 v44, v18, v17
	v_and_b32_e32 v17, 0xffff0000, v16
	v_add_f32_e32 v17, v5, v17
	v_mul_f32_e32 v17, 0xbfb8aa3b, v17
	v_exp_f32_e32 v17, v17
	v_and_b32_e32 v18, 0xffff0000, v20
	v_add_f32_e32 v17, 1.0, v17
	v_rcp_f32_e32 v17, v17
	s_nop 0
	v_mul_f32_e32 v43, v17, v18
	v_lshlrev_b32_e32 v17, 16, v16
	v_mul_f32_e32 v18, v42, v44
	v_add_f32_e32 v17, v4, v17
	v_pk_fma_f32 v[46:47], v[42:43], v[44:45], v[18:19] op_sel_hi:[1,1,0]
	v_lshlrev_b32_e32 v18, 16, v20
	v_cndmask_b32_e32 v20, 0, v221, vcc
	v_mul_f32_e32 v17, 0xbfb8aa3b, v17
	v_add_f32_e32 v20, v31, v20
	v_exp_f32_e32 v17, v17
	v_exp_f32_e32 v20, v20
	v_cndmask_b32_e32 v16, 0, v220, vcc
	v_add_f32_e32 v17, 1.0, v17
	v_ldexp_f32 v16, v20, v16
	v_rcp_f32_e32 v20, v17
	v_sqrt_f32_e32 v17, v41
	v_mul_f32_e32 v41, v20, v18
	v_mul_f32_e32 v18, v41, v17
	v_pk_fma_f32 v[42:43], v[40:41], v[16:17], v[18:19] op_sel_hi:[1,1,0]
	v_and_b32_e32 v16, 0xffff0000, v19
	v_add_f32_e32 v16, v15, v16
	v_mul_f32_e32 v16, 0xbfb8aa3b, v16
	v_exp_f32_e32 v16, v16
	v_and_b32_e32 v17, 0xffff0000, v23
	v_cvt_pk_bf16_f32 v18, v56, v52
	v_add_f32_e32 v16, 1.0, v16
	v_rcp_f32_e32 v16, v16
	s_nop 0
	v_mul_f32_e32 v59, v16, v17
	v_mul_f32_e32 v16, v59, v63
	v_pk_fma_f32 v[40:41], v[58:59], v[62:63], v[16:17] op_sel_hi:[1,1,0]
	v_cvt_pk_bf16_f32 v16, v42, v47
	v_cvt_pk_bf16_f32 v17, v48, v50
	v_cvt_pk_bf16_f32 v19, v54, v40
	global_store_dwordx4 v[24:25], v[16:19], off
	s_nop 1
	v_add_co_u32_e32 v16, vcc, s1, v38
	s_mov_b32 s1, 0x13e00000
	s_nop 0
	v_addc_co_u32_e32 v17, vcc, 0, v39, vcc
	global_load_dwordx4 v[24:27], v[16:17], off offset:2560
	v_add_co_u32_e32 v16, vcc, s1, v38
	s_waitcnt vmcnt(0)
; __device__ __forceinline__ unsigned pk2(float lo, float hi) { f32x2_pk v = {lo, hi}; bf16x2_pk b = __builtin_convertvector(v, bf16x2_pk); return __builtin_bit_cast(unsigned, b); }
; __device__ __forceinline__ float sigmoidf_(float x) { return __builtin_amdgcn_rcpf(1.0f + __expf(-x)); }
; __device__ __forceinline__ void rg_unpack8(const u32x4 w, float* v) { v[0] = bflo(w.x); v[1] = bfhi(w.x); v[2] = bflo(w.y); v[3] = bfhi(w.y); v[4] = bflo(w.z); v[5] = bfhi(w.z); v[6] = bflo(w.w); v[7] = bfhi(w.w); }
; __device__ __forceinline__ void rg_ab(float ra, float ri, float x, float ba, float bx, float sp, float& a, float& b) {
;     const float r = sigmoidf_(ra + ba), ig = sigmoidf_(ri + bx); const float l2 = r * sp; a = exp2f(l2);
;     const float x2 = 1.3862943611198906f * l2;
;     const float om = x2 > -0.125f ? -x2 * (1.0f + x2 * (0.5f + x2 * (0.16666667f + x2 * (0.041666668f + x2 * 0.0083333338f)))) : 1.0f - __expf(x2);
;     b = __builtin_amdgcn_sqrtf(om) * (ig * x);
; }
; __device__ __forceinline__ void rg_scan2_phase(const bf16_t* RA0, bf16_t* RI0, const bf16_t* RA1, const bf16_t* RI1, const bf16_t* XCV, const float* bap, const float* bxp, const float* lamp, const float* CAR, bf16_t* Gb, int gtid, int ngt) {
;     ...
;         for (int i = 0; i < 64; ++i) { const size_t off = (size_t)(row0 + i) * DRNN + 8 * cg;
;             float ra[8], ri[8], xv[8]; rg_unpack8(*(const u32x4*)(RA0 + off), ra); rg_unpack8(*(const u32x4*)(RI0 + off), ri); rg_unpack8(*(const u32x4*)(XCV + off), xv);
; #pragma unroll
;             for (int e = 0; e < 8; ++e) { float a, bb; rg_ab(ra[e], ri[e], xv[e], ba[e], bx[e], sp[e], a, bb); h[e] = a * h[e] + bb; }
;             u32x4 o; o.x = pk2(h[0], h[1]); o.y = pk2(h[2], h[3]); o.z = pk2(h[4], h[5]); o.w = pk2(h[6], h[7]); *(u32x4*)(RI0 + off) = o; }
	v_lshlrev_b32_e32 v31, 16, v24
	v_addc_co_u32_e32 v17, vcc, 0, v39, vcc
	v_add_co_u32_e32 v20, vcc, 0x8a00000, v38
	global_load_dwordx4 v[16:19], v[16:17], off offset:2560
	s_nop 0
	v_addc_co_u32_e32 v21, vcc, 0, v39, vcc
	global_load_dwordx4 v[20:23], v[20:21], off offset:2560
	v_add_f32_e32 v31, v0, v31
	v_mul_f32_e32 v31, 0xbfb8aa3b, v31
	v_exp_f32_e32 v31, v31
	s_nop 0
	v_add_f32_e32 v31, 1.0, v31
	v_rcp_f32_e32 v31, v31
	s_nop 0
	v_mul_f32_e32 v31, v74, v31
	v_mul_f32_e32 v43, 0x3fb17218, v31
	v_mul_f32_e32 v92, 0x3fb8aa3b, v43
	v_exp_f32_e32 v92, v92
	v_fmamk_f32 v93, v43, 0x3c088889, v202
	v_fmaak_f32 v93, v43, v93, 0x3e2aaaab
	v_fma_f32 v93, v43, v93, 0.5
	v_fma_f32 v93, v43, v93, 1.0
	v_mul_f32_e64 v93, v93, -v43
	v_sub_f32_e32 v92, 1.0, v92
	v_cmp_nlt_f32_e32 vcc, s5, v43
	s_nop 1
	v_cndmask_b32_e32 v41, v93, v92, vcc
	v_and_b32_e32 v24, 0xffff0000, v24
	v_add_f32_e32 v24, v1, v24
	v_mul_f32_e32 v24, 0xbfb8aa3b, v24
	v_exp_f32_e32 v24, v24
	s_nop 0
	v_add_f32_e32 v24, 1.0, v24
	v_rcp_f32_e32 v24, v24
	s_nop 0
	v_mul_f32_e32 v43, v73, v24
	v_mul_f32_e32 v24, 0x3fb17218, v43
	v_mul_f32_e32 v92, 0x3fb8aa3b, v24
	v_exp_f32_e32 v92, v92
	v_fmamk_f32 v93, v24, 0x3c088889, v202
	v_fmaak_f32 v93, v24, v93, 0x3e2aaaab
	v_fma_f32 v93, v24, v93, 0.5
	v_fma_f32 v93, v24, v93, 1.0
	v_mul_f32_e64 v93, v93, -v24
	v_sub_f32_e32 v92, 1.0, v92
	v_cmp_nlt_f32_e32 vcc, s5, v24
	s_nop 1
	v_cndmask_b32_e32 v46, v93, v92, vcc
	v_lshlrev_b32_e32 v24, 16, v25
	v_add_f32_e32 v24, v2, v24
	v_mul_f32_e32 v24, 0xbfb8aa3b, v24
	v_exp_f32_e32 v24, v24
	s_nop 0
	v_add_f32_e32 v24, 1.0, v24
	v_rcp_f32_e32 v24, v24
	s_nop 0
	v_mul_f32_e32 v49, v71, v24
	v_mul_f32_e32 v24, 0x3fb17218, v49
	v_mul_f32_e32 v92, 0x3fb8aa3b, v24
	v_exp_f32_e32 v92, v92
	v_fmamk_f32 v93, v24, 0x3c088889, v202
	v_fmaak_f32 v93, v24, v93, 0x3e2aaaab
	v_fma_f32 v93, v24, v93, 0.5
	v_fma_f32 v93, v24, v93, 1.0
	v_mul_f32_e64 v93, v93, -v24
	v_sub_f32_e32 v92, 1.0, v92
	v_cmp_nlt_f32_e32 vcc, s5, v24
	s_nop 1
	v_cndmask_b32_e32 v58, v93, v92, vcc
	v_and_b32_e32 v24, 0xffff0000, v25
	v_add_f32_e32 v24, v3, v24
	v_mul_f32_e32 v24, 0xbfb8aa3b, v24
	v_exp_f32_e32 v24, v24
	s_nop 0
	v_add_f32_e32 v24, 1.0, v24
	v_rcp_f32_e32 v24, v24
	s_nop 0
	v_mul_f32_e32 v59, v70, v24
	v_mul_f32_e32 v24, 0x3fb17218, v59
	v_mul_f32_e32 v92, 0x3fb8aa3b, v24
	v_exp_f32_e32 v92, v92
	v_fmamk_f32 v93, v24, 0x3c088889, v202
	v_fmaak_f32 v93, v24, v93, 0x3e2aaaab
	v_fma_f32 v93, v24, v93, 0.5
	v_fma_f32 v93, v24, v93, 1.0
	v_mul_f32_e64 v93, v93, -v24
	v_sub_f32_e32 v92, 1.0, v92
	v_cmp_nlt_f32_e32 vcc, s5, v24
	s_nop 1
	v_cndmask_b32_e32 v51, v93, v92, vcc
	v_lshlrev_b32_e32 v24, 16, v26
	v_add_f32_e32 v24, v8, v24
	v_mul_f32_e32 v24, 0xbfb8aa3b, v24
	v_exp_f32_e32 v24, v24
	s_nop 0
	v_add_f32_e32 v24, 1.0, v24
	v_rcp_f32_e32 v24, v24
	s_nop 0
	v_mul_f32_e32 v45, v69, v24
	v_mul_f32_e32 v24, 0x3fb17218, v45
	v_mul_f32_e32 v92, 0x3fb8aa3b, v24
	v_exp_f32_e32 v92, v92
	v_fmamk_f32 v93, v24, 0x3c088889, v202
	v_fmaak_f32 v93, v24, v93, 0x3e2aaaab
	v_fma_f32 v93, v24, v93, 0.5
	v_fma_f32 v93, v24, v93, 1.0
	v_mul_f32_e64 v93, v93, -v24
	v_sub_f32_e32 v92, 1.0, v92
	v_cmp_nlt_f32_e32 vcc, s5, v24
	s_nop 1
	v_cndmask_b32_e32 v44, v93, v92, vcc
	v_and_b32_e32 v24, 0xffff0000, v26
	v_add_f32_e32 v24, v9, v24
	v_mul_f32_e32 v24, 0xbfb8aa3b, v24
	v_exp_f32_e32 v24, v24
	s_nop 0
	v_add_f32_e32 v24, 1.0, v24
	v_rcp_f32_e32 v24, v24
	s_nop 0
	v_mul_f32_e32 v57, v68, v24
	v_mul_f32_e32 v24, 0x3fb17218, v57
	v_mul_f32_e32 v92, 0x3fb8aa3b, v24
	v_exp_f32_e32 v92, v92
	v_fmamk_f32 v93, v24, 0x3c088889, v202
	v_fmaak_f32 v93, v24, v93, 0x3e2aaaab
	v_fma_f32 v93, v24, v93, 0.5
	v_fma_f32 v93, v24, v93, 1.0
	v_mul_f32_e64 v93, v93, -v24
	v_sub_f32_e32 v92, 1.0, v92
	v_cmp_nlt_f32_e32 vcc, s5, v24
	s_nop 1
	v_cndmask_b32_e32 v53, v93, v92, vcc
	v_lshlrev_b32_e32 v24, 16, v27
	v_add_f32_e32 v24, v10, v24
	v_mul_f32_e32 v24, 0xbfb8aa3b, v24
	v_exp_f32_e32 v24, v24
	s_nop 0
	v_add_f32_e32 v24, 1.0, v24
	v_rcp_f32_e32 v24, v24
	s_nop 0
	v_mul_f32_e32 v60, v67, v24
	v_mul_f32_e32 v24, 0x3fb17218, v60
	v_mul_f32_e32 v92, 0x3fb8aa3b, v24
	v_exp_f32_e32 v92, v92
	v_fmamk_f32 v93, v24, 0x3c088889, v202
	v_fmaak_f32 v93, v24, v93, 0x3e2aaaab
	v_fma_f32 v93, v24, v93, 0.5
	v_fma_f32 v93, v24, v93, 1.0
	v_mul_f32_e64 v93, v93, -v24
	v_sub_f32_e32 v92, 1.0, v92
	v_cmp_nlt_f32_e32 vcc, s5, v24
	s_nop 1
	v_cndmask_b32_e32 v55, v93, v92, vcc
	v_and_b32_e32 v24, 0xffff0000, v27
	v_add_f32_e32 v24, v11, v24
	v_mul_f32_e32 v24, 0xbfb8aa3b, v24
	v_exp_f32_e32 v24, v24
	s_nop 0
	v_add_f32_e32 v24, 1.0, v24
	v_rcp_f32_e32 v24, v24
	s_nop 0
	v_mul_f32_e32 v27, v75, v24
	v_mul_f32_e32 v24, 0x3fb17218, v27
	v_mul_f32_e32 v92, 0x3fb8aa3b, v24
	v_exp_f32_e32 v92, v92
	v_fmamk_f32 v93, v24, 0x3c088889, v202
	v_fmaak_f32 v93, v24, v93, 0x3e2aaaab
	v_fma_f32 v93, v24, v93, 0.5
	v_fma_f32 v93, v24, v93, 1.0
	v_mul_f32_e64 v93, v93, -v24
	v_sub_f32_e32 v92, 1.0, v92
	v_cmp_nlt_f32_e32 vcc, s5, v24
	s_nop 1
	v_cndmask_b32_e32 v26, v93, v92, vcc
	v_cmp_gt_f32_e32 vcc, s82, v60
	v_sqrt_f32_e32 v77, v26
	s_mov_b32 s1, 0xe401000
	v_cndmask_b32_e32 v62, 0, v221, vcc
	v_add_f32_e32 v60, v60, v62
	v_exp_f32_e32 v60, v60
	v_cndmask_b32_e32 v61, 0, v220, vcc
	s_waitcnt vmcnt(0)
; __device__ __forceinline__ unsigned pk2(float lo, float hi) { f32x2_pk v = {lo, hi}; bf16x2_pk b = __builtin_convertvector(v, bf16x2_pk); return __builtin_bit_cast(unsigned, b); }
; __device__ __forceinline__ float sigmoidf_(float x) { return __builtin_amdgcn_rcpf(1.0f + __expf(-x)); }
; __device__ __forceinline__ void rg_ab(float ra, float ri, float x, float ba, float bx, float sp, float& a, float& b) {
;     const float r = sigmoidf_(ra + ba), ig = sigmoidf_(ri + bx); const float l2 = r * sp; a = exp2f(l2);
;     const float x2 = 1.3862943611198906f * l2;
;     const float om = x2 > -0.125f ? -x2 * (1.0f + x2 * (0.5f + x2 * (0.16666667f + x2 * (0.041666668f + x2 * 0.0083333338f)))) : 1.0f - __expf(x2);
;     b = __builtin_amdgcn_sqrtf(om) * (ig * x);
; __device__ __forceinline__ void rg_scan2_phase(const bf16_t* RA0, bf16_t* RI0, const bf16_t* RA1, const bf16_t* RI1, const bf16_t* XCV, const float* bap, const float* bxp, const float* lamp, const float* CAR, bf16_t* Gb, int gtid, int ngt) {
;     ...
;             for (int e = 0; e < 8; ++e) { float a, bb; rg_ab(ra[e], ri[e], xv[e], ba[e], bx[e], sp[e], a, bb); h[e] = a * h[e] + bb; }
;             u32x4 o; o.x = pk2(h[0], h[1]); o.y = pk2(h[2], h[3]); o.z = pk2(h[4], h[5]); o.w = pk2(h[6], h[7]); *(u32x4*)(RI0 + off) = o; }
	v_lshlrev_b32_e32 v62, 16, v23
	v_cmp_gt_f32_e32 vcc, s82, v27
	v_ldexp_f32 v60, v60, v61
	v_lshlrev_b32_e32 v61, 16, v19
	v_add_f32_e32 v61, v14, v61
	v_mul_f32_e32 v61, 0xbfb8aa3b, v61
	v_exp_f32_e32 v61, v61
	s_mov_b64 s[2:3], 0x13e00a00
	v_lshl_add_u64 v[24:25], v[38:39], 0, s[2:3]
	v_add_f32_e32 v61, 1.0, v61
	v_rcp_f32_e32 v63, v61
	v_sqrt_f32_e32 v61, v55
	v_mul_f32_e32 v55, v63, v62
	v_mul_f32_e32 v62, v55, v61
	v_pk_fma_f32 v[54:55], v[54:55], v[60:61], v[62:63] op_sel_hi:[1,1,0]
	v_cndmask_b32_e32 v60, 0, v221, vcc
	v_add_f32_e32 v27, v27, v60
	v_exp_f32_e32 v27, v27
	v_cndmask_b32_e32 v55, 0, v220, vcc
	v_cmp_gt_f32_e32 vcc, s82, v57
	v_sqrt_f32_e32 v61, v53
	v_ldexp_f32 v76, v27, v55
	v_cndmask_b32_e32 v55, 0, v221, vcc
	v_add_f32_e32 v55, v57, v55
	v_exp_f32_e32 v55, v55
	v_cndmask_b32_e32 v27, 0, v220, vcc
	v_cmp_gt_f32_e32 vcc, s82, v45
	v_ldexp_f32 v60, v55, v27
	v_and_b32_e32 v27, 0xffff0000, v18
	v_add_f32_e32 v27, v13, v27
	v_mul_f32_e32 v27, 0xbfb8aa3b, v27
	v_exp_f32_e32 v27, v27
	v_lshlrev_b32_e32 v18, 16, v18
	v_add_f32_e32 v18, v12, v18
	v_mul_f32_e32 v18, 0xbfb8aa3b, v18
	v_add_f32_e32 v27, 1.0, v27
	v_rcp_f32_e32 v27, v27
	v_exp_f32_e32 v18, v18
	v_and_b32_e32 v55, 0xffff0000, v22
	v_lshlrev_b32_e32 v22, 16, v22
	v_mul_f32_e32 v53, v27, v55
	v_add_f32_e32 v18, 1.0, v18
	v_mul_f32_e32 v62, v53, v61
	v_rcp_f32_e32 v18, v18
	v_pk_fma_f32 v[52:53], v[52:53], v[60:61], v[62:63] op_sel_hi:[1,1,0]
	v_cndmask_b32_e32 v27, 0, v220, vcc
	v_cndmask_b32_e32 v53, 0, v221, vcc
	v_add_f32_e32 v45, v45, v53
	v_cmp_gt_f32_e32 vcc, s82, v59
	v_exp_f32_e32 v45, v45
	v_sqrt_f32_e32 v61, v44
	v_mul_f32_e32 v57, v18, v22
	v_cndmask_b32_e32 v22, 0, v221, vcc
	v_add_f32_e32 v22, v59, v22
	v_exp_f32_e32 v22, v22
	v_ldexp_f32 v60, v45, v27
	v_mul_f32_e32 v18, v57, v61
	v_pk_fma_f32 v[44:45], v[56:57], v[60:61], v[18:19] op_sel_hi:[1,1,0]
	v_cndmask_b32_e32 v18, 0, v220, vcc
	v_ldexp_f32 v56, v22, v18
	v_and_b32_e32 v18, 0xffff0000, v17
	v_add_f32_e32 v18, v7, v18
	v_mul_f32_e32 v18, 0xbfb8aa3b, v18
	v_exp_f32_e32 v18, v18
	v_lshlrev_b32_e32 v17, 16, v17
	v_add_f32_e32 v17, v6, v17
	v_mul_f32_e32 v17, 0xbfb8aa3b, v17
	v_add_f32_e32 v18, 1.0, v18
	v_rcp_f32_e32 v18, v18
	v_exp_f32_e32 v17, v17
	v_and_b32_e32 v22, 0xffff0000, v21
	v_sqrt_f32_e32 v57, v51
	v_cmp_gt_f32_e32 vcc, s82, v49
	v_mul_f32_e32 v51, v18, v22
	v_add_f32_e32 v17, 1.0, v17
	v_cndmask_b32_e32 v22, 0, v221, vcc
	v_add_f32_e32 v22, v49, v22
	v_exp_f32_e32 v22, v22
	v_mul_f32_e32 v18, v51, v57
	v_rcp_f32_e32 v17, v17
	v_pk_fma_f32 v[60:61], v[50:51], v[56:57], v[18:19] op_sel_hi:[1,1,0]
	v_sqrt_f32_e32 v51, v58
	v_cndmask_b32_e32 v18, 0, v220, vcc
	v_ldexp_f32 v50, v22, v18
	v_lshlrev_b32_e32 v18, 16, v21
	v_mul_f32_e32 v49, v17, v18
	v_mul_f32_e32 v18, v49, v51
	v_cmp_gt_f32_e32 vcc, s82, v43
	v_pk_fma_f32 v[58:59], v[48:49], v[50:51], v[18:19] op_sel_hi:[1,1,0]
	v_sqrt_f32_e32 v49, v46
	v_cndmask_b32_e32 v18, 0, v221, vcc
	v_add_f32_e32 v18, v43, v18
	v_exp_f32_e32 v18, v18
	v_cndmask_b32_e32 v17, 0, v220, vcc
	v_mov_b32_e32 v50, v47
	v_cmp_gt_f32_e32 vcc, s82, v31
	v_ldexp_f32 v48, v18, v17
	v_and_b32_e32 v17, 0xffff0000, v16
	v_add_f32_e32 v17, v5, v17
	v_mul_f32_e32 v17, 0xbfb8aa3b, v17
	v_exp_f32_e32 v17, v17
	v_and_b32_e32 v18, 0xffff0000, v20
	v_add_f32_e32 v17, 1.0, v17
	v_rcp_f32_e32 v17, v17
	s_nop 0
	v_mul_f32_e32 v51, v17, v18
	v_lshlrev_b32_e32 v17, 16, v16
	v_mul_f32_e32 v18, v47, v48
	v_add_f32_e32 v17, v4, v17
	v_pk_fma_f32 v[62:63], v[50:51], v[48:49], v[18:19] op_sel_hi:[1,1,0]
	v_lshlrev_b32_e32 v18, 16, v20
	v_cndmask_b32_e32 v20, 0, v221, vcc
	v_mul_f32_e32 v17, 0xbfb8aa3b, v17
	v_add_f32_e32 v20, v31, v20
	v_exp_f32_e32 v17, v17
	v_exp_f32_e32 v20, v20
	v_cndmask_b32_e32 v16, 0, v220, vcc
	v_add_co_u32_e32 v48, vcc, s1, v38
	v_add_f32_e32 v17, 1.0, v17
	v_ldexp_f32 v16, v20, v16
	v_rcp_f32_e32 v20, v17
	v_sqrt_f32_e32 v17, v41
	v_addc_co_u32_e32 v49, vcc, 0, v39, vcc
	v_mul_f32_e32 v43, v20, v18
	v_mul_f32_e32 v18, v43, v17
	v_pk_fma_f32 v[56:57], v[42:43], v[16:17], v[18:19] op_sel_hi:[1,1,0]
	v_and_b32_e32 v16, 0xffff0000, v19
	v_add_f32_e32 v16, v15, v16
	v_mul_f32_e32 v16, 0xbfb8aa3b, v16
	v_exp_f32_e32 v16, v16
	v_and_b32_e32 v17, 0xffff0000, v23
	v_cvt_pk_bf16_f32 v18, v44, v52
	s_mov_b32 s1, 0x13e01000
	v_add_f32_e32 v16, 1.0, v16
	v_rcp_f32_e32 v16, v16
	s_nop 0
	v_mul_f32_e32 v41, v16, v17
	v_mul_f32_e32 v16, v41, v77
	v_pk_fma_f32 v[50:51], v[40:41], v[76:77], v[16:17] op_sel_hi:[1,1,0]
	v_cvt_pk_bf16_f32 v16, v56, v63
	v_cvt_pk_bf16_f32 v17, v58, v60
	v_cvt_pk_bf16_f32 v19, v54, v50
	global_store_dwordx4 v[24:25], v[16:19], off
	global_load_dwordx4 v[24:27], v[48:49], off offset:1024
	v_add_co_u32_e32 v40, vcc, s1, v38
	s_waitcnt vmcnt(0)
; __device__ __forceinline__ unsigned pk2(float lo, float hi) { f32x2_pk v = {lo, hi}; bf16x2_pk b = __builtin_convertvector(v, bf16x2_pk); return __builtin_bit_cast(unsigned, b); }
; __device__ __forceinline__ float sigmoidf_(float x) { return __builtin_amdgcn_rcpf(1.0f + __expf(-x)); }
; __device__ __forceinline__ void rg_unpack8(const u32x4 w, float* v) { v[0] = bflo(w.x); v[1] = bfhi(w.x); v[2] = bflo(w.y); v[3] = bfhi(w.y); v[4] = bflo(w.z); v[5] = bfhi(w.z); v[6] = bflo(w.w); v[7] = bfhi(w.w); }
; __device__ __forceinline__ void rg_ab(float ra, float ri, float x, float ba, float bx, float sp, float& a, float& b) {
;     const float r = sigmoidf_(ra + ba), ig = sigmoidf_(ri + bx); const float l2 = r * sp; a = exp2f(l2);
;     const float x2 = 1.3862943611198906f * l2;
;     const float om = x2 > -0.125f ? -x2 * (1.0f + x2 * (0.5f + x2 * (0.16666667f + x2 * (0.041666668f + x2 * 0.0083333338f)))) : 1.0f - __expf(x2);
;     b = __builtin_amdgcn_sqrtf(om) * (ig * x);
; }
; __device__ __forceinline__ void rg_scan2_phase(const bf16_t* RA0, bf16_t* RI0, const bf16_t* RA1, const bf16_t* RI1, const bf16_t* XCV, const float* bap, const float* bxp, const float* lamp, const float* CAR, bf16_t* Gb, int gtid, int ngt) {
;     ...
; #pragma unroll 4
;         for (int i = 0; i < 64; ++i) { const size_t off = (size_t)(row0 + i) * DRNN + 8 * cg;
;             float ra[8], ri[8], xv[8]; rg_unpack8(*(const u32x4*)(RA0 + off), ra); rg_unpack8(*(const u32x4*)(RI0 + off), ri); rg_unpack8(*(const u32x4*)(XCV + off), xv);
; #pragma unroll
;             for (int e = 0; e < 8; ++e) { float a, bb; rg_ab(ra[e], ri[e], xv[e], ba[e], bx[e], sp[e], a, bb); h[e] = a * h[e] + bb; }
;             u32x4 o; o.x = pk2(h[0], h[1]); o.y = pk2(h[2], h[3]); o.z = pk2(h[4], h[5]); o.w = pk2(h[6], h[7]); *(u32x4*)(RI0 + off) = o; }
	v_lshlrev_b32_e32 v31, 16, v24
	v_addc_co_u32_e32 v41, vcc, 0, v39, vcc
	v_add_co_u32_e32 v20, vcc, 0x8a01000, v38
	global_load_dwordx4 v[16:19], v[40:41], off offset:1024
	s_nop 0
	v_addc_co_u32_e32 v21, vcc, 0, v39, vcc
	global_load_dwordx4 v[20:23], v[20:21], off offset:1024
	v_add_f32_e32 v31, v0, v31
	v_mul_f32_e32 v31, 0xbfb8aa3b, v31
	v_exp_f32_e32 v31, v31
	s_nop 0
	v_add_f32_e32 v31, 1.0, v31
	v_rcp_f32_e32 v31, v31
	s_nop 0
	v_mul_f32_e32 v31, v74, v31
	v_mul_f32_e32 v42, 0x3fb17218, v31
	v_mul_f32_e32 v92, 0x3fb8aa3b, v42
	v_exp_f32_e32 v92, v92
	v_fmamk_f32 v93, v42, 0x3c088889, v202
	v_fmaak_f32 v93, v42, v93, 0x3e2aaaab
	v_fma_f32 v93, v42, v93, 0.5
	v_fma_f32 v93, v42, v93, 1.0
	v_mul_f32_e64 v93, v93, -v42
	v_sub_f32_e32 v92, 1.0, v92
	v_cmp_nlt_f32_e32 vcc, s5, v42
	s_nop 1
	v_cndmask_b32_e32 v51, v93, v92, vcc
	v_and_b32_e32 v24, 0xffff0000, v24
	v_add_f32_e32 v24, v1, v24
	v_mul_f32_e32 v24, 0xbfb8aa3b, v24
	v_exp_f32_e32 v24, v24
	s_nop 0
	v_add_f32_e32 v24, 1.0, v24
	v_rcp_f32_e32 v24, v24
	s_nop 0
	v_mul_f32_e32 v57, v73, v24
	v_mul_f32_e32 v24, 0x3fb17218, v57
	v_mul_f32_e32 v92, 0x3fb8aa3b, v24
	v_exp_f32_e32 v92, v92
	v_fmamk_f32 v93, v24, 0x3c088889, v202
	v_fmaak_f32 v93, v24, v93, 0x3e2aaaab
	v_fma_f32 v93, v24, v93, 0.5
	v_fma_f32 v93, v24, v93, 1.0
	v_mul_f32_e64 v93, v93, -v24
	v_sub_f32_e32 v92, 1.0, v92
	v_cmp_nlt_f32_e32 vcc, s5, v24
	s_nop 1
	v_cndmask_b32_e32 v62, v93, v92, vcc
	v_lshlrev_b32_e32 v24, 16, v25
	v_add_f32_e32 v24, v2, v24
	v_mul_f32_e32 v24, 0xbfb8aa3b, v24
	v_exp_f32_e32 v24, v24
	s_nop 0
	v_add_f32_e32 v24, 1.0, v24
	v_rcp_f32_e32 v24, v24
	s_nop 0
	v_mul_f32_e32 v59, v71, v24
	v_mul_f32_e32 v24, 0x3fb17218, v59
	v_mul_f32_e32 v92, 0x3fb8aa3b, v24
	v_exp_f32_e32 v92, v92
	v_fmamk_f32 v93, v24, 0x3c088889, v202
	v_fmaak_f32 v93, v24, v93, 0x3e2aaaab
	v_fma_f32 v93, v24, v93, 0.5
	v_fma_f32 v93, v24, v93, 1.0
	v_mul_f32_e64 v93, v93, -v24
	v_sub_f32_e32 v92, 1.0, v92
	v_cmp_nlt_f32_e32 vcc, s5, v24
	s_nop 1
	v_cndmask_b32_e32 v76, v93, v92, vcc
	v_and_b32_e32 v24, 0xffff0000, v25
	v_add_f32_e32 v24, v3, v24
	v_mul_f32_e32 v24, 0xbfb8aa3b, v24
	v_exp_f32_e32 v24, v24
	s_nop 0
	v_add_f32_e32 v24, 1.0, v24
	v_rcp_f32_e32 v24, v24
	s_nop 0
	v_mul_f32_e32 v77, v70, v24
	v_mul_f32_e32 v24, 0x3fb17218, v77
	v_mul_f32_e32 v92, 0x3fb8aa3b, v24
	v_exp_f32_e32 v92, v92
	v_fmamk_f32 v93, v24, 0x3c088889, v202
	v_fmaak_f32 v93, v24, v93, 0x3e2aaaab
	v_fma_f32 v93, v24, v93, 0.5
	v_fma_f32 v93, v24, v93, 1.0
	v_mul_f32_e64 v93, v93, -v24
	v_sub_f32_e32 v92, 1.0, v92
	v_cmp_nlt_f32_e32 vcc, s5, v24
	s_nop 1
	v_cndmask_b32_e32 v61, v93, v92, vcc
	v_lshlrev_b32_e32 v24, 16, v26
	v_add_f32_e32 v24, v8, v24
	v_mul_f32_e32 v24, 0xbfb8aa3b, v24
	v_exp_f32_e32 v24, v24
	s_nop 0
	v_add_f32_e32 v24, 1.0, v24
	v_rcp_f32_e32 v24, v24
	s_nop 0
	v_mul_f32_e32 v78, v69, v24
	v_mul_f32_e32 v24, 0x3fb17218, v78
	v_mul_f32_e32 v92, 0x3fb8aa3b, v24
	v_exp_f32_e32 v92, v92
	v_fmamk_f32 v93, v24, 0x3c088889, v202
	v_fmaak_f32 v93, v24, v93, 0x3e2aaaab
	v_fma_f32 v93, v24, v93, 0.5
	v_fma_f32 v93, v24, v93, 1.0
	v_mul_f32_e64 v93, v93, -v24
	v_sub_f32_e32 v92, 1.0, v92
	v_cmp_nlt_f32_e32 vcc, s5, v24
	s_nop 1
	v_cndmask_b32_e32 v45, v93, v92, vcc
	v_and_b32_e32 v24, 0xffff0000, v26
	v_add_f32_e32 v24, v9, v24
	v_mul_f32_e32 v24, 0xbfb8aa3b, v24
	v_exp_f32_e32 v24, v24
	s_nop 0
	v_add_f32_e32 v24, 1.0, v24
	v_rcp_f32_e32 v24, v24
	s_nop 0
	v_mul_f32_e32 v47, v68, v24
	v_mul_f32_e32 v24, 0x3fb17218, v47
	v_mul_f32_e32 v92, 0x3fb8aa3b, v24
	v_exp_f32_e32 v92, v92
	v_fmamk_f32 v93, v24, 0x3c088889, v202
	v_fmaak_f32 v93, v24, v93, 0x3e2aaaab
	v_fma_f32 v93, v24, v93, 0.5
	v_fma_f32 v93, v24, v93, 1.0
	v_mul_f32_e64 v93, v93, -v24
	v_sub_f32_e32 v92, 1.0, v92
	v_cmp_nlt_f32_e32 vcc, s5, v24
	s_nop 1
	v_cndmask_b32_e32 v46, v93, v92, vcc
	v_lshlrev_b32_e32 v24, 16, v27
	v_add_f32_e32 v24, v10, v24
	v_mul_f32_e32 v24, 0xbfb8aa3b, v24
	v_exp_f32_e32 v24, v24
	s_nop 0
	v_add_f32_e32 v24, 1.0, v24
	v_rcp_f32_e32 v24, v24
	s_nop 0
	v_mul_f32_e32 v43, v67, v24
	v_mul_f32_e32 v24, 0x3fb17218, v43
	v_mul_f32_e32 v92, 0x3fb8aa3b, v24
	v_exp_f32_e32 v92, v92
	v_fmamk_f32 v93, v24, 0x3c088889, v202
	v_fmaak_f32 v93, v24, v93, 0x3e2aaaab
	v_fma_f32 v93, v24, v93, 0.5
	v_fma_f32 v93, v24, v93, 1.0
	v_mul_f32_e64 v93, v93, -v24
	v_sub_f32_e32 v92, 1.0, v92
	v_cmp_nlt_f32_e32 vcc, s5, v24
	s_nop 1
	v_cndmask_b32_e32 v42, v93, v92, vcc
	v_and_b32_e32 v24, 0xffff0000, v27
	v_add_f32_e32 v24, v11, v24
	v_mul_f32_e32 v24, 0xbfb8aa3b, v24
	v_exp_f32_e32 v24, v24
	s_nop 0
	v_add_f32_e32 v24, 1.0, v24
	v_rcp_f32_e32 v24, v24
	s_nop 0
	v_mul_f32_e32 v27, v75, v24
	v_mul_f32_e32 v24, 0x3fb17218, v27
	v_mul_f32_e32 v92, 0x3fb8aa3b, v24
	v_exp_f32_e32 v92, v92
	v_fmamk_f32 v93, v24, 0x3c088889, v202
	v_fmaak_f32 v93, v24, v93, 0x3e2aaaab
	v_fma_f32 v93, v24, v93, 0.5
	v_fma_f32 v93, v24, v93, 1.0
	v_mul_f32_e64 v93, v93, -v24
	v_sub_f32_e32 v92, 1.0, v92
	v_cmp_nlt_f32_e32 vcc, s5, v24
	s_nop 1
	v_cndmask_b32_e32 v26, v93, v92, vcc
	v_cmp_gt_f32_e32 vcc, s82, v43
	v_sqrt_f32_e32 v81, v42
	s_mov_b64 s[2:3], 0x13e01400
	v_cndmask_b32_e32 v55, 0, v221, vcc
	v_add_f32_e32 v43, v43, v55
	v_exp_f32_e32 v43, v43
	v_cndmask_b32_e32 v53, 0, v220, vcc
	v_cmp_gt_f32_e32 vcc, s82, v27
	v_lshl_add_u64 v[24:25], v[38:39], 0, s[2:3]
	v_ldexp_f32 v80, v43, v53
	s_waitcnt vmcnt(1)
	v_lshlrev_b32_e32 v43, 16, v19
	v_add_f32_e32 v43, v14, v43
	v_mul_f32_e32 v43, 0xbfb8aa3b, v43
	v_exp_f32_e32 v43, v43
	s_waitcnt vmcnt(0)
; __device__ __forceinline__ unsigned pk2(float lo, float hi) { f32x2_pk v = {lo, hi}; bf16x2_pk b = __builtin_convertvector(v, bf16x2_pk); return __builtin_bit_cast(unsigned, b); }
; __device__ __forceinline__ float sigmoidf_(float x) { return __builtin_amdgcn_rcpf(1.0f + __expf(-x)); }
; __device__ __forceinline__ void rg_unpack8(const u32x4 w, float* v) { v[0] = bflo(w.x); v[1] = bfhi(w.x); v[2] = bflo(w.y); v[3] = bfhi(w.y); v[4] = bflo(w.z); v[5] = bfhi(w.z); v[6] = bflo(w.w); v[7] = bfhi(w.w); }
; __device__ __forceinline__ void rg_ab(float ra, float ri, float x, float ba, float bx, float sp, float& a, float& b) {
;     const float r = sigmoidf_(ra + ba), ig = sigmoidf_(ri + bx); const float l2 = r * sp; a = exp2f(l2);
;     const float x2 = 1.3862943611198906f * l2;
;     const float om = x2 > -0.125f ? -x2 * (1.0f + x2 * (0.5f + x2 * (0.16666667f + x2 * (0.041666668f + x2 * 0.0083333338f)))) : 1.0f - __expf(x2);
;     b = __builtin_amdgcn_sqrtf(om) * (ig * x);
; }
; __device__ __forceinline__ void rg_scan2_phase(const bf16_t* RA0, bf16_t* RI0, const bf16_t* RA1, const bf16_t* RI1, const bf16_t* XCV, const float* bap, const float* bxp, const float* lamp, const float* CAR, bf16_t* Gb, int gtid, int ngt) {
;     ...
;         for (int i = 0; i < 64; ++i) { const size_t off = (size_t)(row0 + i) * DRNN + 8 * cg;
;             float ra[8], ri[8], xv[8]; rg_unpack8(*(const u32x4*)(RA0 + off), ra); rg_unpack8(*(const u32x4*)(RI0 + off), ri); rg_unpack8(*(const u32x4*)(XCV + off), xv);
; #pragma unroll
;             for (int e = 0; e < 8; ++e) { float a, bb; rg_ab(ra[e], ri[e], xv[e], ba[e], bx[e], sp[e], a, bb); h[e] = a * h[e] + bb; }
;             u32x4 o; o.x = pk2(h[0], h[1]); o.y = pk2(h[2], h[3]); o.z = pk2(h[4], h[5]); o.w = pk2(h[6], h[7]); *(u32x4*)(RI0 + off) = o; }
	v_lshlrev_b32_e32 v53, 16, v23
	v_add_f32_e32 v43, 1.0, v43
	v_rcp_f32_e32 v43, v43
	s_nop 0
	v_mul_f32_e32 v55, v43, v53
	v_cndmask_b32_e32 v53, 0, v221, vcc
	v_add_f32_e32 v27, v27, v53
	v_exp_f32_e32 v27, v27
	v_mul_f32_e32 v42, v55, v81
	v_pk_fma_f32 v[42:43], v[54:55], v[80:81], v[42:43] op_sel_hi:[1,1,0]
	v_sqrt_f32_e32 v81, v46
	v_cndmask_b32_e32 v43, 0, v220, vcc
	v_cmp_gt_f32_e32 vcc, s82, v47
	v_ldexp_f32 v54, v27, v43
	v_sqrt_f32_e32 v55, v26
	v_cndmask_b32_e32 v43, 0, v221, vcc
	v_add_f32_e32 v43, v47, v43
	v_exp_f32_e32 v43, v43
	v_cndmask_b32_e32 v27, 0, v220, vcc
	v_cmp_gt_f32_e32 vcc, s82, v78
	v_ldexp_f32 v80, v43, v27
	v_and_b32_e32 v27, 0xffff0000, v18
	v_add_f32_e32 v27, v13, v27
	v_mul_f32_e32 v27, 0xbfb8aa3b, v27
	v_lshlrev_b32_e32 v18, 16, v18
	v_exp_f32_e32 v27, v27
	v_add_f32_e32 v18, v12, v18
	v_mul_f32_e32 v18, 0xbfb8aa3b, v18
	v_exp_f32_e32 v18, v18
	v_add_f32_e32 v27, 1.0, v27
	v_rcp_f32_e32 v27, v27
	v_and_b32_e32 v43, 0xffff0000, v22
	v_add_f32_e32 v18, 1.0, v18
	v_rcp_f32_e32 v18, v18
	v_mul_f32_e32 v53, v27, v43
	v_cndmask_b32_e32 v43, 0, v221, vcc
	v_mul_f32_e32 v46, v53, v81
	v_cndmask_b32_e32 v27, 0, v220, vcc
	v_add_f32_e32 v43, v78, v43
	v_lshlrev_b32_e32 v22, 16, v22
	v_cmp_gt_f32_e32 vcc, s82, v77
	v_pk_fma_f32 v[46:47], v[52:53], v[80:81], v[46:47] op_sel_hi:[1,1,0]
	v_exp_f32_e32 v43, v43
	v_sqrt_f32_e32 v53, v45
	v_mul_f32_e32 v45, v18, v22
	v_cndmask_b32_e32 v22, 0, v221, vcc
	v_add_f32_e32 v22, v77, v22
	v_exp_f32_e32 v22, v22
	v_ldexp_f32 v52, v43, v27
	v_mul_f32_e32 v18, v45, v53
	v_pk_fma_f32 v[52:53], v[44:45], v[52:53], v[18:19] op_sel_hi:[1,1,0]
	v_cndmask_b32_e32 v18, 0, v220, vcc
	v_ldexp_f32 v44, v22, v18
	v_and_b32_e32 v18, 0xffff0000, v17
	v_add_f32_e32 v18, v7, v18
	v_mul_f32_e32 v18, 0xbfb8aa3b, v18
	v_exp_f32_e32 v18, v18
	v_lshlrev_b32_e32 v17, 16, v17
	v_add_f32_e32 v17, v6, v17
	v_mul_f32_e32 v17, 0xbfb8aa3b, v17
	v_add_f32_e32 v18, 1.0, v18
	v_rcp_f32_e32 v18, v18
	v_exp_f32_e32 v17, v17
	v_and_b32_e32 v22, 0xffff0000, v21
	v_sqrt_f32_e32 v45, v61
	v_cmp_gt_f32_e32 vcc, s82, v59
	v_mul_f32_e32 v61, v18, v22
	v_add_f32_e32 v17, 1.0, v17
	v_cndmask_b32_e32 v22, 0, v221, vcc
	v_add_f32_e32 v22, v59, v22
	v_exp_f32_e32 v22, v22
	v_mul_f32_e32 v18, v61, v45
	v_rcp_f32_e32 v17, v17
	v_pk_fma_f32 v[60:61], v[60:61], v[44:45], v[18:19] op_sel_hi:[1,1,0]
	v_sqrt_f32_e32 v45, v76
	v_cndmask_b32_e32 v18, 0, v220, vcc
	v_ldexp_f32 v44, v22, v18
	v_lshlrev_b32_e32 v18, 16, v21
	v_mul_f32_e32 v59, v17, v18
	v_mul_f32_e32 v18, v59, v45
	v_cmp_gt_f32_e32 vcc, s82, v57
	v_pk_fma_f32 v[44:45], v[58:59], v[44:45], v[18:19] op_sel_hi:[1,1,0]
	v_sqrt_f32_e32 v59, v62
	v_cndmask_b32_e32 v18, 0, v221, vcc
	v_add_f32_e32 v18, v57, v18
	v_exp_f32_e32 v18, v18
	v_cndmask_b32_e32 v17, 0, v220, vcc
	v_mov_b32_e32 v76, v63
	v_cmp_gt_f32_e32 vcc, s82, v31
	v_ldexp_f32 v58, v18, v17
	v_and_b32_e32 v17, 0xffff0000, v16
	v_add_f32_e32 v17, v5, v17
	v_mul_f32_e32 v17, 0xbfb8aa3b, v17
	v_exp_f32_e32 v17, v17
	v_and_b32_e32 v18, 0xffff0000, v20
	v_add_f32_e32 v17, 1.0, v17
	v_rcp_f32_e32 v17, v17
	s_nop 0
	v_mul_f32_e32 v77, v17, v18
	v_lshlrev_b32_e32 v17, 16, v16
	v_mul_f32_e32 v18, v63, v58
	v_add_f32_e32 v17, v4, v17
	v_pk_fma_f32 v[58:59], v[76:77], v[58:59], v[18:19] op_sel_hi:[1,1,0]
	v_lshlrev_b32_e32 v18, 16, v20
	v_cndmask_b32_e32 v20, 0, v221, vcc
	v_mul_f32_e32 v17, 0xbfb8aa3b, v17
	v_add_f32_e32 v20, v31, v20
	v_exp_f32_e32 v17, v17
	v_exp_f32_e32 v20, v20
	v_cndmask_b32_e32 v16, 0, v220, vcc
	v_add_f32_e32 v17, 1.0, v17
	v_ldexp_f32 v16, v20, v16
	v_rcp_f32_e32 v20, v17
	v_sqrt_f32_e32 v17, v51
	v_mul_f32_e32 v57, v20, v18
	v_mul_f32_e32 v18, v57, v17
	v_pk_fma_f32 v[56:57], v[56:57], v[16:17], v[18:19] op_sel_hi:[1,1,0]
	v_and_b32_e32 v16, 0xffff0000, v19
	v_add_f32_e32 v16, v15, v16
	v_mul_f32_e32 v16, 0xbfb8aa3b, v16
	v_exp_f32_e32 v16, v16
	v_and_b32_e32 v17, 0xffff0000, v23
	v_cvt_pk_bf16_f32 v18, v52, v46
	global_load_dwordx4 v[20:23], v[40:41], off offset:3584
	v_add_f32_e32 v16, 1.0, v16
	v_rcp_f32_e32 v16, v16
	s_nop 0
	v_mul_f32_e32 v51, v16, v17
	v_mul_f32_e32 v16, v51, v55
	v_pk_fma_f32 v[54:55], v[50:51], v[54:55], v[16:17] op_sel_hi:[1,1,0]
	v_cvt_pk_bf16_f32 v16, v56, v59
	v_cvt_pk_bf16_f32 v17, v44, v60
	v_cvt_pk_bf16_f32 v19, v42, v54
	global_store_dwordx4 v[24:25], v[16:19], off
	global_load_dwordx4 v[24:27], v[48:49], off offset:3584
	s_waitcnt vmcnt(0)
; __device__ __forceinline__ unsigned pk2(float lo, float hi) { f32x2_pk v = {lo, hi}; bf16x2_pk b = __builtin_convertvector(v, bf16x2_pk); return __builtin_bit_cast(unsigned, b); }
; __device__ __forceinline__ float sigmoidf_(float x) { return __builtin_amdgcn_rcpf(1.0f + __expf(-x)); }
; __device__ __forceinline__ void rg_unpack8(const u32x4 w, float* v) { v[0] = bflo(w.x); v[1] = bfhi(w.x); v[2] = bflo(w.y); v[3] = bfhi(w.y); v[4] = bflo(w.z); v[5] = bfhi(w.z); v[6] = bflo(w.w); v[7] = bfhi(w.w); }
; __device__ __forceinline__ void rg_ab(float ra, float ri, float x, float ba, float bx, float sp, float& a, float& b) {
;     const float r = sigmoidf_(ra + ba), ig = sigmoidf_(ri + bx); const float l2 = r * sp; a = exp2f(l2);
;     const float x2 = 1.3862943611198906f * l2;
;     const float om = x2 > -0.125f ? -x2 * (1.0f + x2 * (0.5f + x2 * (0.16666667f + x2 * (0.041666668f + x2 * 0.0083333338f)))) : 1.0f - __expf(x2);
;     b = __builtin_amdgcn_sqrtf(om) * (ig * x);
; }
; __device__ __forceinline__ void rg_scan2_phase(const bf16_t* RA0, bf16_t* RI0, const bf16_t* RA1, const bf16_t* RI1, const bf16_t* XCV, const float* bap, const float* bxp, const float* lamp, const float* CAR, bf16_t* Gb, int gtid, int ngt) {
;     ...
; #pragma unroll 4
;         for (int i = 0; i < 64; ++i) { const size_t off = (size_t)(row0 + i) * DRNN + 8 * cg;
;             float ra[8], ri[8], xv[8]; rg_unpack8(*(const u32x4*)(RA0 + off), ra); rg_unpack8(*(const u32x4*)(RI0 + off), ri); rg_unpack8(*(const u32x4*)(XCV + off), xv);
; #pragma unroll
;             for (int e = 0; e < 8; ++e) { float a, bb; rg_ab(ra[e], ri[e], xv[e], ba[e], bx[e], sp[e], a, bb); h[e] = a * h[e] + bb; }
;             u32x4 o; o.x = pk2(h[0], h[1]); o.y = pk2(h[2], h[3]); o.z = pk2(h[4], h[5]); o.w = pk2(h[6], h[7]); *(u32x4*)(RI0 + off) = o; }
	v_lshlrev_b32_e32 v31, 16, v24
	v_add_co_u32_e32 v16, vcc, 0x8a01000, v38
	v_add_f32_e32 v31, v0, v31
	s_nop 0
	v_addc_co_u32_e32 v17, vcc, 0, v39, vcc
	global_load_dwordx4 v[16:19], v[16:17], off offset:3584
	v_mul_f32_e32 v31, 0xbfb8aa3b, v31
	v_exp_f32_e32 v31, v31
	s_nop 0
	v_add_f32_e32 v31, 1.0, v31
	v_rcp_f32_e32 v31, v31
	s_nop 0
	v_mul_f32_e32 v31, v74, v31
	v_mul_f32_e32 v41, 0x3fb17218, v31
	v_mul_f32_e32 v92, 0x3fb8aa3b, v41
	v_exp_f32_e32 v92, v92
	v_fmamk_f32 v93, v41, 0x3c088889, v202
	v_fmaak_f32 v93, v41, v93, 0x3e2aaaab
	v_fma_f32 v93, v41, v93, 0.5
	v_fma_f32 v93, v41, v93, 1.0
	v_mul_f32_e64 v93, v93, -v41
	v_sub_f32_e32 v92, 1.0, v92
	v_cmp_nlt_f32_e32 vcc, s5, v41
	s_nop 1
	v_cndmask_b32_e32 v40, v93, v92, vcc
	v_and_b32_e32 v24, 0xffff0000, v24
	v_add_f32_e32 v24, v1, v24
	v_mul_f32_e32 v24, 0xbfb8aa3b, v24
	v_exp_f32_e32 v24, v24
	s_nop 0
	v_add_f32_e32 v24, 1.0, v24
	v_rcp_f32_e32 v24, v24
	s_nop 0
	v_mul_f32_e32 v24, v73, v24
	v_mul_f32_e32 v41, 0x3fb17218, v24
	v_mul_f32_e32 v92, 0x3fb8aa3b, v41
	v_exp_f32_e32 v92, v92
	v_fmamk_f32 v93, v41, 0x3c088889, v202
	v_fmaak_f32 v93, v41, v93, 0x3e2aaaab
	v_fma_f32 v93, v41, v93, 0.5
	v_fma_f32 v93, v41, v93, 1.0
	v_mul_f32_e64 v93, v93, -v41
	v_sub_f32_e32 v92, 1.0, v92
	v_cmp_nlt_f32_e32 vcc, s5, v41
	s_nop 1
	v_cndmask_b32_e32 v43, v93, v92, vcc
	v_lshlrev_b32_e32 v41, 16, v25
	v_add_f32_e32 v41, v2, v41
	v_mul_f32_e32 v41, 0xbfb8aa3b, v41
	v_exp_f32_e32 v41, v41
	s_nop 0
	v_add_f32_e32 v41, 1.0, v41
	v_rcp_f32_e32 v41, v41
	s_nop 0
	v_mul_f32_e32 v45, v71, v41
	v_mul_f32_e32 v41, 0x3fb17218, v45
	v_mul_f32_e32 v92, 0x3fb8aa3b, v41
	v_exp_f32_e32 v92, v92
	v_fmamk_f32 v93, v41, 0x3c088889, v202
	v_fmaak_f32 v93, v41, v93, 0x3e2aaaab
	v_fma_f32 v93, v41, v93, 0.5
	v_fma_f32 v93, v41, v93, 1.0
	v_mul_f32_e64 v93, v93, -v41
	v_sub_f32_e32 v92, 1.0, v92
	v_cmp_nlt_f32_e32 vcc, s5, v41
	s_nop 1
	v_cndmask_b32_e32 v47, v93, v92, vcc
	v_and_b32_e32 v25, 0xffff0000, v25
	v_add_f32_e32 v25, v3, v25
	v_mul_f32_e32 v25, 0xbfb8aa3b, v25
	v_exp_f32_e32 v25, v25
	s_nop 0
	v_add_f32_e32 v25, 1.0, v25
	v_rcp_f32_e32 v25, v25
	s_nop 0
	v_mul_f32_e32 v25, v70, v25
	v_mul_f32_e32 v41, 0x3fb17218, v25
	v_mul_f32_e32 v92, 0x3fb8aa3b, v41
	v_exp_f32_e32 v92, v92
	v_fmamk_f32 v93, v41, 0x3c088889, v202
	v_fmaak_f32 v93, v41, v93, 0x3e2aaaab
	v_fma_f32 v93, v41, v93, 0.5
	v_fma_f32 v93, v41, v93, 1.0
	v_mul_f32_e64 v93, v93, -v41
	v_sub_f32_e32 v92, 1.0, v92
	v_cmp_nlt_f32_e32 vcc, s5, v41
	s_nop 1
	v_cndmask_b32_e32 v48, v93, v92, vcc
	v_lshlrev_b32_e32 v41, 16, v26
	v_add_f32_e32 v41, v8, v41
	v_mul_f32_e32 v41, 0xbfb8aa3b, v41
	v_exp_f32_e32 v41, v41
	s_nop 0
	v_add_f32_e32 v41, 1.0, v41
	v_rcp_f32_e32 v41, v41
	s_nop 0
	v_mul_f32_e32 v49, v69, v41
	v_mul_f32_e32 v41, 0x3fb17218, v49
	v_mul_f32_e32 v92, 0x3fb8aa3b, v41
	v_exp_f32_e32 v92, v92
	v_fmamk_f32 v93, v41, 0x3c088889, v202
	v_fmaak_f32 v93, v41, v93, 0x3e2aaaab
	v_fma_f32 v93, v41, v93, 0.5
	v_fma_f32 v93, v41, v93, 1.0
	v_mul_f32_e64 v93, v93, -v41
	v_sub_f32_e32 v92, 1.0, v92
	v_cmp_nlt_f32_e32 vcc, s5, v41
	s_nop 1
	v_cndmask_b32_e32 v53, v93, v92, vcc
	v_and_b32_e32 v26, 0xffff0000, v26
	v_add_f32_e32 v26, v9, v26
	v_mul_f32_e32 v26, 0xbfb8aa3b, v26
	v_exp_f32_e32 v26, v26
	s_nop 0
	v_add_f32_e32 v26, 1.0, v26
	v_rcp_f32_e32 v26, v26
	s_nop 0
	v_mul_f32_e32 v26, v68, v26
	v_mul_f32_e32 v41, 0x3fb17218, v26
	v_mul_f32_e32 v92, 0x3fb8aa3b, v41
	v_exp_f32_e32 v92, v92
	v_fmamk_f32 v93, v41, 0x3c088889, v202
	v_fmaak_f32 v93, v41, v93, 0x3e2aaaab
	v_fma_f32 v93, v41, v93, 0.5
	v_fma_f32 v93, v41, v93, 1.0
	v_mul_f32_e64 v93, v93, -v41
	v_sub_f32_e32 v92, 1.0, v92
	v_cmp_nlt_f32_e32 vcc, s5, v41
	s_nop 1
	v_cndmask_b32_e32 v55, v93, v92, vcc
	v_lshlrev_b32_e32 v41, 16, v27
	v_add_f32_e32 v41, v10, v41
	v_mul_f32_e32 v41, 0xbfb8aa3b, v41
	v_exp_f32_e32 v41, v41
	s_nop 0
	v_add_f32_e32 v41, 1.0, v41
	v_rcp_f32_e32 v41, v41
	s_nop 0
	v_mul_f32_e32 v58, v67, v41
	v_mul_f32_e32 v41, 0x3fb17218, v58
	v_mul_f32_e32 v92, 0x3fb8aa3b, v41
	v_exp_f32_e32 v92, v92
	v_fmamk_f32 v93, v41, 0x3c088889, v202
	v_fmaak_f32 v93, v41, v93, 0x3e2aaaab
	v_fma_f32 v93, v41, v93, 0.5
	v_fma_f32 v93, v41, v93, 1.0
	v_mul_f32_e64 v93, v93, -v41
	v_sub_f32_e32 v92, 1.0, v92
	v_cmp_nlt_f32_e32 vcc, s5, v41
	s_nop 1
	v_cndmask_b32_e32 v62, v93, v92, vcc
	v_and_b32_e32 v27, 0xffff0000, v27
	v_add_f32_e32 v27, v11, v27
	v_mul_f32_e32 v27, 0xbfb8aa3b, v27
	v_exp_f32_e32 v27, v27
	s_nop 0
	v_add_f32_e32 v27, 1.0, v27
	v_rcp_f32_e32 v27, v27
	s_nop 0
	v_mul_f32_e32 v27, v75, v27
	v_mul_f32_e32 v41, 0x3fb17218, v27
	v_cmp_nlt_f32_e32 vcc, s5, v41
	s_and_saveexec_b64 s[2:3], vcc
	s_xor_b64 s[24:25], exec, s[2:3]
	v_mul_f32_e32 v41, 0x3fb8aa3b, v41
	v_exp_f32_e32 v41, v41
	s_nop 0
	v_sub_f32_e32 v63, 1.0, v41
	s_andn2_saveexec_b64 s[24:25], s[24:25]
	s_cbranch_execz .LBB0_1250
	v_fmamk_f32 v50, v41, 0x3c088889, v202
	v_fmaak_f32 v50, v41, v50, 0x3e2aaaab
	v_fma_f32 v50, v41, v50, 0.5
	v_fma_f32 v50, v41, v50, 1.0
	v_mul_f32_e64 v63, v50, -v41
	s_branch .LBB0_1250

; __device__ __forceinline__ unsigned pk2(float lo, float hi) { f32x2_pk v = {lo, hi}; bf16x2_pk b = __builtin_convertvector(v, bf16x2_pk); return __builtin_bit_cast(unsigned, b); }
; __device__ __forceinline__ float sigmoidf_(float x) { return __builtin_amdgcn_rcpf(1.0f + __expf(-x)); }
; __device__ __forceinline__ void rg_unpack8(const u32x4 w, float* v) { v[0] = bflo(w.x); v[1] = bfhi(w.x); v[2] = bflo(w.y); v[3] = bfhi(w.y); v[4] = bflo(w.z); v[5] = bfhi(w.z); v[6] = bflo(w.w); v[7] = bfhi(w.w); }
; __device__ __forceinline__ void rg_ab(float ra, float ri, float x, float ba, float bx, float sp, float& a, float& b) {
;     const float r = sigmoidf_(ra + ba), ig = sigmoidf_(ri + bx); const float l2 = r * sp; a = exp2f(l2);
;     const float x2 = 1.3862943611198906f * l2;
;     const float om = x2 > -0.125f ? -x2 * (1.0f + x2 * (0.5f + x2 * (0.16666667f + x2 * (0.041666668f + x2 * 0.0083333338f)))) : 1.0f - __expf(x2);
;     b = __builtin_amdgcn_sqrtf(om) * (ig * x);
; }
; __device__ __forceinline__ void rg_scan2_phase(const bf16_t* RA0, bf16_t* RI0, const bf16_t* RA1, const bf16_t* RI1, const bf16_t* XCV, const float* bap, const float* bxp, const float* lamp, const float* CAR, bf16_t* Gb, int gtid, int ngt) {
;     ...
; #pragma unroll 4
;         for (int i = 63; i >= 0; --i) { const size_t off = (size_t)(row0 + i) * DRNN + 8 * cg;
;             float ra[8], ri[8], xv[8], hf[8], gv[8]; rg_unpack8(*(const u32x4*)(RA1 + off), ra); rg_unpack8(*(const u32x4*)(RI1 + off), ri); rg_unpack8(*(const u32x4*)(XCV + off), xv);
;             rg_unpack8(*(const u32x4*)(RI0 + off), hf); rg_unpack8(*(const u32x4*)(Gb + off), gv);
; #pragma unroll
;             for (int e = 0; e < 8; ++e) { float a, bb; rg_ab(ra[e], ri[e], xv[e], ba[e], bx[e], sp[e], a, bb); h[e] = a * h[e] + bb; gv[e] *= hf[e] + h[e]; }
;             u32x4 o; o.x = pk2(gv[0], gv[1]); o.y = pk2(gv[2], gv[3]); o.z = pk2(gv[4], gv[5]); o.w = pk2(gv[6], gv[7]); *(u32x4*)(Gb + off) = o; }
.LBB0_1417:
	v_lshl_add_u64 v[42:43], v[38:39], 0, v[36:37]
	v_add_co_u32_e32 v16, vcc, 0x19827000, v42
	v_lshl_add_u64 v[44:45], v[40:41], 0, v[36:37]
	s_nop 0
	v_addc_co_u32_e32 v17, vcc, 0, v43, vcc
	global_load_dwordx4 v[32:35], v[16:17], off offset:1536
	v_add_co_u32_e32 v16, vcc, 0x27000, v44
	s_waitcnt vmcnt(0)
	v_lshlrev_b32_e32 v47, 16, v32
	v_addc_co_u32_e32 v17, vcc, 0, v45, vcc
	v_add_co_u32_e32 v20, vcc, 0x8a27000, v42
	global_load_dwordx4 v[16:19], v[16:17], off offset:1536
	s_nop 0
	v_addc_co_u32_e32 v21, vcc, 0, v43, vcc
	v_add_co_u32_e32 v22, vcc, 0x13e27000, v42
	v_add_f32_e32 v47, v0, v47
	s_nop 0
	v_addc_co_u32_e32 v23, vcc, 0, v43, vcc
	v_add_co_u32_e32 v28, vcc, 0x3027000, v42
	global_load_dwordx4 v[24:27], v[20:21], off offset:1536
	s_nop 0
	global_load_dwordx4 v[20:23], v[22:23], off offset:1536
	v_addc_co_u32_e32 v29, vcc, 0, v43, vcc
	global_load_dwordx4 v[28:31], v[28:29], off offset:1536
	v_mul_f32_e32 v47, 0xbfb8aa3b, v47
	v_exp_f32_e32 v47, v47
	s_nop 0
	v_add_f32_e32 v47, 1.0, v47
	v_rcp_f32_e32 v47, v47
	s_nop 0
	v_mul_f32_e32 v47, v79, v47
	v_mul_f32_e32 v49, 0x3fb17218, v47
	v_mul_f32_e32 v92, 0x3fb8aa3b, v49
	v_exp_f32_e32 v92, v92
	v_fmamk_f32 v93, v49, 0x3c088889, v202
	v_fmaak_f32 v93, v49, v93, 0x3e2aaaab
	v_fma_f32 v93, v49, v93, 0.5
	v_fma_f32 v93, v49, v93, 1.0
	v_mul_f32_e64 v93, v93, -v49
	v_sub_f32_e32 v92, 1.0, v92
	v_cmp_nlt_f32_e32 vcc, s5, v49
	s_nop 1
	v_cndmask_b32_e32 v51, v93, v92, vcc
	v_and_b32_e32 v32, 0xffff0000, v32
	v_add_f32_e32 v32, v1, v32
	v_mul_f32_e32 v32, 0xbfb8aa3b, v32
	v_exp_f32_e32 v32, v32
	s_nop 0
	v_add_f32_e32 v32, 1.0, v32
	v_rcp_f32_e32 v32, v32
	s_nop 0
	v_mul_f32_e32 v53, v78, v32
	v_mul_f32_e32 v49, 0x3fb17218, v53
	v_mul_f32_e32 v92, 0x3fb8aa3b, v49
	v_exp_f32_e32 v92, v92
	v_fmamk_f32 v93, v49, 0x3c088889, v202
	v_fmaak_f32 v93, v49, v93, 0x3e2aaaab
	v_fma_f32 v93, v49, v93, 0.5
	v_fma_f32 v93, v49, v93, 1.0
	v_mul_f32_e64 v93, v93, -v49
	v_sub_f32_e32 v92, 1.0, v92
	v_cmp_nlt_f32_e32 vcc, s5, v49
	s_nop 1
	v_cndmask_b32_e32 v32, v93, v92, vcc
	v_lshlrev_b32_e32 v49, 16, v33
	v_add_f32_e32 v49, v2, v49
	v_mul_f32_e32 v49, 0xbfb8aa3b, v49
	v_exp_f32_e32 v49, v49
	s_nop 0
	v_add_f32_e32 v49, 1.0, v49
	v_rcp_f32_e32 v49, v49
	s_nop 0
	v_mul_f32_e32 v57, v77, v49
	v_mul_f32_e32 v55, 0x3fb17218, v57
	v_mul_f32_e32 v92, 0x3fb8aa3b, v55
	v_exp_f32_e32 v92, v92
	v_fmamk_f32 v93, v55, 0x3c088889, v202
	v_fmaak_f32 v93, v55, v93, 0x3e2aaaab
	v_fma_f32 v93, v55, v93, 0.5
	v_fma_f32 v93, v55, v93, 1.0
	v_mul_f32_e64 v93, v93, -v55
	v_sub_f32_e32 v92, 1.0, v92
	v_cmp_nlt_f32_e32 vcc, s5, v55
	s_nop 1
	v_cndmask_b32_e32 v49, v93, v92, vcc
	v_and_b32_e32 v33, 0xffff0000, v33
	v_add_f32_e32 v33, v3, v33
	v_mul_f32_e32 v33, 0xbfb8aa3b, v33
	v_exp_f32_e32 v33, v33
	s_nop 0
	v_add_f32_e32 v33, 1.0, v33
	v_rcp_f32_e32 v33, v33
	s_nop 0
	v_mul_f32_e32 v66, v76, v33
	v_mul_f32_e32 v55, 0x3fb17218, v66
	v_mul_f32_e32 v92, 0x3fb8aa3b, v55
	v_exp_f32_e32 v92, v92
	v_fmamk_f32 v93, v55, 0x3c088889, v202
	v_fmaak_f32 v93, v55, v93, 0x3e2aaaab
	v_fma_f32 v93, v55, v93, 0.5
	v_fma_f32 v93, v55, v93, 1.0
	v_mul_f32_e64 v93, v93, -v55
	v_sub_f32_e32 v92, 1.0, v92
	v_cmp_nlt_f32_e32 vcc, s5, v55
	s_nop 1
	v_cndmask_b32_e32 v33, v93, v92, vcc
	v_lshlrev_b32_e32 v55, 16, v34
	v_add_f32_e32 v55, v8, v55
	v_mul_f32_e32 v55, 0xbfb8aa3b, v55
	v_exp_f32_e32 v55, v55
	s_nop 0
	v_add_f32_e32 v55, 1.0, v55
	v_rcp_f32_e32 v55, v55
	s_nop 0
	v_mul_f32_e32 v61, v75, v55
	v_mul_f32_e32 v59, 0x3fb17218, v61
	v_mul_f32_e32 v92, 0x3fb8aa3b, v59
	v_exp_f32_e32 v92, v92
	v_fmamk_f32 v93, v59, 0x3c088889, v202
	v_fmaak_f32 v93, v59, v93, 0x3e2aaaab
	v_fma_f32 v93, v59, v93, 0.5
	v_fma_f32 v93, v59, v93, 1.0
	v_mul_f32_e64 v93, v93, -v59
	v_sub_f32_e32 v92, 1.0, v92
	v_cmp_nlt_f32_e32 vcc, s5, v59
	s_nop 1
	v_cndmask_b32_e32 v55, v93, v92, vcc
	v_and_b32_e32 v34, 0xffff0000, v34
	v_add_f32_e32 v34, v9, v34
	v_mul_f32_e32 v34, 0xbfb8aa3b, v34
	v_exp_f32_e32 v34, v34
	s_nop 0
	v_add_f32_e32 v34, 1.0, v34
	v_rcp_f32_e32 v34, v34
	s_nop 0
	v_mul_f32_e32 v68, v74, v34
	v_mul_f32_e32 v34, 0x3fb17218, v68
	v_mul_f32_e32 v92, 0x3fb8aa3b, v34
	v_exp_f32_e32 v92, v92
	v_fmamk_f32 v93, v34, 0x3c088889, v202
	v_fmaak_f32 v93, v34, v93, 0x3e2aaaab
	v_fma_f32 v93, v34, v93, 0.5
	v_fma_f32 v93, v34, v93, 1.0
	v_mul_f32_e64 v93, v93, -v34
	v_sub_f32_e32 v92, 1.0, v92
	v_cmp_nlt_f32_e32 vcc, s5, v34
	s_nop 1
	v_cndmask_b32_e32 v67, v93, v92, vcc
	v_lshlrev_b32_e32 v34, 16, v35
	v_add_f32_e32 v34, v10, v34
	v_mul_f32_e32 v34, 0xbfb8aa3b, v34
	v_exp_f32_e32 v34, v34
	s_nop 0
	v_add_f32_e32 v34, 1.0, v34
	v_rcp_f32_e32 v34, v34
	s_nop 0
	v_mul_f32_e32 v62, v73, v34
	v_mul_f32_e32 v34, 0x3fb17218, v62
	v_mul_f32_e32 v92, 0x3fb8aa3b, v34
	v_exp_f32_e32 v92, v92
	v_fmamk_f32 v93, v34, 0x3c088889, v202
	v_fmaak_f32 v93, v34, v93, 0x3e2aaaab
	v_fma_f32 v93, v34, v93, 0.5
	v_fma_f32 v93, v34, v93, 1.0
	v_mul_f32_e64 v93, v93, -v34
	v_sub_f32_e32 v92, 1.0, v92
	v_cmp_nlt_f32_e32 vcc, s5, v34
	s_nop 1
	v_cndmask_b32_e32 v59, v93, v92, vcc
	v_and_b32_e32 v34, 0xffff0000, v35
	v_add_f32_e32 v34, v11, v34
	v_mul_f32_e32 v34, 0xbfb8aa3b, v34
	v_exp_f32_e32 v34, v34
	s_nop 0
	v_add_f32_e32 v34, 1.0, v34
	v_rcp_f32_e32 v34, v34
	s_nop 0
	v_mul_f32_e32 v35, v80, v34
	v_mul_f32_e32 v63, 0x3fb17218, v35
	v_mul_f32_e32 v92, 0x3fb8aa3b, v63
	v_exp_f32_e32 v92, v92
	v_fmamk_f32 v93, v63, 0x3c088889, v202
	v_fmaak_f32 v93, v63, v93, 0x3e2aaaab
	v_fma_f32 v93, v63, v93, 0.5
	v_fma_f32 v93, v63, v93, 1.0
	v_mul_f32_e64 v93, v93, -v63
	v_sub_f32_e32 v92, 1.0, v92
	v_cmp_nlt_f32_e32 vcc, s5, v63
	s_nop 1
	v_cndmask_b32_e32 v34, v93, v92, vcc
	v_cmp_gt_f32_e32 vcc, s82, v62
	s_waitcnt vmcnt(2)
; __device__ __forceinline__ unsigned pk2(float lo, float hi) { f32x2_pk v = {lo, hi}; bf16x2_pk b = __builtin_convertvector(v, bf16x2_pk); return __builtin_bit_cast(unsigned, b); }
; __device__ __forceinline__ float sigmoidf_(float x) { return __builtin_amdgcn_rcpf(1.0f + __expf(-x)); }
; __device__ __forceinline__ void rg_unpack8(const u32x4 w, float* v) { v[0] = bflo(w.x); v[1] = bfhi(w.x); v[2] = bflo(w.y); v[3] = bfhi(w.y); v[4] = bflo(w.z); v[5] = bfhi(w.z); v[6] = bflo(w.w); v[7] = bfhi(w.w); }
; __device__ __forceinline__ void rg_ab(float ra, float ri, float x, float ba, float bx, float sp, float& a, float& b) {
;     const float r = sigmoidf_(ra + ba), ig = sigmoidf_(ri + bx); const float l2 = r * sp; a = exp2f(l2);
;     const float x2 = 1.3862943611198906f * l2;
;     const float om = x2 > -0.125f ? -x2 * (1.0f + x2 * (0.5f + x2 * (0.16666667f + x2 * (0.041666668f + x2 * 0.0083333338f)))) : 1.0f - __expf(x2);
;     b = __builtin_amdgcn_sqrtf(om) * (ig * x);
; }
; __device__ __forceinline__ void rg_scan2_phase(const bf16_t* RA0, bf16_t* RI0, const bf16_t* RA1, const bf16_t* RI1, const bf16_t* XCV, const float* bap, const float* bxp, const float* lamp, const float* CAR, bf16_t* Gb, int gtid, int ngt) {
;     ...
; #pragma unroll 4
;         for (int i = 63; i >= 0; --i) { const size_t off = (size_t)(row0 + i) * DRNN + 8 * cg;
;             float ra[8], ri[8], xv[8], hf[8], gv[8]; rg_unpack8(*(const u32x4*)(RA1 + off), ra); rg_unpack8(*(const u32x4*)(RI1 + off), ri); rg_unpack8(*(const u32x4*)(XCV + off), xv);
;             rg_unpack8(*(const u32x4*)(RI0 + off), hf); rg_unpack8(*(const u32x4*)(Gb + off), gv);
; #pragma unroll
;             for (int e = 0; e < 8; ++e) { float a, bb; rg_ab(ra[e], ri[e], xv[e], ba[e], bx[e], sp[e], a, bb); h[e] = a * h[e] + bb; gv[e] *= hf[e] + h[e]; }
;             u32x4 o; o.x = pk2(gv[0], gv[1]); o.y = pk2(gv[2], gv[3]); o.z = pk2(gv[4], gv[5]); o.w = pk2(gv[6], gv[7]); *(u32x4*)(Gb + off) = o; }
	v_lshlrev_b32_e32 v65, 16, v27
	s_waitcnt vmcnt(1)
	v_lshlrev_b32_e32 v69, 16, v23
	v_cndmask_b32_e32 v64, 0, v221, vcc
	v_add_f32_e32 v62, v62, v64
	v_lshlrev_b32_e32 v64, 16, v19
	v_add_f32_e32 v64, v14, v64
	v_mul_f32_e32 v64, 0xbfb8aa3b, v64
	v_exp_f32_e32 v62, v62
	v_exp_f32_e32 v64, v64
	v_cndmask_b32_e32 v63, 0, v220, vcc
	s_waitcnt vmcnt(0)
	v_lshlrev_b32_e32 v81, 16, v31
	v_ldexp_f32 v62, v62, v63
	v_add_f32_e32 v63, 1.0, v64
	v_rcp_f32_e32 v64, v63
	v_sqrt_f32_e32 v63, v59
	v_cmp_gt_f32_e32 vcc, s82, v35
	s_mov_b64 s[2:3], 0x3027600
	v_mul_f32_e32 v59, v64, v65
	v_mul_f32_e32 v64, v59, v63
	v_pk_fma_f32 v[64:65], v[58:59], v[62:63], v[64:65] op_sel_hi:[1,1,0]
	v_cndmask_b32_e32 v59, 0, v221, vcc
	v_add_f32_e32 v58, v64, v69
	v_mul_f32_e32 v65, v58, v81
	v_cndmask_b32_e32 v58, 0, v220, vcc
	v_cmp_gt_f32_e32 vcc, s82, v61
	v_add_f32_e32 v35, v35, v59
	v_exp_f32_e32 v35, v35
	v_cndmask_b32_e32 v62, 0, v221, vcc
	v_add_f32_e32 v61, v61, v62
	v_lshlrev_b32_e32 v62, 16, v18
	v_add_f32_e32 v62, v12, v62
	v_mul_f32_e32 v62, 0xbfb8aa3b, v62
	v_exp_f32_e32 v61, v61
	v_exp_f32_e32 v62, v62
	v_cndmask_b32_e32 v59, 0, v220, vcc
	v_ldexp_f32 v82, v35, v58
	v_ldexp_f32 v58, v61, v59
	v_add_f32_e32 v59, 1.0, v62
	v_rcp_f32_e32 v61, v59
	v_sqrt_f32_e32 v59, v55
	v_lshlrev_b32_e32 v35, 16, v26
	v_and_b32_e32 v18, 0xffff0000, v18
	v_mul_f32_e32 v55, v61, v35
	v_add_f32_e32 v18, v13, v18
	v_mul_f32_e32 v62, v55, v59
	v_cmp_gt_f32_e32 vcc, s82, v68
	v_mul_f32_e32 v18, 0xbfb8aa3b, v18
	v_pk_fma_f32 v[62:63], v[54:55], v[58:59], v[62:63] op_sel_hi:[1,1,0]
	v_cndmask_b32_e32 v55, 0, v221, vcc
	v_exp_f32_e32 v18, v18
	v_add_f32_e32 v55, v68, v55
	v_exp_f32_e32 v55, v55
	v_cndmask_b32_e32 v54, 0, v220, vcc
	v_add_f32_e32 v18, 1.0, v18
	v_rcp_f32_e32 v18, v18
	v_ldexp_f32 v54, v55, v54
	v_sqrt_f32_e32 v55, v67
	v_and_b32_e32 v26, 0xffff0000, v26
	v_mul_f32_e32 v61, v18, v26
	v_cmp_gt_f32_e32 vcc, s82, v57
	v_mul_f32_e32 v18, v61, v55
	v_pk_fma_f32 v[60:61], v[60:61], v[54:55], v[18:19] op_sel_hi:[1,1,0]
	v_lshlrev_b32_e32 v54, 16, v17
	v_cndmask_b32_e32 v26, 0, v221, vcc
	v_add_f32_e32 v54, v6, v54
	v_add_f32_e32 v26, v57, v26
	v_mul_f32_e32 v54, 0xbfb8aa3b, v54
	v_exp_f32_e32 v26, v26
	v_exp_f32_e32 v55, v54
	v_lshlrev_b32_e32 v69, 16, v22
	v_and_b32_e32 v22, 0xffff0000, v22
	v_add_f32_e32 v18, v60, v22
	v_cndmask_b32_e32 v22, 0, v220, vcc
	v_ldexp_f32 v54, v26, v22
	v_add_f32_e32 v22, 1.0, v55
	v_rcp_f32_e32 v22, v22
	v_and_b32_e32 v17, 0xffff0000, v17
	v_sqrt_f32_e32 v55, v49
	v_add_f32_e32 v17, v7, v17
	v_lshlrev_b32_e32 v81, 16, v30
	v_and_b32_e32 v30, 0xffff0000, v30
	v_mul_f32_e32 v17, 0xbfb8aa3b, v17
	v_mul_f32_e32 v30, v18, v30
	v_lshlrev_b32_e32 v18, 16, v25
	v_exp_f32_e32 v17, v17
	v_mul_f32_e32 v49, v22, v18
	v_mul_f32_e32 v18, v49, v55
	v_lshlrev_b32_e32 v26, 16, v21
	v_pk_fma_f32 v[58:59], v[48:49], v[54:55], v[18:19] op_sel_hi:[1,1,0]
	v_cmp_gt_f32_e32 vcc, s82, v66
	v_add_f32_e32 v18, v58, v26
	v_add_f32_e32 v17, 1.0, v17
	v_cndmask_b32_e32 v26, 0, v221, vcc
	v_add_f32_e32 v26, v66, v26
	v_rcp_f32_e32 v17, v17
	v_exp_f32_e32 v26, v26
	v_sqrt_f32_e32 v49, v33
	v_lshlrev_b32_e32 v57, 16, v29
	v_mul_f32_e32 v59, v18, v57
	v_and_b32_e32 v18, 0xffff0000, v25
	v_cndmask_b32_e32 v22, 0, v220, vcc
	v_mul_f32_e32 v57, v17, v18
	v_ldexp_f32 v48, v26, v22
	v_mul_f32_e32 v18, v57, v49
	v_and_b32_e32 v21, 0xffff0000, v21
	v_pk_fma_f32 v[56:57], v[56:57], v[48:49], v[18:19] op_sel_hi:[1,1,0]
	v_and_b32_e32 v22, 0xffff0000, v29
	v_add_f32_e32 v17, v56, v21
	v_mul_f32_e32 v21, v17, v22
	v_lshlrev_b32_e32 v17, 16, v16
	v_add_f32_e32 v17, v4, v17
	v_mul_f32_e32 v17, 0xbfb8aa3b, v17
	v_exp_f32_e32 v17, v17
	v_cmp_gt_f32_e32 vcc, s82, v47
	v_sqrt_f32_e32 v49, v51
	v_lshlrev_b32_e32 v18, 16, v24
	v_cndmask_b32_e32 v26, 0, v221, vcc
	v_add_f32_e32 v17, 1.0, v17
	v_add_f32_e32 v26, v47, v26
	v_rcp_f32_e32 v17, v17
	v_exp_f32_e32 v26, v26
	v_cndmask_b32_e32 v25, 0, v220, vcc
	v_and_b32_e32 v16, 0xffff0000, v16
	v_mul_f32_e32 v47, v17, v18
	v_ldexp_f32 v48, v26, v25
	v_mul_f32_e32 v18, v47, v49
	v_lshlrev_b32_e32 v22, 16, v20
	v_pk_fma_f32 v[54:55], v[46:47], v[48:49], v[18:19] op_sel_hi:[1,1,0]
	v_cmp_gt_f32_e32 vcc, s82, v53
	v_add_f32_e32 v16, v5, v16
	v_add_f32_e32 v17, v54, v22
	v_cndmask_b32_e32 v22, 0, v221, vcc
	v_mul_f32_e32 v16, 0xbfb8aa3b, v16
	v_add_f32_e32 v22, v53, v22
	v_exp_f32_e32 v25, v16
	v_exp_f32_e32 v22, v22
	v_lshlrev_b32_e32 v29, 16, v28
	v_cndmask_b32_e32 v18, 0, v220, vcc
	v_mul_f32_e32 v26, v17, v29
	v_add_f32_e32 v17, 1.0, v25
	v_ldexp_f32 v16, v22, v18
	v_rcp_f32_e32 v22, v17
	v_sqrt_f32_e32 v17, v32
	v_and_b32_e32 v18, 0xffff0000, v24
	v_lshl_add_u64 v[70:71], v[42:43], 0, s[2:3]
	v_mul_f32_e32 v53, v22, v18
	v_mul_f32_e32 v18, v53, v17
	v_pk_fma_f32 v[52:53], v[52:53], v[16:17], v[18:19] op_sel_hi:[1,1,0]
	v_and_b32_e32 v16, 0xffff0000, v19
	v_add_f32_e32 v16, v15, v16
	v_mul_f32_e32 v16, 0xbfb8aa3b, v16
	v_exp_f32_e32 v16, v16
	s_mov_b32 s2, 0x19826000
	v_add_f32_e32 v35, v62, v69
	v_add_co_u32_e32 v48, vcc, s2, v42
	v_add_f32_e32 v16, 1.0, v16
	v_rcp_f32_e32 v16, v16
	v_mul_f32_e32 v35, v35, v81
	v_and_b32_e32 v18, 0xffff0000, v27
	v_addc_co_u32_e32 v49, vcc, 0, v43, vcc
	v_sqrt_f32_e32 v83, v34
	v_mul_f32_e32 v51, v16, v18
	v_cvt_pk_bf16_f32 v18, v35, v30
	global_load_dwordx4 v[32:35], v[48:49], off offset:3072
	s_mov_b32 s2, 0x26000
	v_and_b32_e32 v20, 0xffff0000, v20
	v_add_co_u32_e32 v46, vcc, s2, v44
	v_and_b32_e32 v24, 0xffff0000, v28
	v_add_f32_e32 v17, v52, v20
	v_addc_co_u32_e32 v47, vcc, 0, v45, vcc
	s_mov_b32 s2, 0x8a26000
	v_mul_f32_e32 v17, v17, v24
	v_mul_f32_e32 v16, v51, v83
	v_add_co_u32_e32 v66, vcc, s2, v42
	v_and_b32_e32 v19, 0xffff0000, v23
	v_pk_fma_f32 v[50:51], v[50:51], v[82:83], v[16:17] op_sel_hi:[1,1,0]
	v_addc_co_u32_e32 v67, vcc, 0, v43, vcc
	s_mov_b32 s2, 0x13e26000
	v_and_b32_e32 v20, 0xffff0000, v31
	v_add_f32_e32 v16, v50, v19
	v_add_co_u32_e32 v68, vcc, s2, v42
	v_mul_f32_e32 v19, v16, v20
	s_nop 0
	v_addc_co_u32_e32 v69, vcc, 0, v43, vcc
	v_cvt_pk_bf16_f32 v16, v26, v17
	v_cvt_pk_bf16_f32 v17, v59, v21
	v_cvt_pk_bf16_f32 v19, v65, v19
	v_add_co_u32_e32 v28, vcc, 0x3026000, v42
	global_store_dwordx4 v[70:71], v[16:19], off
	s_nop 0
	v_addc_co_u32_e32 v29, vcc, 0, v43, vcc
	global_load_dwordx4 v[16:19], v[46:47], off offset:3072
	global_load_dwordx4 v[24:27], v[66:67], off offset:3072
	global_load_dwordx4 v[20:23], v[68:69], off offset:3072
	s_waitcnt vmcnt(4)
; __device__ __forceinline__ unsigned pk2(float lo, float hi) { f32x2_pk v = {lo, hi}; bf16x2_pk b = __builtin_convertvector(v, bf16x2_pk); return __builtin_bit_cast(unsigned, b); }
; __device__ __forceinline__ float sigmoidf_(float x) { return __builtin_amdgcn_rcpf(1.0f + __expf(-x)); }
; __device__ __forceinline__ void rg_unpack8(const u32x4 w, float* v) { v[0] = bflo(w.x); v[1] = bfhi(w.x); v[2] = bflo(w.y); v[3] = bfhi(w.y); v[4] = bflo(w.z); v[5] = bfhi(w.z); v[6] = bflo(w.w); v[7] = bfhi(w.w); }
; __device__ __forceinline__ void rg_ab(float ra, float ri, float x, float ba, float bx, float sp, float& a, float& b) {
;     const float r = sigmoidf_(ra + ba), ig = sigmoidf_(ri + bx); const float l2 = r * sp; a = exp2f(l2);
;     const float x2 = 1.3862943611198906f * l2;
;     const float om = x2 > -0.125f ? -x2 * (1.0f + x2 * (0.5f + x2 * (0.16666667f + x2 * (0.041666668f + x2 * 0.0083333338f)))) : 1.0f - __expf(x2);
;     b = __builtin_amdgcn_sqrtf(om) * (ig * x);
; }
; __device__ __forceinline__ void rg_scan2_phase(const bf16_t* RA0, bf16_t* RI0, const bf16_t* RA1, const bf16_t* RI1, const bf16_t* XCV, const float* bap, const float* bxp, const float* lamp, const float* CAR, bf16_t* Gb, int gtid, int ngt) {
;     ...
; #pragma unroll 4
;         for (int i = 63; i >= 0; --i) { const size_t off = (size_t)(row0 + i) * DRNN + 8 * cg;
;             float ra[8], ri[8], xv[8], hf[8], gv[8]; rg_unpack8(*(const u32x4*)(RA1 + off), ra); rg_unpack8(*(const u32x4*)(RI1 + off), ri); rg_unpack8(*(const u32x4*)(XCV + off), xv);
;             rg_unpack8(*(const u32x4*)(RI0 + off), hf); rg_unpack8(*(const u32x4*)(Gb + off), gv);
; #pragma unroll
;             for (int e = 0; e < 8; ++e) { float a, bb; rg_ab(ra[e], ri[e], xv[e], ba[e], bx[e], sp[e], a, bb); h[e] = a * h[e] + bb; gv[e] *= hf[e] + h[e]; }
;             u32x4 o; o.x = pk2(gv[0], gv[1]); o.y = pk2(gv[2], gv[3]); o.z = pk2(gv[4], gv[5]); o.w = pk2(gv[6], gv[7]); *(u32x4*)(Gb + off) = o; }
	v_lshlrev_b32_e32 v51, 16, v32
	global_load_dwordx4 v[28:31], v[28:29], off offset:3072
	v_add_f32_e32 v51, v0, v51
	v_mul_f32_e32 v51, 0xbfb8aa3b, v51
	v_exp_f32_e32 v51, v51
	s_nop 0
	v_add_f32_e32 v51, 1.0, v51
	v_rcp_f32_e32 v51, v51
	s_nop 0
	v_mul_f32_e32 v51, v79, v51
	v_mul_f32_e32 v55, 0x3fb17218, v51
	v_mul_f32_e32 v92, 0x3fb8aa3b, v55
	v_exp_f32_e32 v92, v92
	v_fmamk_f32 v93, v55, 0x3c088889, v202
	v_fmaak_f32 v93, v55, v93, 0x3e2aaaab
	v_fma_f32 v93, v55, v93, 0.5
	v_fma_f32 v93, v55, v93, 1.0
	v_mul_f32_e64 v93, v93, -v55
	v_sub_f32_e32 v92, 1.0, v92
	v_cmp_nlt_f32_e32 vcc, s5, v55
	s_nop 1
	v_cndmask_b32_e32 v53, v93, v92, vcc
	v_and_b32_e32 v32, 0xffff0000, v32
	v_add_f32_e32 v32, v1, v32
	v_mul_f32_e32 v32, 0xbfb8aa3b, v32
	v_exp_f32_e32 v32, v32
	s_nop 0
	v_add_f32_e32 v32, 1.0, v32
	v_rcp_f32_e32 v32, v32
	s_nop 0
	v_mul_f32_e32 v81, v78, v32
	v_mul_f32_e32 v55, 0x3fb17218, v81
	v_mul_f32_e32 v92, 0x3fb8aa3b, v55
	v_exp_f32_e32 v92, v92
	v_fmamk_f32 v93, v55, 0x3c088889, v202
	v_fmaak_f32 v93, v55, v93, 0x3e2aaaab
	v_fma_f32 v93, v55, v93, 0.5
	v_fma_f32 v93, v55, v93, 1.0
	v_mul_f32_e64 v93, v93, -v55
	v_sub_f32_e32 v92, 1.0, v92
	v_cmp_nlt_f32_e32 vcc, s5, v55
	s_nop 1
	v_cndmask_b32_e32 v32, v93, v92, vcc
	v_lshlrev_b32_e32 v55, 16, v33
	v_add_f32_e32 v55, v2, v55
	v_mul_f32_e32 v55, 0xbfb8aa3b, v55
	v_exp_f32_e32 v55, v55
	s_nop 0
	v_add_f32_e32 v55, 1.0, v55
	v_rcp_f32_e32 v55, v55
	s_nop 0
	v_mul_f32_e32 v57, v77, v55
	v_mul_f32_e32 v59, 0x3fb17218, v57
	v_mul_f32_e32 v92, 0x3fb8aa3b, v59
	v_exp_f32_e32 v92, v92
	v_fmamk_f32 v93, v59, 0x3c088889, v202
	v_fmaak_f32 v93, v59, v93, 0x3e2aaaab
	v_fma_f32 v93, v59, v93, 0.5
	v_fma_f32 v93, v59, v93, 1.0
	v_mul_f32_e64 v93, v93, -v59
	v_sub_f32_e32 v92, 1.0, v92
	v_cmp_nlt_f32_e32 vcc, s5, v59
	s_nop 1
	v_cndmask_b32_e32 v55, v93, v92, vcc
	v_and_b32_e32 v33, 0xffff0000, v33
	v_add_f32_e32 v33, v3, v33
	v_mul_f32_e32 v33, 0xbfb8aa3b, v33
	v_exp_f32_e32 v33, v33
	s_nop 0
	v_add_f32_e32 v33, 1.0, v33
	v_rcp_f32_e32 v33, v33
	s_nop 0
	v_mul_f32_e32 v82, v76, v33
	v_mul_f32_e32 v59, 0x3fb17218, v82
	v_mul_f32_e32 v92, 0x3fb8aa3b, v59
	v_exp_f32_e32 v92, v92
	v_fmamk_f32 v93, v59, 0x3c088889, v202
	v_fmaak_f32 v93, v59, v93, 0x3e2aaaab
	v_fma_f32 v93, v59, v93, 0.5
	v_fma_f32 v93, v59, v93, 1.0
	v_mul_f32_e64 v93, v93, -v59
	v_sub_f32_e32 v92, 1.0, v92
	v_cmp_nlt_f32_e32 vcc, s5, v59
	s_nop 1
	v_cndmask_b32_e32 v33, v93, v92, vcc
	v_lshlrev_b32_e32 v59, 16, v34
	v_add_f32_e32 v59, v8, v59
	v_mul_f32_e32 v59, 0xbfb8aa3b, v59
	v_exp_f32_e32 v59, v59
	s_nop 0
	v_add_f32_e32 v59, 1.0, v59
	v_rcp_f32_e32 v59, v59
	s_nop 0
	v_mul_f32_e32 v61, v75, v59
	v_mul_f32_e32 v63, 0x3fb17218, v61
	v_mul_f32_e32 v92, 0x3fb8aa3b, v63
	v_exp_f32_e32 v92, v92
	v_fmamk_f32 v93, v63, 0x3c088889, v202
	v_fmaak_f32 v93, v63, v93, 0x3e2aaaab
	v_fma_f32 v93, v63, v93, 0.5
	v_fma_f32 v93, v63, v93, 1.0
	v_mul_f32_e64 v93, v93, -v63
	v_sub_f32_e32 v92, 1.0, v92
	v_cmp_nlt_f32_e32 vcc, s5, v63
	s_nop 1
	v_cndmask_b32_e32 v59, v93, v92, vcc
	v_and_b32_e32 v34, 0xffff0000, v34
	v_add_f32_e32 v34, v9, v34
	v_mul_f32_e32 v34, 0xbfb8aa3b, v34
	v_exp_f32_e32 v34, v34
	s_nop 0
	v_add_f32_e32 v34, 1.0, v34
	v_rcp_f32_e32 v34, v34
	s_nop 0
	v_mul_f32_e32 v84, v74, v34
	v_mul_f32_e32 v34, 0x3fb17218, v84
	v_mul_f32_e32 v92, 0x3fb8aa3b, v34
	v_exp_f32_e32 v92, v92
	v_fmamk_f32 v93, v34, 0x3c088889, v202
	v_fmaak_f32 v93, v34, v93, 0x3e2aaaab
	v_fma_f32 v93, v34, v93, 0.5
	v_fma_f32 v93, v34, v93, 1.0
	v_mul_f32_e64 v93, v93, -v34
	v_sub_f32_e32 v92, 1.0, v92
	v_cmp_nlt_f32_e32 vcc, s5, v34
	s_nop 1
	v_cndmask_b32_e32 v83, v93, v92, vcc
	v_lshlrev_b32_e32 v34, 16, v35
	v_add_f32_e32 v34, v10, v34
	v_mul_f32_e32 v34, 0xbfb8aa3b, v34
	v_exp_f32_e32 v34, v34
	s_nop 0
	v_add_f32_e32 v34, 1.0, v34
	v_rcp_f32_e32 v34, v34
	s_nop 0
	v_mul_f32_e32 v65, v73, v34
	v_mul_f32_e32 v34, 0x3fb17218, v65
	v_mul_f32_e32 v92, 0x3fb8aa3b, v34
	v_exp_f32_e32 v92, v92
	v_fmamk_f32 v93, v34, 0x3c088889, v202
	v_fmaak_f32 v93, v34, v93, 0x3e2aaaab
	v_fma_f32 v93, v34, v93, 0.5
	v_fma_f32 v93, v34, v93, 1.0
	v_mul_f32_e64 v93, v93, -v34
	v_sub_f32_e32 v92, 1.0, v92
	v_cmp_nlt_f32_e32 vcc, s5, v34
	s_nop 1
	v_cndmask_b32_e32 v63, v93, v92, vcc
	v_and_b32_e32 v34, 0xffff0000, v35
	v_add_f32_e32 v34, v11, v34
	v_mul_f32_e32 v34, 0xbfb8aa3b, v34
	v_exp_f32_e32 v34, v34
	s_nop 0
	v_add_f32_e32 v34, 1.0, v34
	v_rcp_f32_e32 v34, v34
	s_nop 0
	v_mul_f32_e32 v35, v80, v34
	v_mul_f32_e32 v70, 0x3fb17218, v35
	v_mul_f32_e32 v92, 0x3fb8aa3b, v70
	v_exp_f32_e32 v92, v92
	v_fmamk_f32 v93, v70, 0x3c088889, v202
	v_fmaak_f32 v93, v70, v93, 0x3e2aaaab
	v_fma_f32 v93, v70, v93, 0.5
	v_fma_f32 v93, v70, v93, 1.0
	v_mul_f32_e64 v93, v93, -v70
	v_sub_f32_e32 v92, 1.0, v92
	v_cmp_nlt_f32_e32 vcc, s5, v70
	s_nop 1
	v_cndmask_b32_e32 v34, v93, v92, vcc
	v_cmp_gt_f32_e32 vcc, s82, v65
	s_waitcnt vmcnt(0)
; __device__ __forceinline__ unsigned pk2(float lo, float hi) { f32x2_pk v = {lo, hi}; bf16x2_pk b = __builtin_convertvector(v, bf16x2_pk); return __builtin_bit_cast(unsigned, b); }
; __device__ __forceinline__ float sigmoidf_(float x) { return __builtin_amdgcn_rcpf(1.0f + __expf(-x)); }
; __device__ __forceinline__ void rg_unpack8(const u32x4 w, float* v) { v[0] = bflo(w.x); v[1] = bfhi(w.x); v[2] = bflo(w.y); v[3] = bfhi(w.y); v[4] = bflo(w.z); v[5] = bfhi(w.z); v[6] = bflo(w.w); v[7] = bfhi(w.w); }
; __device__ __forceinline__ void rg_ab(float ra, float ri, float x, float ba, float bx, float sp, float& a, float& b) {
;     const float r = sigmoidf_(ra + ba), ig = sigmoidf_(ri + bx); const float l2 = r * sp; a = exp2f(l2);
;     const float x2 = 1.3862943611198906f * l2;
;     const float om = x2 > -0.125f ? -x2 * (1.0f + x2 * (0.5f + x2 * (0.16666667f + x2 * (0.041666668f + x2 * 0.0083333338f)))) : 1.0f - __expf(x2);
;     b = __builtin_amdgcn_sqrtf(om) * (ig * x);
; }
; __device__ __forceinline__ void rg_scan2_phase(const bf16_t* RA0, bf16_t* RI0, const bf16_t* RA1, const bf16_t* RI1, const bf16_t* XCV, const float* bap, const float* bxp, const float* lamp, const float* CAR, bf16_t* Gb, int gtid, int ngt) {
;     ...
; #pragma unroll 4
;         for (int i = 63; i >= 0; --i) { const size_t off = (size_t)(row0 + i) * DRNN + 8 * cg;
;             float ra[8], ri[8], xv[8], hf[8], gv[8]; rg_unpack8(*(const u32x4*)(RA1 + off), ra); rg_unpack8(*(const u32x4*)(RI1 + off), ri); rg_unpack8(*(const u32x4*)(XCV + off), xv);
;             rg_unpack8(*(const u32x4*)(RI0 + off), hf); rg_unpack8(*(const u32x4*)(Gb + off), gv);
; #pragma unroll
;             for (int e = 0; e < 8; ++e) { float a, bb; rg_ab(ra[e], ri[e], xv[e], ba[e], bx[e], sp[e], a, bb); h[e] = a * h[e] + bb; gv[e] *= hf[e] + h[e]; }
;             u32x4 o; o.x = pk2(gv[0], gv[1]); o.y = pk2(gv[2], gv[3]); o.z = pk2(gv[4], gv[5]); o.w = pk2(gv[6], gv[7]); *(u32x4*)(Gb + off) = o; }
	v_lshlrev_b32_e32 v89, 16, v31
	s_mov_b64 s[2:3], 0x3026c00
	v_cndmask_b32_e32 v71, 0, v221, vcc
	v_add_f32_e32 v65, v65, v71
	v_lshlrev_b32_e32 v71, 16, v19
	v_add_f32_e32 v71, v14, v71
	v_mul_f32_e32 v71, 0xbfb8aa3b, v71
	v_exp_f32_e32 v71, v71
	v_exp_f32_e32 v65, v65
	v_cndmask_b32_e32 v70, 0, v220, vcc
	v_cmp_gt_f32_e32 vcc, s82, v35
	v_add_f32_e32 v71, 1.0, v71
	v_rcp_f32_e32 v85, v71
	v_sqrt_f32_e32 v71, v63
	v_ldexp_f32 v70, v65, v70
	v_lshlrev_b32_e32 v65, 16, v27
	v_mul_f32_e32 v65, v85, v65
	v_mul_f32_e32 v88, v65, v71
	v_lshlrev_b32_e32 v63, 16, v23
	v_pk_fma_f32 v[70:71], v[64:65], v[70:71], v[88:89] op_sel_hi:[1,1,0]
	v_cndmask_b32_e32 v64, 0, v221, vcc
	v_add_f32_e32 v63, v70, v63
	v_mul_f32_e32 v71, v63, v89
	v_cndmask_b32_e32 v63, 0, v220, vcc
	v_cmp_gt_f32_e32 vcc, s82, v61
	v_add_f32_e32 v35, v35, v64
	v_exp_f32_e32 v35, v35
	v_cndmask_b32_e32 v65, 0, v221, vcc
	v_add_f32_e32 v61, v61, v65
	v_lshlrev_b32_e32 v65, 16, v18
	v_add_f32_e32 v65, v12, v65
	v_mul_f32_e32 v65, 0xbfb8aa3b, v65
	v_exp_f32_e32 v61, v61
	v_exp_f32_e32 v65, v65
	v_cndmask_b32_e32 v64, 0, v220, vcc
	v_and_b32_e32 v18, 0xffff0000, v18
	v_ldexp_f32 v64, v61, v64
	v_add_f32_e32 v61, 1.0, v65
	v_add_f32_e32 v18, v13, v18
	v_rcp_f32_e32 v61, v61
	v_mul_f32_e32 v18, 0xbfb8aa3b, v18
	v_exp_f32_e32 v18, v18
	v_sqrt_f32_e32 v65, v59
	v_ldexp_f32 v88, v35, v63
	v_lshlrev_b32_e32 v35, 16, v26
	v_cmp_gt_f32_e32 vcc, s82, v84
	v_mul_f32_e32 v63, v61, v35
	v_add_f32_e32 v18, 1.0, v18
	v_cndmask_b32_e32 v61, 0, v221, vcc
	v_add_f32_e32 v61, v84, v61
	v_mul_f32_e32 v90, v63, v65
	v_exp_f32_e32 v61, v61
	v_rcp_f32_e32 v18, v18
	v_lshlrev_b32_e32 v59, 16, v22
	v_pk_fma_f32 v[64:65], v[62:63], v[64:65], v[90:91] op_sel_hi:[1,1,0]
	v_lshlrev_b32_e32 v85, 16, v30
	v_add_f32_e32 v35, v64, v59
	v_cndmask_b32_e32 v59, 0, v220, vcc
	v_mul_f32_e32 v65, v35, v85
	v_and_b32_e32 v26, 0xffff0000, v26
	v_sqrt_f32_e32 v63, v83
	v_cmp_gt_f32_e32 vcc, s82, v57
	v_lshlrev_b32_e32 v35, 16, v17
	v_ldexp_f32 v62, v61, v59
	v_mul_f32_e32 v61, v18, v26
	v_cndmask_b32_e32 v26, 0, v221, vcc
	v_add_f32_e32 v35, v6, v35
	v_add_f32_e32 v26, v57, v26
	v_mul_f32_e32 v35, 0xbfb8aa3b, v35
	v_exp_f32_e32 v26, v26
	v_exp_f32_e32 v35, v35
	v_mul_f32_e32 v18, v61, v63
	v_and_b32_e32 v22, 0xffff0000, v22
	v_pk_fma_f32 v[62:63], v[60:61], v[62:63], v[18:19] op_sel_hi:[1,1,0]
	v_and_b32_e32 v17, 0xffff0000, v17
	v_add_f32_e32 v18, v62, v22
	v_cndmask_b32_e32 v22, 0, v220, vcc
	v_ldexp_f32 v60, v26, v22
	v_add_f32_e32 v22, 1.0, v35
	v_rcp_f32_e32 v22, v22
	v_sqrt_f32_e32 v61, v55
	v_add_f32_e32 v17, v7, v17
	v_and_b32_e32 v30, 0xffff0000, v30
	v_mul_f32_e32 v17, 0xbfb8aa3b, v17
	v_mul_f32_e32 v30, v18, v30
	v_lshlrev_b32_e32 v18, 16, v25
	v_exp_f32_e32 v17, v17
	v_mul_f32_e32 v59, v22, v18
	v_mul_f32_e32 v18, v59, v61
	v_lshlrev_b32_e32 v26, 16, v21
	v_pk_fma_f32 v[60:61], v[58:59], v[60:61], v[18:19] op_sel_hi:[1,1,0]
	v_cmp_gt_f32_e32 vcc, s82, v82
	v_add_f32_e32 v18, v60, v26
	v_add_f32_e32 v17, 1.0, v17
	v_cndmask_b32_e32 v26, 0, v221, vcc
	v_add_f32_e32 v26, v82, v26
	v_rcp_f32_e32 v17, v17
	v_exp_f32_e32 v26, v26
	v_sqrt_f32_e32 v59, v33
	v_lshlrev_b32_e32 v35, 16, v29
	v_mul_f32_e32 v61, v18, v35
	v_and_b32_e32 v18, 0xffff0000, v25
	v_cndmask_b32_e32 v22, 0, v220, vcc
	v_mul_f32_e32 v57, v17, v18
	v_ldexp_f32 v58, v26, v22
	v_mul_f32_e32 v18, v57, v59
	v_and_b32_e32 v21, 0xffff0000, v21
	v_pk_fma_f32 v[58:59], v[56:57], v[58:59], v[18:19] op_sel_hi:[1,1,0]
	v_and_b32_e32 v22, 0xffff0000, v29
	v_add_f32_e32 v17, v58, v21
	v_mul_f32_e32 v21, v17, v22
	v_lshlrev_b32_e32 v17, 16, v16
	v_add_f32_e32 v17, v4, v17
	v_mul_f32_e32 v17, 0xbfb8aa3b, v17
	v_exp_f32_e32 v17, v17
	v_cmp_gt_f32_e32 vcc, s82, v51
	v_sqrt_f32_e32 v57, v53
	v_lshlrev_b32_e32 v18, 16, v24
	v_cndmask_b32_e32 v26, 0, v221, vcc
	v_add_f32_e32 v17, 1.0, v17
	v_add_f32_e32 v26, v51, v26
	v_rcp_f32_e32 v17, v17
	v_exp_f32_e32 v26, v26
	v_cndmask_b32_e32 v25, 0, v220, vcc
	v_and_b32_e32 v16, 0xffff0000, v16
	v_mul_f32_e32 v55, v17, v18
	v_ldexp_f32 v56, v26, v25
	v_mul_f32_e32 v18, v55, v57
	v_lshlrev_b32_e32 v22, 16, v20
	v_pk_fma_f32 v[56:57], v[54:55], v[56:57], v[18:19] op_sel_hi:[1,1,0]
	v_cmp_gt_f32_e32 vcc, s82, v81
	v_add_f32_e32 v16, v5, v16
	v_add_f32_e32 v17, v56, v22
	v_cndmask_b32_e32 v22, 0, v221, vcc
	v_mul_f32_e32 v16, 0xbfb8aa3b, v16
	v_add_f32_e32 v22, v81, v22
	v_exp_f32_e32 v25, v16
	v_exp_f32_e32 v22, v22
	v_lshlrev_b32_e32 v29, 16, v28
	v_cndmask_b32_e32 v18, 0, v220, vcc
	v_mul_f32_e32 v26, v17, v29
	v_add_f32_e32 v17, 1.0, v25
	v_ldexp_f32 v16, v22, v18
	v_rcp_f32_e32 v22, v17
	v_sqrt_f32_e32 v17, v32
	v_and_b32_e32 v18, 0xffff0000, v24
	v_sqrt_f32_e32 v89, v34
	v_mul_f32_e32 v53, v22, v18
	v_mul_f32_e32 v18, v53, v17
	v_pk_fma_f32 v[54:55], v[52:53], v[16:17], v[18:19] op_sel_hi:[1,1,0]
	v_and_b32_e32 v16, 0xffff0000, v19
	v_add_f32_e32 v16, v15, v16
	v_mul_f32_e32 v16, 0xbfb8aa3b, v16
	v_exp_f32_e32 v16, v16
	global_load_dwordx4 v[32:35], v[48:49], off offset:512
	v_and_b32_e32 v20, 0xffff0000, v20
	v_and_b32_e32 v18, 0xffff0000, v27
	v_add_f32_e32 v16, 1.0, v16
	v_rcp_f32_e32 v16, v16
	v_and_b32_e32 v24, 0xffff0000, v28
	v_add_f32_e32 v17, v54, v20
	v_mul_f32_e32 v17, v17, v24
	v_mul_f32_e32 v51, v16, v18
	v_mul_f32_e32 v16, v51, v89
	v_and_b32_e32 v19, 0xffff0000, v23
	v_pk_fma_f32 v[52:53], v[50:51], v[88:89], v[16:17] op_sel_hi:[1,1,0]
	v_and_b32_e32 v20, 0xffff0000, v31
	v_add_f32_e32 v16, v52, v19
	v_mul_f32_e32 v19, v16, v20
	v_lshl_add_u64 v[86:87], v[42:43], 0, s[2:3]
	v_cvt_pk_bf16_f32 v16, v26, v17
	v_cvt_pk_bf16_f32 v17, v61, v21
	v_cvt_pk_bf16_f32 v18, v65, v30
	v_cvt_pk_bf16_f32 v19, v71, v19
	global_store_dwordx4 v[86:87], v[16:19], off
	v_add_co_u32_e32 v28, vcc, 0x3026000, v42
	global_load_dwordx4 v[24:27], v[46:47], off offset:512
	global_load_dwordx4 v[20:23], v[66:67], off offset:512
	global_load_dwordx4 v[16:19], v[68:69], off offset:512
	v_addc_co_u32_e32 v29, vcc, 0, v43, vcc
	global_load_dwordx4 v[28:31], v[28:29], off offset:512
	s_waitcnt vmcnt(5)
; __device__ __forceinline__ unsigned pk2(float lo, float hi) { f32x2_pk v = {lo, hi}; bf16x2_pk b = __builtin_convertvector(v, bf16x2_pk); return __builtin_bit_cast(unsigned, b); }
; __device__ __forceinline__ float sigmoidf_(float x) { return __builtin_amdgcn_rcpf(1.0f + __expf(-x)); }
; __device__ __forceinline__ void rg_unpack8(const u32x4 w, float* v) { v[0] = bflo(w.x); v[1] = bfhi(w.x); v[2] = bflo(w.y); v[3] = bfhi(w.y); v[4] = bflo(w.z); v[5] = bfhi(w.z); v[6] = bflo(w.w); v[7] = bfhi(w.w); }
; __device__ __forceinline__ void rg_ab(float ra, float ri, float x, float ba, float bx, float sp, float& a, float& b) {
;     const float r = sigmoidf_(ra + ba), ig = sigmoidf_(ri + bx); const float l2 = r * sp; a = exp2f(l2);
;     const float x2 = 1.3862943611198906f * l2;
;     const float om = x2 > -0.125f ? -x2 * (1.0f + x2 * (0.5f + x2 * (0.16666667f + x2 * (0.041666668f + x2 * 0.0083333338f)))) : 1.0f - __expf(x2);
;     b = __builtin_amdgcn_sqrtf(om) * (ig * x);
; }
; __device__ __forceinline__ void rg_scan2_phase(const bf16_t* RA0, bf16_t* RI0, const bf16_t* RA1, const bf16_t* RI1, const bf16_t* XCV, const float* bap, const float* bxp, const float* lamp, const float* CAR, bf16_t* Gb, int gtid, int ngt) {
;     ...
; #pragma unroll 4
;         for (int i = 63; i >= 0; --i) { const size_t off = (size_t)(row0 + i) * DRNN + 8 * cg;
;             float ra[8], ri[8], xv[8], hf[8], gv[8]; rg_unpack8(*(const u32x4*)(RA1 + off), ra); rg_unpack8(*(const u32x4*)(RI1 + off), ri); rg_unpack8(*(const u32x4*)(XCV + off), xv);
;             rg_unpack8(*(const u32x4*)(RI0 + off), hf); rg_unpack8(*(const u32x4*)(Gb + off), gv);
; #pragma unroll
;             for (int e = 0; e < 8; ++e) { float a, bb; rg_ab(ra[e], ri[e], xv[e], ba[e], bx[e], sp[e], a, bb); h[e] = a * h[e] + bb; gv[e] *= hf[e] + h[e]; }
;             u32x4 o; o.x = pk2(gv[0], gv[1]); o.y = pk2(gv[2], gv[3]); o.z = pk2(gv[4], gv[5]); o.w = pk2(gv[6], gv[7]); *(u32x4*)(Gb + off) = o; }
	v_lshlrev_b32_e32 v46, 16, v32
	v_add_f32_e32 v46, v0, v46
	v_mul_f32_e32 v46, 0xbfb8aa3b, v46
	v_exp_f32_e32 v46, v46
	s_nop 0
	v_add_f32_e32 v46, 1.0, v46
	v_rcp_f32_e32 v46, v46
	s_nop 0
	v_mul_f32_e32 v53, v79, v46
	v_mul_f32_e32 v46, 0x3fb17218, v53
	v_mul_f32_e32 v92, 0x3fb8aa3b, v46
	v_exp_f32_e32 v92, v92
	v_fmamk_f32 v93, v46, 0x3c088889, v202
	v_fmaak_f32 v93, v46, v93, 0x3e2aaaab
	v_fma_f32 v93, v46, v93, 0.5
	v_fma_f32 v93, v46, v93, 1.0
	v_mul_f32_e64 v93, v93, -v46
	v_sub_f32_e32 v92, 1.0, v92
	v_cmp_nlt_f32_e32 vcc, s5, v46
	s_nop 1
	v_cndmask_b32_e32 v55, v93, v92, vcc
	v_and_b32_e32 v32, 0xffff0000, v32
	v_add_f32_e32 v32, v1, v32
	v_mul_f32_e32 v32, 0xbfb8aa3b, v32
	v_exp_f32_e32 v32, v32
	s_nop 0
	v_add_f32_e32 v32, 1.0, v32
	v_rcp_f32_e32 v32, v32
	s_nop 0
	v_mul_f32_e32 v66, v78, v32
	v_mul_f32_e32 v46, 0x3fb17218, v66
	v_mul_f32_e32 v92, 0x3fb8aa3b, v46
	v_exp_f32_e32 v92, v92
	v_fmamk_f32 v93, v46, 0x3c088889, v202
	v_fmaak_f32 v93, v46, v93, 0x3e2aaaab
	v_fma_f32 v93, v46, v93, 0.5
	v_fma_f32 v93, v46, v93, 1.0
	v_mul_f32_e64 v93, v93, -v46
	v_sub_f32_e32 v92, 1.0, v92
	v_cmp_nlt_f32_e32 vcc, s5, v46
	s_nop 1
	v_cndmask_b32_e32 v32, v93, v92, vcc
	v_lshlrev_b32_e32 v46, 16, v33
	v_add_f32_e32 v46, v2, v46
	v_mul_f32_e32 v46, 0xbfb8aa3b, v46
	v_exp_f32_e32 v46, v46
	s_nop 0
	v_add_f32_e32 v46, 1.0, v46
	v_rcp_f32_e32 v46, v46
	s_nop 0
	v_mul_f32_e32 v59, v77, v46
	v_mul_f32_e32 v46, 0x3fb17218, v59
	v_mul_f32_e32 v92, 0x3fb8aa3b, v46
	v_exp_f32_e32 v92, v92
	v_fmamk_f32 v93, v46, 0x3c088889, v202
	v_fmaak_f32 v93, v46, v93, 0x3e2aaaab
	v_fma_f32 v93, v46, v93, 0.5
	v_fma_f32 v93, v46, v93, 1.0
	v_mul_f32_e64 v93, v93, -v46
	v_sub_f32_e32 v92, 1.0, v92
	v_cmp_nlt_f32_e32 vcc, s5, v46
	s_nop 1
	v_cndmask_b32_e32 v57, v93, v92, vcc
	v_and_b32_e32 v33, 0xffff0000, v33
	v_add_f32_e32 v33, v3, v33
	v_mul_f32_e32 v33, 0xbfb8aa3b, v33
	v_exp_f32_e32 v33, v33
	s_nop 0
	v_add_f32_e32 v33, 1.0, v33
	v_rcp_f32_e32 v33, v33
	s_nop 0
	v_mul_f32_e32 v67, v76, v33
	v_mul_f32_e32 v46, 0x3fb17218, v67
	v_mul_f32_e32 v92, 0x3fb8aa3b, v46
	v_exp_f32_e32 v92, v92
	v_fmamk_f32 v93, v46, 0x3c088889, v202
	v_fmaak_f32 v93, v46, v93, 0x3e2aaaab
	v_fma_f32 v93, v46, v93, 0.5
	v_fma_f32 v93, v46, v93, 1.0
	v_mul_f32_e64 v93, v93, -v46
	v_sub_f32_e32 v92, 1.0, v92
	v_cmp_nlt_f32_e32 vcc, s5, v46
	s_nop 1
	v_cndmask_b32_e32 v33, v93, v92, vcc
	v_lshlrev_b32_e32 v46, 16, v34
	v_add_f32_e32 v46, v8, v46
	v_mul_f32_e32 v46, 0xbfb8aa3b, v46
	v_exp_f32_e32 v46, v46
	s_nop 0
	v_add_f32_e32 v46, 1.0, v46
	v_rcp_f32_e32 v46, v46
	s_nop 0
	v_mul_f32_e32 v49, v75, v46
	v_mul_f32_e32 v46, 0x3fb17218, v49
	v_mul_f32_e32 v92, 0x3fb8aa3b, v46
	v_exp_f32_e32 v92, v92
	v_fmamk_f32 v93, v46, 0x3c088889, v202
	v_fmaak_f32 v93, v46, v93, 0x3e2aaaab
	v_fma_f32 v93, v46, v93, 0.5
	v_fma_f32 v93, v46, v93, 1.0
	v_mul_f32_e64 v93, v93, -v46
	v_sub_f32_e32 v92, 1.0, v92
	v_cmp_nlt_f32_e32 vcc, s5, v46
	s_nop 1
	v_cndmask_b32_e32 v48, v93, v92, vcc
	v_and_b32_e32 v34, 0xffff0000, v34
	v_add_f32_e32 v34, v9, v34
	v_mul_f32_e32 v34, 0xbfb8aa3b, v34
	v_exp_f32_e32 v34, v34
	s_nop 0
	v_add_f32_e32 v34, 1.0, v34
	v_rcp_f32_e32 v34, v34
	s_nop 0
	v_mul_f32_e32 v51, v74, v34
	v_mul_f32_e32 v34, 0x3fb17218, v51
	v_mul_f32_e32 v92, 0x3fb8aa3b, v34
	v_exp_f32_e32 v92, v92
	v_fmamk_f32 v93, v34, 0x3c088889, v202
	v_fmaak_f32 v93, v34, v93, 0x3e2aaaab
	v_fma_f32 v93, v34, v93, 0.5
	v_fma_f32 v93, v34, v93, 1.0
	v_mul_f32_e64 v93, v93, -v34
	v_sub_f32_e32 v92, 1.0, v92
	v_cmp_nlt_f32_e32 vcc, s5, v34
	s_nop 1
	v_cndmask_b32_e32 v50, v93, v92, vcc
	v_lshlrev_b32_e32 v34, 16, v35
	v_add_f32_e32 v34, v10, v34
	v_mul_f32_e32 v34, 0xbfb8aa3b, v34
	v_exp_f32_e32 v34, v34
	s_nop 0
	v_add_f32_e32 v34, 1.0, v34
	v_rcp_f32_e32 v34, v34
	s_nop 0
	v_mul_f32_e32 v47, v73, v34
	v_mul_f32_e32 v34, 0x3fb17218, v47
	v_mul_f32_e32 v92, 0x3fb8aa3b, v34
	v_exp_f32_e32 v92, v92
	v_fmamk_f32 v93, v34, 0x3c088889, v202
	v_fmaak_f32 v93, v34, v93, 0x3e2aaaab
	v_fma_f32 v93, v34, v93, 0.5
	v_fma_f32 v93, v34, v93, 1.0
	v_mul_f32_e64 v93, v93, -v34
	v_sub_f32_e32 v92, 1.0, v92
	v_cmp_nlt_f32_e32 vcc, s5, v34
	s_nop 1
	v_cndmask_b32_e32 v46, v93, v92, vcc
	v_and_b32_e32 v34, 0xffff0000, v35
	v_add_f32_e32 v34, v11, v34
	v_mul_f32_e32 v34, 0xbfb8aa3b, v34
	v_exp_f32_e32 v34, v34
	s_nop 0
	v_add_f32_e32 v34, 1.0, v34
	v_rcp_f32_e32 v34, v34
	s_nop 0
	v_mul_f32_e32 v35, v80, v34
	v_mul_f32_e32 v61, 0x3fb17218, v35
	v_mul_f32_e32 v92, 0x3fb8aa3b, v61
	v_exp_f32_e32 v92, v92
	v_fmamk_f32 v93, v61, 0x3c088889, v202
	v_fmaak_f32 v93, v61, v93, 0x3e2aaaab
	v_fma_f32 v93, v61, v93, 0.5
	v_fma_f32 v93, v61, v93, 1.0
	v_mul_f32_e64 v93, v93, -v61
	v_sub_f32_e32 v92, 1.0, v92
	v_cmp_nlt_f32_e32 vcc, s5, v61
	s_nop 1
	v_cndmask_b32_e32 v34, v93, v92, vcc
	v_cmp_gt_f32_e32 vcc, s82, v47
	v_sqrt_f32_e32 v83, v46
	s_waitcnt vmcnt(0)
; __device__ __forceinline__ unsigned pk2(float lo, float hi) { f32x2_pk v = {lo, hi}; bf16x2_pk b = __builtin_convertvector(v, bf16x2_pk); return __builtin_bit_cast(unsigned, b); }
; __device__ __forceinline__ float sigmoidf_(float x) { return __builtin_amdgcn_rcpf(1.0f + __expf(-x)); }
; __device__ __forceinline__ void rg_unpack8(const u32x4 w, float* v) { v[0] = bflo(w.x); v[1] = bfhi(w.x); v[2] = bflo(w.y); v[3] = bfhi(w.y); v[4] = bflo(w.z); v[5] = bfhi(w.z); v[6] = bflo(w.w); v[7] = bfhi(w.w); }
; __device__ __forceinline__ void rg_ab(float ra, float ri, float x, float ba, float bx, float sp, float& a, float& b) {
;     const float r = sigmoidf_(ra + ba), ig = sigmoidf_(ri + bx); const float l2 = r * sp; a = exp2f(l2);
;     const float x2 = 1.3862943611198906f * l2;
;     const float om = x2 > -0.125f ? -x2 * (1.0f + x2 * (0.5f + x2 * (0.16666667f + x2 * (0.041666668f + x2 * 0.0083333338f)))) : 1.0f - __expf(x2);
;     b = __builtin_amdgcn_sqrtf(om) * (ig * x);
; }
; __device__ __forceinline__ void rg_scan2_phase(const bf16_t* RA0, bf16_t* RI0, const bf16_t* RA1, const bf16_t* RI1, const bf16_t* XCV, const float* bap, const float* bxp, const float* lamp, const float* CAR, bf16_t* Gb, int gtid, int ngt) {
;     ...
; #pragma unroll 4
;         for (int i = 63; i >= 0; --i) { const size_t off = (size_t)(row0 + i) * DRNN + 8 * cg;
;             float ra[8], ri[8], xv[8], hf[8], gv[8]; rg_unpack8(*(const u32x4*)(RA1 + off), ra); rg_unpack8(*(const u32x4*)(RI1 + off), ri); rg_unpack8(*(const u32x4*)(XCV + off), xv);
;             rg_unpack8(*(const u32x4*)(RI0 + off), hf); rg_unpack8(*(const u32x4*)(Gb + off), gv);
; #pragma unroll
;             for (int e = 0; e < 8; ++e) { float a, bb; rg_ab(ra[e], ri[e], xv[e], ba[e], bx[e], sp[e], a, bb); h[e] = a * h[e] + bb; gv[e] *= hf[e] + h[e]; }
;             u32x4 o; o.x = pk2(gv[0], gv[1]); o.y = pk2(gv[2], gv[3]); o.z = pk2(gv[4], gv[5]); o.w = pk2(gv[6], gv[7]); *(u32x4*)(Gb + off) = o; }
	v_lshlrev_b32_e32 v65, 16, v31
	v_cndmask_b32_e32 v63, 0, v221, vcc
	v_add_f32_e32 v47, v47, v63
	v_lshlrev_b32_e32 v63, 16, v27
	v_add_f32_e32 v63, v14, v63
	v_mul_f32_e32 v63, 0xbfb8aa3b, v63
	v_exp_f32_e32 v47, v47
	v_exp_f32_e32 v63, v63
	v_cndmask_b32_e32 v61, 0, v220, vcc
	v_cmp_gt_f32_e32 vcc, s82, v35
	v_ldexp_f32 v82, v47, v61
	v_add_f32_e32 v61, 1.0, v63
	v_rcp_f32_e32 v61, v61
	v_lshlrev_b32_e32 v47, 16, v23
	v_lshlrev_b32_e32 v63, 16, v19
	s_mov_b64 s[2:3], 0x3026200
	v_mul_f32_e32 v71, v61, v47
	v_mul_f32_e32 v46, v71, v83
	v_pk_fma_f32 v[46:47], v[70:71], v[82:83], v[46:47] op_sel_hi:[1,1,0]
	v_cndmask_b32_e32 v61, 0, v220, vcc
	v_add_f32_e32 v47, v46, v63
	v_cndmask_b32_e32 v63, 0, v221, vcc
	v_cmp_gt_f32_e32 vcc, s82, v49
	v_mul_f32_e32 v47, v47, v65
	v_add_f32_e32 v35, v35, v63
	v_cndmask_b32_e32 v65, 0, v221, vcc
	v_add_f32_e32 v49, v49, v65
	v_lshlrev_b32_e32 v65, 16, v26
	v_add_f32_e32 v65, v12, v65
	v_mul_f32_e32 v65, 0xbfb8aa3b, v65
	v_exp_f32_e32 v49, v49
	v_exp_f32_e32 v65, v65
	v_cndmask_b32_e32 v63, 0, v220, vcc
	v_exp_f32_e32 v35, v35
	v_ldexp_f32 v82, v49, v63
	v_add_f32_e32 v49, 1.0, v65
	v_rcp_f32_e32 v49, v49
	v_and_b32_e32 v26, 0xffff0000, v26
	v_sqrt_f32_e32 v83, v48
	v_add_f32_e32 v26, v13, v26
	v_mul_f32_e32 v26, 0xbfb8aa3b, v26
	v_ldexp_f32 v70, v35, v61
	v_lshlrev_b32_e32 v35, 16, v22
	v_exp_f32_e32 v26, v26
	v_mul_f32_e32 v65, v49, v35
	v_mul_f32_e32 v48, v65, v83
	v_lshlrev_b32_e32 v61, 16, v18
	v_pk_fma_f32 v[48:49], v[64:65], v[82:83], v[48:49] op_sel_hi:[1,1,0]
	v_cmp_gt_f32_e32 vcc, s82, v51
	v_add_f32_e32 v35, v48, v61
	v_add_f32_e32 v26, 1.0, v26
	v_cndmask_b32_e32 v61, 0, v221, vcc
	v_add_f32_e32 v51, v51, v61
	v_rcp_f32_e32 v26, v26
	v_exp_f32_e32 v51, v51
	v_sqrt_f32_e32 v65, v50
	v_lshlrev_b32_e32 v63, 16, v30
	v_and_b32_e32 v22, 0xffff0000, v22
	v_cndmask_b32_e32 v49, 0, v220, vcc
	v_mul_f32_e32 v35, v35, v63
	v_mul_f32_e32 v63, v26, v22
	v_ldexp_f32 v64, v51, v49
	v_and_b32_e32 v49, 0xffff0000, v18
	v_mul_f32_e32 v18, v63, v65
	v_pk_fma_f32 v[50:51], v[62:63], v[64:65], v[18:19] op_sel_hi:[1,1,0]
	v_cmp_gt_f32_e32 vcc, s82, v59
	v_add_f32_e32 v18, v50, v49
	v_lshlrev_b32_e32 v49, 16, v25
	v_cndmask_b32_e32 v26, 0, v221, vcc
	v_add_f32_e32 v49, v6, v49
	v_add_f32_e32 v26, v59, v26
	v_mul_f32_e32 v49, 0xbfb8aa3b, v49
	v_exp_f32_e32 v26, v26
	v_exp_f32_e32 v49, v49
	v_cndmask_b32_e32 v22, 0, v220, vcc
	v_sqrt_f32_e32 v63, v57
	v_ldexp_f32 v62, v26, v22
	v_add_f32_e32 v22, 1.0, v49
	v_rcp_f32_e32 v22, v22
	v_and_b32_e32 v25, 0xffff0000, v25
	v_and_b32_e32 v30, 0xffff0000, v30
	v_add_f32_e32 v25, v7, v25
	v_mul_f32_e32 v30, v18, v30
	v_lshlrev_b32_e32 v18, 16, v21
	v_mul_f32_e32 v25, 0xbfb8aa3b, v25
	v_mul_f32_e32 v61, v22, v18
	v_exp_f32_e32 v25, v25
	v_mul_f32_e32 v18, v61, v63
	v_lshlrev_b32_e32 v26, 16, v17
	v_pk_fma_f32 v[60:61], v[60:61], v[62:63], v[18:19] op_sel_hi:[1,1,0]
	v_lshlrev_b32_e32 v49, 16, v29
	v_add_f32_e32 v18, v60, v26
	v_cmp_gt_f32_e32 vcc, s82, v67
	v_mul_f32_e32 v49, v18, v49
	v_and_b32_e32 v18, 0xffff0000, v21
	v_cndmask_b32_e32 v26, 0, v221, vcc
	v_add_f32_e32 v21, 1.0, v25
	v_add_f32_e32 v26, v67, v26
	v_rcp_f32_e32 v21, v21
	v_exp_f32_e32 v26, v26
	v_sqrt_f32_e32 v63, v33
	v_cndmask_b32_e32 v22, 0, v220, vcc
	v_mul_f32_e32 v59, v21, v18
	v_ldexp_f32 v62, v26, v22
	v_mul_f32_e32 v18, v59, v63
	v_pk_fma_f32 v[58:59], v[58:59], v[62:63], v[18:19] op_sel_hi:[1,1,0]
	v_lshlrev_b32_e32 v18, 16, v24
	v_add_f32_e32 v18, v4, v18
	v_mul_f32_e32 v18, 0xbfb8aa3b, v18
	v_exp_f32_e32 v18, v18
	v_cmp_gt_f32_e32 vcc, s82, v53
	v_sqrt_f32_e32 v63, v55
	v_lshlrev_b32_e32 v21, 16, v20
	v_cndmask_b32_e32 v26, 0, v221, vcc
	v_add_f32_e32 v18, 1.0, v18
	v_add_f32_e32 v26, v53, v26
	v_rcp_f32_e32 v18, v18
	v_exp_f32_e32 v26, v26
	v_and_b32_e32 v17, 0xffff0000, v17
	v_cndmask_b32_e32 v25, 0, v220, vcc
	v_mul_f32_e32 v57, v18, v21
	v_and_b32_e32 v22, 0xffff0000, v29
	v_add_f32_e32 v17, v58, v17
	v_ldexp_f32 v62, v26, v25
	v_mul_f32_e32 v18, v57, v63
	v_mul_f32_e32 v17, v17, v22
	v_lshlrev_b32_e32 v22, 16, v16
	v_pk_fma_f32 v[56:57], v[56:57], v[62:63], v[18:19] op_sel_hi:[1,1,0]
	v_cmp_gt_f32_e32 vcc, s82, v66
	v_and_b32_e32 v24, 0xffff0000, v24
	v_add_f32_e32 v18, v56, v22
	v_cndmask_b32_e32 v22, 0, v221, vcc
	v_add_f32_e32 v24, v5, v24
	v_add_f32_e32 v22, v66, v22
	v_mul_f32_e32 v24, 0xbfb8aa3b, v24
	v_exp_f32_e32 v22, v22
	v_exp_f32_e32 v25, v24
	v_cndmask_b32_e32 v21, 0, v220, vcc
	v_and_b32_e32 v20, 0xffff0000, v20
	v_ldexp_f32 v24, v22, v21
	v_add_f32_e32 v21, 1.0, v25
	v_rcp_f32_e32 v21, v21
	v_sqrt_f32_e32 v25, v32
	v_and_b32_e32 v22, 0xffff0000, v16
	v_sqrt_f32_e32 v71, v34
	v_mul_f32_e32 v55, v21, v20
	v_mul_f32_e32 v16, v55, v25
	v_pk_fma_f32 v[54:55], v[54:55], v[24:25], v[16:17] op_sel_hi:[1,1,0]
	v_and_b32_e32 v16, 0xffff0000, v27
	v_add_f32_e32 v16, v15, v16
	v_mul_f32_e32 v16, 0xbfb8aa3b, v16
	v_exp_f32_e32 v16, v16
	v_and_b32_e32 v21, 0xffff0000, v23
	v_and_b32_e32 v19, 0xffff0000, v19
	v_lshlrev_b32_e32 v29, 16, v28
	v_add_f32_e32 v16, 1.0, v16
	v_rcp_f32_e32 v16, v16
	v_and_b32_e32 v26, 0xffff0000, v28
	v_add_f32_e32 v20, v54, v22
	v_and_b32_e32 v22, 0xffff0000, v31
	v_mul_f32_e32 v53, v16, v21
	v_mul_f32_e32 v16, v53, v71
	v_pk_fma_f32 v[62:63], v[52:53], v[70:71], v[16:17] op_sel_hi:[1,1,0]
	v_mul_f32_e32 v18, v18, v29
	v_add_f32_e32 v16, v62, v19
	v_mul_f32_e32 v20, v20, v26
	v_mul_f32_e32 v19, v16, v22
	v_lshl_add_u64 v[68:69], v[42:43], 0, s[2:3]
	v_cvt_pk_bf16_f32 v16, v18, v20
	v_cvt_pk_bf16_f32 v17, v49, v17
	v_cvt_pk_bf16_f32 v18, v35, v30
	v_cvt_pk_bf16_f32 v19, v47, v19
	s_mov_b32 s2, 0x19825000
	global_store_dwordx4 v[68:69], v[16:19], off
	s_nop 1
	v_add_co_u32_e32 v16, vcc, s2, v42
	s_mov_b32 s2, 0x25000
	s_nop 0
	v_addc_co_u32_e32 v17, vcc, 0, v43, vcc
	global_load_dwordx4 v[32:35], v[16:17], off offset:2048
	v_add_co_u32_e32 v16, vcc, s2, v44
	s_mov_b32 s2, 0x8a25000
	s_nop 0
	v_addc_co_u32_e32 v17, vcc, 0, v45, vcc
	v_add_co_u32_e32 v20, vcc, s2, v42
	s_mov_b32 s2, 0x13e25000
	s_nop 0
	v_addc_co_u32_e32 v21, vcc, 0, v43, vcc
	v_add_co_u32_e32 v22, vcc, s2, v42
	global_load_dwordx4 v[16:19], v[16:17], off offset:2048
	s_nop 0
	v_addc_co_u32_e32 v23, vcc, 0, v43, vcc
	v_add_co_u32_e32 v28, vcc, 0x3025000, v42
	global_load_dwordx4 v[24:27], v[20:21], off offset:2048
	s_nop 0
	global_load_dwordx4 v[20:23], v[22:23], off offset:2048
	v_addc_co_u32_e32 v29, vcc, 0, v43, vcc
	global_load_dwordx4 v[28:31], v[28:29], off offset:2048
	s_waitcnt vmcnt(4)
; __device__ __forceinline__ unsigned pk2(float lo, float hi) { f32x2_pk v = {lo, hi}; bf16x2_pk b = __builtin_convertvector(v, bf16x2_pk); return __builtin_bit_cast(unsigned, b); }
; __device__ __forceinline__ float sigmoidf_(float x) { return __builtin_amdgcn_rcpf(1.0f + __expf(-x)); }
; __device__ __forceinline__ void rg_unpack8(const u32x4 w, float* v) { v[0] = bflo(w.x); v[1] = bfhi(w.x); v[2] = bflo(w.y); v[3] = bfhi(w.y); v[4] = bflo(w.z); v[5] = bfhi(w.z); v[6] = bflo(w.w); v[7] = bfhi(w.w); }
; __device__ __forceinline__ void rg_ab(float ra, float ri, float x, float ba, float bx, float sp, float& a, float& b) {
;     const float r = sigmoidf_(ra + ba), ig = sigmoidf_(ri + bx); const float l2 = r * sp; a = exp2f(l2);
;     const float x2 = 1.3862943611198906f * l2;
;     const float om = x2 > -0.125f ? -x2 * (1.0f + x2 * (0.5f + x2 * (0.16666667f + x2 * (0.041666668f + x2 * 0.0083333338f)))) : 1.0f - __expf(x2);
;     b = __builtin_amdgcn_sqrtf(om) * (ig * x);
; }
; __device__ __forceinline__ void rg_scan2_phase(const bf16_t* RA0, bf16_t* RI0, const bf16_t* RA1, const bf16_t* RI1, const bf16_t* XCV, const float* bap, const float* bxp, const float* lamp, const float* CAR, bf16_t* Gb, int gtid, int ngt) {
;     ...
; #pragma unroll 4
;         for (int i = 63; i >= 0; --i) { const size_t off = (size_t)(row0 + i) * DRNN + 8 * cg;
;             float ra[8], ri[8], xv[8], hf[8], gv[8]; rg_unpack8(*(const u32x4*)(RA1 + off), ra); rg_unpack8(*(const u32x4*)(RI1 + off), ri); rg_unpack8(*(const u32x4*)(XCV + off), xv);
;             rg_unpack8(*(const u32x4*)(RI0 + off), hf); rg_unpack8(*(const u32x4*)(Gb + off), gv);
; #pragma unroll
;             for (int e = 0; e < 8; ++e) { float a, bb; rg_ab(ra[e], ri[e], xv[e], ba[e], bx[e], sp[e], a, bb); h[e] = a * h[e] + bb; gv[e] *= hf[e] + h[e]; }
;             u32x4 o; o.x = pk2(gv[0], gv[1]); o.y = pk2(gv[2], gv[3]); o.z = pk2(gv[4], gv[5]); o.w = pk2(gv[6], gv[7]); *(u32x4*)(Gb + off) = o; }
	v_lshlrev_b32_e32 v44, 16, v32
	v_add_f32_e32 v44, v0, v44
	v_mul_f32_e32 v44, 0xbfb8aa3b, v44
	v_exp_f32_e32 v44, v44
	s_nop 0
	v_add_f32_e32 v44, 1.0, v44
	v_rcp_f32_e32 v44, v44
	s_nop 0
	v_mul_f32_e32 v44, v79, v44
	v_mul_f32_e32 v47, 0x3fb17218, v44
	v_mul_f32_e32 v92, 0x3fb8aa3b, v47
	v_exp_f32_e32 v92, v92
	v_fmamk_f32 v93, v47, 0x3c088889, v202
	v_fmaak_f32 v93, v47, v93, 0x3e2aaaab
	v_fma_f32 v93, v47, v93, 0.5
	v_fma_f32 v93, v47, v93, 1.0
	v_mul_f32_e64 v93, v93, -v47
	v_sub_f32_e32 v92, 1.0, v92
	v_cmp_nlt_f32_e32 vcc, s5, v47
	s_nop 1
	v_cndmask_b32_e32 v45, v93, v92, vcc
	v_and_b32_e32 v32, 0xffff0000, v32
	v_add_f32_e32 v32, v1, v32
	v_mul_f32_e32 v32, 0xbfb8aa3b, v32
	v_exp_f32_e32 v32, v32
	s_nop 0
	v_add_f32_e32 v32, 1.0, v32
	v_rcp_f32_e32 v32, v32
	s_nop 0
	v_mul_f32_e32 v32, v78, v32
	v_mul_f32_e32 v49, 0x3fb17218, v32
	v_mul_f32_e32 v92, 0x3fb8aa3b, v49
	v_exp_f32_e32 v92, v92
	v_fmamk_f32 v93, v49, 0x3c088889, v202
	v_fmaak_f32 v93, v49, v93, 0x3e2aaaab
	v_fma_f32 v93, v49, v93, 0.5
	v_fma_f32 v93, v49, v93, 1.0
	v_mul_f32_e64 v93, v93, -v49
	v_sub_f32_e32 v92, 1.0, v92
	v_cmp_nlt_f32_e32 vcc, s5, v49
	s_nop 1
	v_cndmask_b32_e32 v47, v93, v92, vcc
	v_lshlrev_b32_e32 v49, 16, v33
	v_add_f32_e32 v49, v2, v49
	v_mul_f32_e32 v49, 0xbfb8aa3b, v49
	v_exp_f32_e32 v49, v49
	s_nop 0
	v_add_f32_e32 v49, 1.0, v49
	v_rcp_f32_e32 v49, v49
	s_nop 0
	v_mul_f32_e32 v49, v77, v49
	v_mul_f32_e32 v52, 0x3fb17218, v49
	v_mul_f32_e32 v92, 0x3fb8aa3b, v52
	v_exp_f32_e32 v92, v92
	v_fmamk_f32 v93, v52, 0x3c088889, v202
	v_fmaak_f32 v93, v52, v93, 0x3e2aaaab
	v_fma_f32 v93, v52, v93, 0.5
	v_fma_f32 v93, v52, v93, 1.0
	v_mul_f32_e64 v93, v93, -v52
	v_sub_f32_e32 v92, 1.0, v92
	v_cmp_nlt_f32_e32 vcc, s5, v52
	s_nop 1
	v_cndmask_b32_e32 v51, v93, v92, vcc
	v_and_b32_e32 v33, 0xffff0000, v33
	v_add_f32_e32 v33, v3, v33
	v_mul_f32_e32 v33, 0xbfb8aa3b, v33
	v_exp_f32_e32 v33, v33
	s_nop 0
	v_add_f32_e32 v33, 1.0, v33
	v_rcp_f32_e32 v33, v33
	s_nop 0
	v_mul_f32_e32 v33, v76, v33
	v_mul_f32_e32 v53, 0x3fb17218, v33
	v_mul_f32_e32 v92, 0x3fb8aa3b, v53
	v_exp_f32_e32 v92, v92
	v_fmamk_f32 v93, v53, 0x3c088889, v202
	v_fmaak_f32 v93, v53, v93, 0x3e2aaaab
	v_fma_f32 v93, v53, v93, 0.5
	v_fma_f32 v93, v53, v93, 1.0
	v_mul_f32_e64 v93, v93, -v53
	v_sub_f32_e32 v92, 1.0, v92
	v_cmp_nlt_f32_e32 vcc, s5, v53
	s_nop 1
	v_cndmask_b32_e32 v52, v93, v92, vcc
	v_lshlrev_b32_e32 v53, 16, v34
	v_add_f32_e32 v53, v8, v53
	v_mul_f32_e32 v53, 0xbfb8aa3b, v53
	v_exp_f32_e32 v53, v53
	s_nop 0
	v_add_f32_e32 v53, 1.0, v53
	v_rcp_f32_e32 v53, v53
	s_nop 0
	v_mul_f32_e32 v53, v75, v53
	v_mul_f32_e32 v55, 0x3fb17218, v53
	v_mul_f32_e32 v92, 0x3fb8aa3b, v55
	v_exp_f32_e32 v92, v92
	v_fmamk_f32 v93, v55, 0x3c088889, v202
	v_fmaak_f32 v93, v55, v93, 0x3e2aaaab
	v_fma_f32 v93, v55, v93, 0.5
	v_fma_f32 v93, v55, v93, 1.0
	v_mul_f32_e64 v93, v93, -v55
	v_sub_f32_e32 v92, 1.0, v92
	v_cmp_nlt_f32_e32 vcc, s5, v55
	s_nop 1
	v_cndmask_b32_e32 v63, v93, v92, vcc
	v_and_b32_e32 v34, 0xffff0000, v34
	v_add_f32_e32 v34, v9, v34
	v_mul_f32_e32 v34, 0xbfb8aa3b, v34
	v_exp_f32_e32 v34, v34
	s_nop 0
	v_add_f32_e32 v34, 1.0, v34
	v_rcp_f32_e32 v34, v34
	s_nop 0
	v_mul_f32_e32 v34, v74, v34
	v_mul_f32_e32 v55, 0x3fb17218, v34
	v_mul_f32_e32 v92, 0x3fb8aa3b, v55
	v_exp_f32_e32 v92, v92
	v_fmamk_f32 v93, v55, 0x3c088889, v202
	v_fmaak_f32 v93, v55, v93, 0x3e2aaaab
	v_fma_f32 v93, v55, v93, 0.5
	v_fma_f32 v93, v55, v93, 1.0
	v_mul_f32_e64 v93, v93, -v55
	v_sub_f32_e32 v92, 1.0, v92
	v_cmp_nlt_f32_e32 vcc, s5, v55
	s_nop 1
	v_cndmask_b32_e32 v64, v93, v92, vcc
	v_lshlrev_b32_e32 v55, 16, v35
	v_add_f32_e32 v55, v10, v55
	v_mul_f32_e32 v55, 0xbfb8aa3b, v55
	v_exp_f32_e32 v55, v55
	s_nop 0
	v_add_f32_e32 v55, 1.0, v55
	v_rcp_f32_e32 v55, v55
	s_nop 0
	v_mul_f32_e32 v66, v73, v55
	v_mul_f32_e32 v55, 0x3fb17218, v66
	v_mul_f32_e32 v92, 0x3fb8aa3b, v55
	v_exp_f32_e32 v92, v92
	v_fmamk_f32 v93, v55, 0x3c088889, v202
	v_fmaak_f32 v93, v55, v93, 0x3e2aaaab
	v_fma_f32 v93, v55, v93, 0.5
	v_fma_f32 v93, v55, v93, 1.0
	v_mul_f32_e64 v93, v93, -v55
	v_sub_f32_e32 v92, 1.0, v92
	v_cmp_nlt_f32_e32 vcc, s5, v55
	s_nop 1
	v_cndmask_b32_e32 v65, v93, v92, vcc
	v_and_b32_e32 v35, 0xffff0000, v35
	v_add_f32_e32 v35, v11, v35
	v_mul_f32_e32 v35, 0xbfb8aa3b, v35
	v_exp_f32_e32 v35, v35
	s_nop 0
	v_add_f32_e32 v35, 1.0, v35
	v_rcp_f32_e32 v35, v35
	s_nop 0
	v_mul_f32_e32 v67, v80, v35
	v_mul_f32_e32 v55, 0x3fb17218, v67
	v_cmp_nlt_f32_e32 vcc, s5, v55
	s_and_saveexec_b64 s[2:3], vcc
	s_xor_b64 s[6:7], exec, s[2:3]
	v_mul_f32_e32 v35, 0x3fb8aa3b, v55
	v_exp_f32_e32 v35, v35
	s_nop 0
	v_sub_f32_e32 v35, 1.0, v35
	s_andn2_saveexec_b64 s[6:7], s[6:7]
	s_cbranch_execz .LBB0_1416
	v_fmamk_f32 v35, v55, 0x3c088889, v202
	v_fmaak_f32 v35, v55, v35, 0x3e2aaaab
	v_fma_f32 v35, v55, v35, 0.5
	v_fma_f32 v35, v55, v35, 1.0
	v_mul_f32_e64 v35, v35, -v55
	s_branch .LBB0_1416

; template <class Epi, class Sched, bool ALIGN_EPI = false, bool SP2 = false>
; __device__ __forceinline__ void gemm_phase(PG8_LAS unsigned char* lds, const Gemm g, const Sched& S, const Epi& E) {
;     ...
; #pragma unroll
;         for (int a = 0; a < 2; ++a)
; #pragma unroll
;             for (int b = 0; b < 2; ++b)
; #pragma unroll
;                 for (int m = 0; m < 4; ++m)
; #pragma unroll
;                     for (int n = 0; n < 2; ++n) acc[a][b][m][n] = (f32x4){0.f, 0.f, 0.f, 0.f};
;         cur = nxt; cA = nA; cB = nB; ++ui;
.LBB0_1641:
	s_add_u32 s26, s26, 0x80
	s_addc_u32 s27, s27, 0
	s_add_u32 s72, s28, 0x100
	v_mov_b32_e32 v0, 0
	s_addc_u32 s73, s29, 0
	s_mov_b32 s28, 0
	v_mov_b32_e32 v1, v0
	v_mov_b64_e32 v[2:3], 0
	v_mov_b64_e32 v[4:5], 0
	v_mov_b64_e32 v[6:7], 0
	v_mov_b64_e32 v[8:9], 0
	v_mov_b64_e32 v[10:11], 0
	v_mov_b64_e32 v[12:13], 0
	v_mov_b64_e32 v[14:15], 0
	v_mov_b64_e32 v[16:17], 0
	v_mov_b64_e32 v[18:19], 0
	v_mov_b64_e32 v[20:21], 0
	v_mov_b64_e32 v[22:23], 0
	v_mov_b64_e32 v[24:25], 0
	v_mov_b64_e32 v[26:27], 0
	v_mov_b64_e32 v[28:29], 0
	v_mov_b64_e32 v[30:31], 0
	v_mov_b64_e32 v[32:33], 0
	v_mov_b64_e32 v[34:35], 0
	v_mov_b64_e32 v[36:37], 0
	v_mov_b64_e32 v[38:39], 0
	v_mov_b64_e32 v[40:41], 0
	v_mov_b64_e32 v[42:43], 0
	v_mov_b64_e32 v[44:45], 0
	v_mov_b64_e32 v[46:47], 0
	v_mov_b64_e32 v[48:49], 0
	v_mov_b64_e32 v[50:51], 0
	v_mov_b64_e32 v[52:53], 0
	v_mov_b64_e32 v[54:55], 0
	v_mov_b64_e32 v[56:57], 0
	v_mov_b64_e32 v[58:59], 0
	v_mov_b64_e32 v[60:61], 0
	v_mov_b64_e32 v[62:63], 0
	v_mov_b64_e32 v[64:65], 0
	v_mov_b64_e32 v[66:67], 0
	v_mov_b64_e32 v[68:69], 0
	v_mov_b64_e32 v[70:71], 0
	v_mov_b64_e32 v[72:73], 0
	v_mov_b64_e32 v[74:75], 0
	v_mov_b64_e32 v[76:77], 0
	v_mov_b64_e32 v[78:79], 0
	v_mov_b64_e32 v[80:81], 0
	v_mov_b64_e32 v[82:83], 0
	v_mov_b64_e32 v[84:85], 0
	v_mov_b64_e32 v[86:87], 0
	v_mov_b64_e32 v[88:89], 0
	v_mov_b64_e32 v[90:91], 0
	v_mov_b64_e32 v[92:93], 0
	v_mov_b64_e32 v[94:95], 0
	v_mov_b64_e32 v[96:97], 0
	v_mov_b64_e32 v[98:99], 0
	v_mov_b64_e32 v[100:101], 0
	v_mov_b64_e32 v[102:103], 0
	v_mov_b64_e32 v[104:105], 0
	v_mov_b64_e32 v[106:107], 0
	v_mov_b64_e32 v[108:109], 0
	v_mov_b64_e32 v[110:111], 0
	v_mov_b64_e32 v[112:113], 0
	v_mov_b64_e32 v[114:115], 0
	v_mov_b64_e32 v[116:117], 0
	v_mov_b64_e32 v[118:119], 0
	v_mov_b64_e32 v[120:121], 0
	v_mov_b64_e32 v[122:123], 0
	v_mov_b64_e32 v[124:125], 0
	v_mov_b64_e32 v[126:127], 0
	v_readfirstlane_b32 s100, v198
	s_nop 3
	s_bitcmp1_b32 s100, 8
	s_cbranch_scc0 .Lgprio_3_skip
	s_setprio 1

; template <class Epi, class Sched, bool ALIGN_EPI = false, bool SP2 = false>
; __device__ __forceinline__ void gemm_phase(PG8_LAS unsigned char* lds, const Gemm g, const Sched& S, const Epi& E) {
;     ...
;         const bool has_next = S.next(ui + 1, nxt);
;         const char* nA = has_next ? (const char*)g.A + (size_t)nxt.pm * tstepA + (size_t)((nxt.pn / g.kdiv) * g.kmul) * 2 : cA; const char* nB = has_next ? (const char*)g.Bt + (size_t)nxt.pn * tstepB : cB;
;     ...
; #pragma unroll
;         for (int a = 0; a < 2; ++a)
; #pragma unroll
;             for (int b = 0; b < 2; ++b)
; #pragma unroll
;                 for (int m = 0; m < 4; ++m)
; #pragma unroll
;                     for (int n = 0; n < 2; ++n) acc[a][b][m][n] = (f32x4){0.f, 0.f, 0.f, 0.f};
;         cur = nxt; cA = nA; cB = nB; ++ui;
.LBB0_1799:
	s_ashr_i32 s37, s36, 31
	s_lshl_b64 s[8:9], s[36:37], 19
	s_add_u32 s40, s33, s8
	s_addc_u32 s41, s50, s9
	s_and_b64 s[8:9], s[6:7], exec
	s_cselect_b32 s13, s41, s47
	s_cselect_b32 s15, s40, s46
	s_ashr_i32 s35, s34, 31
	s_lshl_b64 s[8:9], s[34:35], 19
	s_add_u32 s42, s51, s8
	s_addc_u32 s43, s52, s9
	s_and_b64 s[8:9], s[6:7], exec
	s_cselect_b32 s35, s43, s45
	s_cselect_b32 s37, s42, s44
	s_add_u32 s8, s46, 0x40080
	s_addc_u32 s9, s47, 0
	s_add_u32 s46, s44, 0x100
	v_mov_b32_e32 v0, 0
	s_addc_u32 s47, s45, 0
	s_mov_b32 s70, -2
	v_mov_b32_e32 v1, v0
	v_mov_b64_e32 v[2:3], 0
	v_mov_b64_e32 v[4:5], 0
	v_mov_b64_e32 v[6:7], 0
	v_mov_b64_e32 v[8:9], 0
	v_mov_b64_e32 v[10:11], 0
	v_mov_b64_e32 v[12:13], 0
	v_mov_b64_e32 v[14:15], 0
	v_mov_b64_e32 v[16:17], 0
	v_mov_b64_e32 v[18:19], 0
	v_mov_b64_e32 v[20:21], 0
	v_mov_b64_e32 v[22:23], 0
	v_mov_b64_e32 v[24:25], 0
	v_mov_b64_e32 v[26:27], 0
	v_mov_b64_e32 v[28:29], 0
	v_mov_b64_e32 v[30:31], 0
	v_mov_b64_e32 v[32:33], 0
	v_mov_b64_e32 v[34:35], 0
	v_mov_b64_e32 v[36:37], 0
	v_mov_b64_e32 v[38:39], 0
	v_mov_b64_e32 v[40:41], 0
	v_mov_b64_e32 v[42:43], 0
	v_mov_b64_e32 v[44:45], 0
	v_mov_b64_e32 v[46:47], 0
	v_mov_b64_e32 v[48:49], 0
	v_mov_b64_e32 v[50:51], 0
	v_mov_b64_e32 v[52:53], 0
	v_mov_b64_e32 v[54:55], 0
	v_mov_b64_e32 v[56:57], 0
	v_mov_b64_e32 v[58:59], 0
	v_mov_b64_e32 v[60:61], 0
	v_mov_b64_e32 v[62:63], 0
	v_mov_b64_e32 v[64:65], 0
	v_mov_b64_e32 v[66:67], 0
	v_mov_b64_e32 v[68:69], 0
	v_mov_b64_e32 v[70:71], 0
	v_mov_b64_e32 v[72:73], 0
	v_mov_b64_e32 v[74:75], 0
	v_mov_b64_e32 v[76:77], 0
	v_mov_b64_e32 v[78:79], 0
	v_mov_b64_e32 v[80:81], 0
	v_mov_b64_e32 v[82:83], 0
	v_mov_b64_e32 v[84:85], 0
	v_mov_b64_e32 v[86:87], 0
	v_mov_b64_e32 v[88:89], 0
	v_mov_b64_e32 v[90:91], 0
	v_mov_b64_e32 v[92:93], 0
	v_mov_b64_e32 v[94:95], 0
	v_mov_b64_e32 v[96:97], 0
	v_mov_b64_e32 v[98:99], 0
	v_mov_b64_e32 v[100:101], 0
	v_mov_b64_e32 v[102:103], 0
	v_mov_b64_e32 v[104:105], 0
	v_mov_b64_e32 v[106:107], 0
	v_mov_b64_e32 v[108:109], 0
	v_mov_b64_e32 v[110:111], 0
	v_mov_b64_e32 v[112:113], 0
	v_mov_b64_e32 v[114:115], 0
	v_mov_b64_e32 v[116:117], 0
	v_mov_b64_e32 v[118:119], 0
	v_mov_b64_e32 v[120:121], 0
	v_mov_b64_e32 v[122:123], 0
	v_mov_b64_e32 v[124:125], 0
	v_mov_b64_e32 v[126:127], 0
	v_readfirstlane_b32 s100, v198
	s_nop 3
	s_bitcmp1_b32 s100, 8
	s_cbranch_scc0 .Lgprio_4_skip
	s_setprio 1

; template <class Epi, class Sched, bool ALIGN_EPI = false, bool SP2 = false>
; __device__ __forceinline__ void gemm_phase(PG8_LAS unsigned char* lds, const Gemm g, const Sched& S, const Epi& E) {
;     ...
; #pragma unroll
;         for (int a = 0; a < 2; ++a)
; #pragma unroll
;             for (int b = 0; b < 2; ++b)
; #pragma unroll
;                 for (int m = 0; m < 4; ++m)
; #pragma unroll
;                     for (int n = 0; n < 2; ++n) acc[a][b][m][n] = (f32x4){0.f, 0.f, 0.f, 0.f};
;         cur = nxt; cA = nA; cB = nB; ++ui;
.LBB0_1992:
	s_add_u32 s65, s24, 0x100
	v_mov_b32_e32 v0, 0
	s_addc_u32 s66, s25, 0
	s_mov_b32 s67, -2
	v_mov_b32_e32 v1, v0
	v_mov_b64_e32 v[2:3], 0
	v_mov_b64_e32 v[4:5], 0
	v_mov_b64_e32 v[6:7], 0
	v_mov_b64_e32 v[8:9], 0
	v_mov_b64_e32 v[10:11], 0
	v_mov_b64_e32 v[12:13], 0
	v_mov_b64_e32 v[14:15], 0
	v_mov_b64_e32 v[16:17], 0
	v_mov_b64_e32 v[18:19], 0
	v_mov_b64_e32 v[20:21], 0
	v_mov_b64_e32 v[22:23], 0
	v_mov_b64_e32 v[24:25], 0
	v_mov_b64_e32 v[26:27], 0
	v_mov_b64_e32 v[28:29], 0
	v_mov_b64_e32 v[30:31], 0
	v_mov_b64_e32 v[32:33], 0
	v_mov_b64_e32 v[34:35], 0
	v_mov_b64_e32 v[36:37], 0
	v_mov_b64_e32 v[38:39], 0
	v_mov_b64_e32 v[40:41], 0
	v_mov_b64_e32 v[42:43], 0
	v_mov_b64_e32 v[44:45], 0
	v_mov_b64_e32 v[46:47], 0
	v_mov_b64_e32 v[48:49], 0
	v_mov_b64_e32 v[50:51], 0
	v_mov_b64_e32 v[52:53], 0
	v_mov_b64_e32 v[54:55], 0
	v_mov_b64_e32 v[56:57], 0
	v_mov_b64_e32 v[58:59], 0
	v_mov_b64_e32 v[60:61], 0
	v_mov_b64_e32 v[62:63], 0
	v_mov_b64_e32 v[64:65], 0
	v_mov_b64_e32 v[66:67], 0
	v_mov_b64_e32 v[68:69], 0
	v_mov_b64_e32 v[70:71], 0
	v_mov_b64_e32 v[72:73], 0
	v_mov_b64_e32 v[74:75], 0
	v_mov_b64_e32 v[76:77], 0
	v_mov_b64_e32 v[78:79], 0
	v_mov_b64_e32 v[80:81], 0
	v_mov_b64_e32 v[82:83], 0
	v_mov_b64_e32 v[84:85], 0
	v_mov_b64_e32 v[86:87], 0
	v_mov_b64_e32 v[88:89], 0
	v_mov_b64_e32 v[90:91], 0
	v_mov_b64_e32 v[92:93], 0
	v_mov_b64_e32 v[94:95], 0
	v_mov_b64_e32 v[96:97], 0
	v_mov_b64_e32 v[98:99], 0
	v_mov_b64_e32 v[100:101], 0
	v_mov_b64_e32 v[102:103], 0
	v_mov_b64_e32 v[104:105], 0
	v_mov_b64_e32 v[106:107], 0
	v_mov_b64_e32 v[108:109], 0
	v_mov_b64_e32 v[110:111], 0
	v_mov_b64_e32 v[112:113], 0
	v_mov_b64_e32 v[114:115], 0
	v_mov_b64_e32 v[116:117], 0
	v_mov_b64_e32 v[118:119], 0
	v_mov_b64_e32 v[120:121], 0
	v_mov_b64_e32 v[122:123], 0
	v_mov_b64_e32 v[124:125], 0
	v_mov_b64_e32 v[126:127], 0
	v_readfirstlane_b32 s100, v198
	s_nop 3
	s_bitcmp1_b32 s100, 8
	s_cbranch_scc0 .Lgprio_5_skip
	s_setprio 1
